# GEMM K-loops: two A-tile LDS-DMAs moved from part 2 to part 3 (6/2 -> 4/4 per part), part-2 wait vmcnt(8)->vmcnt(6); issue order unchanged
# speedup vs baseline: 1.0089x; 1.0089x over previous
; #define PG8_STAGE(bufoff, gbase, voff) do { _Pragma("unroll") for (int _i = 0; _i < 2; ++_i) \
;         __builtin_amdgcn_global_load_lds((const unsigned*)((const char*)(gbase) + (voff)[_i]), (LAS unsigned*)(lds + (bufoff) + ldsw + _i * 8192), 16, 0, 0); } while (0)
; #define PG8_LDA(dst, b, h) do { _Pragma("unroll") for (int m = 0; m < 4; ++m) _Pragma("unroll") for (int k = 0; k < 2; ++k) dst[m][k] = *(const LAS bf16x8*)(lds + PG8_SA(b, h) + aoff + m * 2048 + k * 1024); } while (0)
; #define PG8_LDB(dst, b, h) do { _Pragma("unroll") for (int n = 0; n < 2; ++n) _Pragma("unroll") for (int k = 0; k < 2; ++k) dst[n][k] = *(const LAS bf16x8*)(lds + PG8_SB(b, h) + boff + n * 2048 + k * 1024); } while (0)
; #define PG8_MMA(ai, bj, At, Bt) do { __builtin_amdgcn_s_setprio(1); _Pragma("unroll") for (int m = 0; m < 4; ++m) _Pragma("unroll") for (int n = 0; n < 2; ++n) _Pragma("unroll") for (int k = 0; k < 2; ++k) \
;         acc[ai][bj][m][n] = __builtin_amdgcn_mfma_f32_16x16x32_bf16(Bt[n][k], At[m][k], acc[ai][bj][m][n], 0, 0, 0); __builtin_amdgcn_s_setprio(0); } while (0)
; #define PG8_WAIT_V(n) asm volatile("s_waitcnt vmcnt(" #n ")" ::: "memory")
; #define PG8_WAIT_L(n) asm volatile("s_waitcnt lgkmcnt(" #n ")" ::: "memory")
; #define PG8_BAR __builtin_amdgcn_s_barrier()
; #define PG8_SCHED __builtin_amdgcn_sched_barrier(0)
; template <class Epi, class Sched>
; DI void gemm_phase(LAS unsigned char* lds, const int K, const Sched& S, const Epi& E) {
;     ...
;             const bool last = (t == nt - 2);
;             const char* a1 = cA + (size_t)(t + 1) * kstep;
;             const char* a2 = last ? nA : cA + (size_t)(t + 2) * kstep; const char* b2 = last ? nB : cB + (size_t)(t + 2) * kstep;
;             const char* a3 = a2 + kstep; const char* b3 = b2 + kstep;
;             PG8_LDB(B0, 0, 0); PG8_LDB(B1, 0, 1); PG8_SCHED; PG8_LDA(At, 0, 0); PG8_STAGE(PG8_SA(1, 1), a1 + hstep, voffA);
;             PG8_WAIT_V(8); PG8_WAIT_L(0); PG8_BAR; PG8_MMA(0, 0, At, B0); PG8_MMA(0, 1, At, B1); PG8_BAR; PG8_SCHED;
;             PG8_LDA(At, 0, 1); PG8_STAGE(PG8_SB(0, 0), b2, voffB); PG8_STAGE(PG8_SB(0, 1), b2 + hstep, voffB); PG8_STAGE(PG8_SA(0, 0), a2, voffA);
;             PG8_WAIT_V(8); PG8_WAIT_L(0); PG8_BAR; PG8_MMA(1, 0, At, B0); PG8_MMA(1, 1, At, B1); PG8_BAR; PG8_SCHED;
.LBB0_218:
	s_add_u32 s80, s78, 0xfffc0080
	s_addc_u32 s81, s79, -1
	s_add_i32 vcc_lo, 0, 0x10000
	s_cmp_eq_u32 s87, 12
	s_cselect_b32 s83, s45, s81
	s_cselect_b32 s82, s73, s80
	s_cselect_b32 s81, s77, s86
	s_cselect_b32 s80, s84, s85
	s_add_i32 s63, 0, 0x14000
	v_add_u32_e32 v142, vcc_lo, v201
	v_add_u32_e32 v158, s63, v201
	ds_read_b128 v[130:133], v142
	ds_read_b128 v[134:137], v142 offset:1024
	ds_read_b128 v[138:141], v142 offset:2048
	ds_read_b128 v[142:145], v142 offset:3072
	ds_read_b128 v[146:149], v158
	ds_read_b128 v[150:153], v158 offset:1024
	ds_read_b128 v[154:157], v158 offset:2048
	ds_read_b128 v[158:161], v158 offset:3072
	s_nop 0
	s_add_i32 m0, s56, 0xc000
	ds_read_b128 v[174:177], v202
	ds_read_b128 v[182:185], v202 offset:1024
	ds_read_b128 v[190:193], v202 offset:2048
	ds_read_b128 v[194:197], v202 offset:3072
	ds_read_b128 v[212:215], v202 offset:4096
	ds_read_b128 v[216:219], v202 offset:5120
	ds_read_b128 v[220:223], v202 offset:6144
	ds_read_b128 v[224:227], v202 offset:7168
	global_load_lds_dwordx4 v172, s[78:79]
	s_nop 0
	s_add_i32 m0, s56, 0xe000
	s_nop 0
	global_load_lds_dwordx4 v170, s[78:79]
	s_waitcnt vmcnt(8)
	s_waitcnt lgkmcnt(0)
	s_barrier
	s_nop 0
	s_waitcnt lgkmcnt(0)
	v_mfma_f32_16x16x32_bf16 v[126:129], v[130:133], v[174:177], v[126:129]
	v_mfma_f32_16x16x32_bf16 v[122:125], v[138:141], v[174:177], v[122:125]
	v_mfma_f32_16x16x32_bf16 v[110:113], v[130:133], v[190:193], v[110:113]
	v_mfma_f32_16x16x32_bf16 v[106:109], v[138:141], v[190:193], v[106:109]
	v_mfma_f32_16x16x32_bf16 v[94:97], v[130:133], v[212:215], v[94:97]
	v_mfma_f32_16x16x32_bf16 v[90:93], v[138:141], v[212:215], v[90:93]
	v_mfma_f32_16x16x32_bf16 v[78:81], v[130:133], v[220:223], v[78:81]
	v_mfma_f32_16x16x32_bf16 v[74:77], v[138:141], v[220:223], v[74:77]
	v_mfma_f32_16x16x32_bf16 v[126:129], v[134:137], v[182:185], v[126:129]
	v_mfma_f32_16x16x32_bf16 v[122:125], v[142:145], v[182:185], v[122:125]
	v_mfma_f32_16x16x32_bf16 v[110:113], v[134:137], v[194:197], v[110:113]
	v_mfma_f32_16x16x32_bf16 v[106:109], v[142:145], v[194:197], v[106:109]
	v_mfma_f32_16x16x32_bf16 v[94:97], v[134:137], v[216:219], v[94:97]
	v_mfma_f32_16x16x32_bf16 v[90:93], v[142:145], v[216:219], v[90:93]
	v_mfma_f32_16x16x32_bf16 v[78:81], v[134:137], v[224:227], v[78:81]
	v_mfma_f32_16x16x32_bf16 v[74:77], v[142:145], v[224:227], v[74:77]
	s_nop 0
	s_nop 0
	v_mfma_f32_16x16x32_bf16 v[118:121], v[146:149], v[174:177], v[118:121]
	v_mfma_f32_16x16x32_bf16 v[114:117], v[154:157], v[174:177], v[114:117]
	v_mfma_f32_16x16x32_bf16 v[102:105], v[146:149], v[190:193], v[102:105]
	v_mfma_f32_16x16x32_bf16 v[98:101], v[154:157], v[190:193], v[98:101]
	v_mfma_f32_16x16x32_bf16 v[86:89], v[146:149], v[212:215], v[86:89]
	v_mfma_f32_16x16x32_bf16 v[82:85], v[154:157], v[212:215], v[82:85]
	v_mfma_f32_16x16x32_bf16 v[70:73], v[146:149], v[220:223], v[70:73]
	v_mfma_f32_16x16x32_bf16 v[66:69], v[154:157], v[220:223], v[66:69]
	v_mfma_f32_16x16x32_bf16 v[118:121], v[150:153], v[182:185], v[118:121]
	v_mfma_f32_16x16x32_bf16 v[114:117], v[158:161], v[182:185], v[114:117]
	v_mfma_f32_16x16x32_bf16 v[102:105], v[150:153], v[194:197], v[102:105]
	v_mfma_f32_16x16x32_bf16 v[98:101], v[158:161], v[194:197], v[98:101]
	v_mfma_f32_16x16x32_bf16 v[86:89], v[150:153], v[216:219], v[86:89]
	v_mfma_f32_16x16x32_bf16 v[82:85], v[158:161], v[216:219], v[82:85]
	v_mfma_f32_16x16x32_bf16 v[70:73], v[150:153], v[224:227], v[70:73]
	v_mfma_f32_16x16x32_bf16 v[66:69], v[158:161], v[224:227], v[66:69]
	s_nop 0
	s_barrier
	s_add_i32 vcc_lo, vcc_lo, s55
	s_nop 0
	s_mov_b32 m0, vcc_lo
	ds_read_b128 v[174:177], v202 offset:16384
	ds_read_b128 v[182:185], v202 offset:17408
	ds_read_b128 v[190:193], v202 offset:18432
	ds_read_b128 v[194:197], v202 offset:19456
	ds_read_b128 v[212:215], v202 offset:20480
	ds_read_b128 v[216:219], v202 offset:21504
	ds_read_b128 v[220:223], v202 offset:22528
	ds_read_b128 v[224:227], v202 offset:23552
	global_load_lds_dwordx4 v164, s[80:81]
	s_add_i32 m0, vcc_lo, 0x2000
	s_add_u32 vcc_lo, s80, 0x40000
	s_nop 0
	s_addc_u32 vcc_hi, s81, 0
	s_add_i32 s63, s63, s55
	global_load_lds_dwordx4 v168, s[80:81]
	s_nop 0
	s_mov_b32 m0, s63
	s_nop 0
	global_load_lds_dwordx4 v164, vcc
	s_nop 0
	s_add_i32 m0, s63, 0x2000
	s_nop 0
	global_load_lds_dwordx4 v168, vcc
	s_nop 0
	s_add_u32 s98, s82, s90
	s_addc_u32 s99, s83, s91
	s_waitcnt vmcnt(6)
	s_waitcnt lgkmcnt(0)
	s_barrier
	s_nop 0
	s_waitcnt lgkmcnt(0)
	v_mfma_f32_16x16x32_bf16 v[62:65], v[130:133], v[174:177], v[62:65]
	v_mfma_f32_16x16x32_bf16 v[58:61], v[138:141], v[174:177], v[58:61]
	v_mfma_f32_16x16x32_bf16 v[46:49], v[130:133], v[190:193], v[46:49]
	v_mfma_f32_16x16x32_bf16 v[42:45], v[138:141], v[190:193], v[42:45]
	v_mfma_f32_16x16x32_bf16 v[30:33], v[130:133], v[212:215], v[30:33]
	v_mfma_f32_16x16x32_bf16 v[26:29], v[138:141], v[212:215], v[26:29]
	v_mfma_f32_16x16x32_bf16 v[14:17], v[130:133], v[220:223], v[14:17]
	v_mfma_f32_16x16x32_bf16 v[10:13], v[138:141], v[220:223], v[10:13]
	v_mfma_f32_16x16x32_bf16 v[62:65], v[134:137], v[182:185], v[62:65]
	v_mfma_f32_16x16x32_bf16 v[58:61], v[142:145], v[182:185], v[58:61]
	v_mfma_f32_16x16x32_bf16 v[46:49], v[134:137], v[194:197], v[46:49]
	v_mfma_f32_16x16x32_bf16 v[42:45], v[142:145], v[194:197], v[42:45]
	v_mfma_f32_16x16x32_bf16 v[30:33], v[134:137], v[216:219], v[30:33]
	v_mfma_f32_16x16x32_bf16 v[26:29], v[142:145], v[216:219], v[26:29]
	v_mfma_f32_16x16x32_bf16 v[14:17], v[134:137], v[224:227], v[14:17]
	v_mfma_f32_16x16x32_bf16 v[10:13], v[142:145], v[224:227], v[10:13]
	s_nop 0
	s_nop 0
	v_mfma_f32_16x16x32_bf16 v[54:57], v[146:149], v[174:177], v[54:57]
	v_mfma_f32_16x16x32_bf16 v[50:53], v[154:157], v[174:177], v[50:53]
	v_mfma_f32_16x16x32_bf16 v[38:41], v[146:149], v[190:193], v[38:41]
	v_mfma_f32_16x16x32_bf16 v[34:37], v[154:157], v[190:193], v[34:37]
	v_mfma_f32_16x16x32_bf16 v[22:25], v[146:149], v[212:215], v[22:25]
	v_mfma_f32_16x16x32_bf16 v[18:21], v[154:157], v[212:215], v[18:21]
	v_mfma_f32_16x16x32_bf16 v[6:9], v[146:149], v[220:223], v[6:9]
	v_mfma_f32_16x16x32_bf16 v[2:5], v[154:157], v[220:223], v[2:5]
	v_mfma_f32_16x16x32_bf16 v[54:57], v[150:153], v[182:185], v[54:57]
	v_mfma_f32_16x16x32_bf16 v[50:53], v[158:161], v[182:185], v[50:53]
	v_mfma_f32_16x16x32_bf16 v[38:41], v[150:153], v[194:197], v[38:41]
	v_mfma_f32_16x16x32_bf16 v[34:37], v[158:161], v[194:197], v[34:37]
	v_mfma_f32_16x16x32_bf16 v[22:25], v[150:153], v[216:219], v[22:25]
	v_mfma_f32_16x16x32_bf16 v[18:21], v[158:161], v[216:219], v[18:21]
	v_mfma_f32_16x16x32_bf16 v[6:9], v[150:153], v[224:227], v[6:9]
	v_mfma_f32_16x16x32_bf16 v[2:5], v[158:161], v[224:227], v[2:5]
	s_nop 0
	s_barrier
; #define PG8_STAGE(bufoff, gbase, voff) do { _Pragma("unroll") for (int _i = 0; _i < 2; ++_i) \
;         __builtin_amdgcn_global_load_lds((const unsigned*)((const char*)(gbase) + (voff)[_i]), (LAS unsigned*)(lds + (bufoff) + ldsw + _i * 8192), 16, 0, 0); } while (0)
; #define PG8_LDA(dst, b, h) do { _Pragma("unroll") for (int m = 0; m < 4; ++m) _Pragma("unroll") for (int k = 0; k < 2; ++k) dst[m][k] = *(const LAS bf16x8*)(lds + PG8_SA(b, h) + aoff + m * 2048 + k * 1024); } while (0)
; #define PG8_LDB(dst, b, h) do { _Pragma("unroll") for (int n = 0; n < 2; ++n) _Pragma("unroll") for (int k = 0; k < 2; ++k) dst[n][k] = *(const LAS bf16x8*)(lds + PG8_SB(b, h) + boff + n * 2048 + k * 1024); } while (0)
; #define PG8_MMA(ai, bj, At, Bt) do { __builtin_amdgcn_s_setprio(1); _Pragma("unroll") for (int m = 0; m < 4; ++m) _Pragma("unroll") for (int n = 0; n < 2; ++n) _Pragma("unroll") for (int k = 0; k < 2; ++k) \
;         acc[ai][bj][m][n] = __builtin_amdgcn_mfma_f32_16x16x32_bf16(Bt[n][k], At[m][k], acc[ai][bj][m][n], 0, 0, 0); __builtin_amdgcn_s_setprio(0); } while (0)
; #define PG8_WAIT_V(n) asm volatile("s_waitcnt vmcnt(" #n ")" ::: "memory")
; #define PG8_WAIT_L(n) asm volatile("s_waitcnt lgkmcnt(" #n ")" ::: "memory")
; #define PG8_BAR __builtin_amdgcn_s_barrier()
; #define PG8_SCHED __builtin_amdgcn_sched_barrier(0)
; template <class Epi, class Sched>
; DI void gemm_phase(LAS unsigned char* lds, const int K, const Sched& S, const Epi& E) {
;     ...
;             PG8_LDB(B0, 1, 0); PG8_LDB(B1, 1, 1); PG8_SCHED; PG8_LDA(At, 1, 0); PG8_STAGE(PG8_SA(0, 1), a2 + hstep, voffA);
;             PG8_WAIT_V(8); PG8_WAIT_L(0); PG8_BAR; PG8_MMA(0, 0, At, B0); PG8_MMA(0, 1, At, B1); PG8_BAR; PG8_SCHED;
;             PG8_LDA(At, 1, 1); PG8_STAGE(PG8_SB(1, 0), b3, voffB); PG8_STAGE(PG8_SB(1, 1), b3 + hstep, voffB); PG8_STAGE(PG8_SA(1, 0), a3, voffA);
;             PG8_WAIT_V(8); PG8_WAIT_L(0); PG8_BAR; PG8_MMA(1, 0, At, B0); PG8_MMA(1, 1, At, B1); PG8_BAR; PG8_SCHED;
;         }
;         if (wr == 0) PG8_BAR;
	s_add_i32 s63, 0, 0x18000
	s_add_i32 vcc_lo, 0, 0x1c000
	v_add_u32_e32 v142, s63, v201
	v_add_u32_e32 v158, vcc_lo, v201
	ds_read_b128 v[130:133], v142
	ds_read_b128 v[134:137], v142 offset:1024
	ds_read_b128 v[138:141], v142 offset:2048
	ds_read_b128 v[142:145], v142 offset:3072
	ds_read_b128 v[146:149], v158
	ds_read_b128 v[150:153], v158 offset:1024
	ds_read_b128 v[154:157], v158 offset:2048
	ds_read_b128 v[158:161], v158 offset:3072
	s_mov_b32 m0, s56
	s_nop 0
	ds_read_b128 v[174:177], v202 offset:32768
	ds_read_b128 v[182:185], v202 offset:33792
	ds_read_b128 v[190:193], v202 offset:34816
	ds_read_b128 v[194:197], v202 offset:35840
	ds_read_b128 v[212:215], v202 offset:36864
	ds_read_b128 v[216:219], v202 offset:37888
	ds_read_b128 v[220:223], v202 offset:38912
	ds_read_b128 v[224:227], v202 offset:39936
	global_load_lds_dwordx4 v162, s[82:83]
	s_mov_b32 m0, s57
	s_nop 0
	global_load_lds_dwordx4 v166, s[82:83]
	s_add_u32 s82, s82, 0x40000
	s_addc_u32 s83, s83, 0
	s_mov_b32 m0, s58
	s_nop 0
	global_load_lds_dwordx4 v162, s[82:83]
	s_nop 0
	s_mov_b32 m0, s59
	s_nop 0
	global_load_lds_dwordx4 v166, s[82:83]
	s_waitcnt vmcnt(8)
	s_waitcnt lgkmcnt(0)
	s_barrier
	s_nop 0
	s_waitcnt lgkmcnt(0)
	v_mfma_f32_16x16x32_bf16 v[126:129], v[130:133], v[174:177], v[126:129]
	v_mfma_f32_16x16x32_bf16 v[122:125], v[138:141], v[174:177], v[122:125]
	v_mfma_f32_16x16x32_bf16 v[110:113], v[130:133], v[190:193], v[110:113]
	v_mfma_f32_16x16x32_bf16 v[106:109], v[138:141], v[190:193], v[106:109]
	v_mfma_f32_16x16x32_bf16 v[94:97], v[130:133], v[212:215], v[94:97]
	v_mfma_f32_16x16x32_bf16 v[90:93], v[138:141], v[212:215], v[90:93]
	v_mfma_f32_16x16x32_bf16 v[78:81], v[130:133], v[220:223], v[78:81]
	v_mfma_f32_16x16x32_bf16 v[74:77], v[138:141], v[220:223], v[74:77]
	v_mfma_f32_16x16x32_bf16 v[126:129], v[134:137], v[182:185], v[126:129]
	v_mfma_f32_16x16x32_bf16 v[122:125], v[142:145], v[182:185], v[122:125]
	v_mfma_f32_16x16x32_bf16 v[110:113], v[134:137], v[194:197], v[110:113]
	v_mfma_f32_16x16x32_bf16 v[106:109], v[142:145], v[194:197], v[106:109]
	v_mfma_f32_16x16x32_bf16 v[94:97], v[134:137], v[216:219], v[94:97]
	v_mfma_f32_16x16x32_bf16 v[90:93], v[142:145], v[216:219], v[90:93]
	v_mfma_f32_16x16x32_bf16 v[78:81], v[134:137], v[224:227], v[78:81]
	v_mfma_f32_16x16x32_bf16 v[74:77], v[142:145], v[224:227], v[74:77]
	s_nop 0
	s_nop 0
	v_mfma_f32_16x16x32_bf16 v[118:121], v[146:149], v[174:177], v[118:121]
	v_mfma_f32_16x16x32_bf16 v[114:117], v[154:157], v[174:177], v[114:117]
	v_mfma_f32_16x16x32_bf16 v[102:105], v[146:149], v[190:193], v[102:105]
	v_mfma_f32_16x16x32_bf16 v[98:101], v[154:157], v[190:193], v[98:101]
	v_mfma_f32_16x16x32_bf16 v[86:89], v[146:149], v[212:215], v[86:89]
	v_mfma_f32_16x16x32_bf16 v[82:85], v[154:157], v[212:215], v[82:85]
	v_mfma_f32_16x16x32_bf16 v[70:73], v[146:149], v[220:223], v[70:73]
	v_mfma_f32_16x16x32_bf16 v[66:69], v[154:157], v[220:223], v[66:69]
	v_mfma_f32_16x16x32_bf16 v[118:121], v[150:153], v[182:185], v[118:121]
	v_mfma_f32_16x16x32_bf16 v[114:117], v[158:161], v[182:185], v[114:117]
	v_mfma_f32_16x16x32_bf16 v[102:105], v[150:153], v[194:197], v[102:105]
	v_mfma_f32_16x16x32_bf16 v[98:101], v[158:161], v[194:197], v[98:101]
	v_mfma_f32_16x16x32_bf16 v[86:89], v[150:153], v[216:219], v[86:89]
	v_mfma_f32_16x16x32_bf16 v[82:85], v[158:161], v[216:219], v[82:85]
	v_mfma_f32_16x16x32_bf16 v[70:73], v[150:153], v[224:227], v[70:73]
	v_mfma_f32_16x16x32_bf16 v[66:69], v[158:161], v[224:227], v[66:69]
	s_nop 0
	s_barrier
	s_add_i32 s63, s63, s55
	s_add_u32 s80, s80, 0x80
	s_addc_u32 s81, s81, 0
	s_mov_b32 m0, s63
	ds_read_b128 v[174:177], v202 offset:49152
	ds_read_b128 v[182:185], v202 offset:50176
	ds_read_b128 v[190:193], v202 offset:51200
	ds_read_b128 v[194:197], v202 offset:52224
	ds_read_b128 v[212:215], v202 offset:53248
	ds_read_b128 v[216:219], v202 offset:54272
	ds_read_b128 v[220:223], v202 offset:55296
	ds_read_b128 v[224:227], v202 offset:56320
	global_load_lds_dwordx4 v164, s[80:81]
	s_add_i32 m0, s63, 0x2000
	s_nop 0
	s_nop 0
	s_nop 0
	s_add_i32 s63, vcc_lo, s55
	global_load_lds_dwordx4 v168, s[80:81]
	s_add_u32 s80, s80, 0x40000
	s_addc_u32 s81, s81, 0
	s_nop 0
	s_mov_b32 m0, s63
	s_nop 0
	global_load_lds_dwordx4 v164, s[80:81]
	s_nop 0
	s_add_i32 m0, s63, 0x2000
	s_nop 0
	global_load_lds_dwordx4 v168, s[80:81]
	s_nop 0
	s_mov_b32 m0, s47
	s_nop 0
	global_load_lds_dwordx4 v162, s[98:99]
	s_nop 0
	s_mov_b32 m0, s62
	s_nop 0
	global_load_lds_dwordx4 v166, s[98:99]
	s_waitcnt vmcnt(8)
	s_waitcnt lgkmcnt(0)
	s_barrier
	s_nop 0
	s_waitcnt lgkmcnt(0)
	v_mfma_f32_16x16x32_bf16 v[62:65], v[130:133], v[174:177], v[62:65]
	v_mfma_f32_16x16x32_bf16 v[58:61], v[138:141], v[174:177], v[58:61]
	v_mfma_f32_16x16x32_bf16 v[46:49], v[130:133], v[190:193], v[46:49]
	v_mfma_f32_16x16x32_bf16 v[42:45], v[138:141], v[190:193], v[42:45]
	v_mfma_f32_16x16x32_bf16 v[30:33], v[130:133], v[212:215], v[30:33]
	v_mfma_f32_16x16x32_bf16 v[26:29], v[138:141], v[212:215], v[26:29]
	v_mfma_f32_16x16x32_bf16 v[14:17], v[130:133], v[220:223], v[14:17]
	v_mfma_f32_16x16x32_bf16 v[10:13], v[138:141], v[220:223], v[10:13]
	v_mfma_f32_16x16x32_bf16 v[62:65], v[134:137], v[182:185], v[62:65]
	v_mfma_f32_16x16x32_bf16 v[58:61], v[142:145], v[182:185], v[58:61]
	v_mfma_f32_16x16x32_bf16 v[46:49], v[134:137], v[194:197], v[46:49]
	v_mfma_f32_16x16x32_bf16 v[42:45], v[142:145], v[194:197], v[42:45]
	v_mfma_f32_16x16x32_bf16 v[30:33], v[134:137], v[216:219], v[30:33]
	v_mfma_f32_16x16x32_bf16 v[26:29], v[142:145], v[216:219], v[26:29]
	v_mfma_f32_16x16x32_bf16 v[14:17], v[134:137], v[224:227], v[14:17]
	v_mfma_f32_16x16x32_bf16 v[10:13], v[142:145], v[224:227], v[10:13]
	s_nop 0
	s_nop 0
	v_mfma_f32_16x16x32_bf16 v[54:57], v[146:149], v[174:177], v[54:57]
	v_mfma_f32_16x16x32_bf16 v[50:53], v[154:157], v[174:177], v[50:53]
	v_mfma_f32_16x16x32_bf16 v[38:41], v[146:149], v[190:193], v[38:41]
	v_mfma_f32_16x16x32_bf16 v[34:37], v[154:157], v[190:193], v[34:37]
	v_mfma_f32_16x16x32_bf16 v[22:25], v[146:149], v[212:215], v[22:25]
	v_mfma_f32_16x16x32_bf16 v[18:21], v[154:157], v[212:215], v[18:21]
	v_mfma_f32_16x16x32_bf16 v[6:9], v[146:149], v[220:223], v[6:9]
	v_mfma_f32_16x16x32_bf16 v[2:5], v[154:157], v[220:223], v[2:5]
	v_mfma_f32_16x16x32_bf16 v[54:57], v[150:153], v[182:185], v[54:57]
	v_mfma_f32_16x16x32_bf16 v[50:53], v[158:161], v[182:185], v[50:53]
	v_mfma_f32_16x16x32_bf16 v[38:41], v[150:153], v[194:197], v[38:41]
	v_mfma_f32_16x16x32_bf16 v[34:37], v[158:161], v[194:197], v[34:37]
	v_mfma_f32_16x16x32_bf16 v[22:25], v[150:153], v[216:219], v[22:25]
	v_mfma_f32_16x16x32_bf16 v[18:21], v[158:161], v[216:219], v[18:21]
	v_mfma_f32_16x16x32_bf16 v[6:9], v[150:153], v[224:227], v[6:9]
	v_mfma_f32_16x16x32_bf16 v[2:5], v[158:161], v[224:227], v[2:5]
	s_nop 0
	s_barrier
	s_add_i32 s87, s87, 2
	s_add_u32 s85, s85, 0x100
	s_addc_u32 s86, s86, 0
	s_add_u32 s78, s78, 0x100
	s_addc_u32 s79, s79, 0
	s_cmp_gt_u32 s87, 13
	s_cbranch_scc0 .LBB0_218
	s_and_b64 vcc, exec, s[50:51]
	s_cbranch_vccz .LBB0_221
	s_barrier

; #define PG8_STAGE(bufoff, gbase, voff) do { _Pragma("unroll") for (int _i = 0; _i < 2; ++_i) \
;         __builtin_amdgcn_global_load_lds((const unsigned*)((const char*)(gbase) + (voff)[_i]), (LAS unsigned*)(lds + (bufoff) + ldsw + _i * 8192), 16, 0, 0); } while (0)
; #define PG8_LDA(dst, b, h) do { _Pragma("unroll") for (int m = 0; m < 4; ++m) _Pragma("unroll") for (int k = 0; k < 2; ++k) dst[m][k] = *(const LAS bf16x8*)(lds + PG8_SA(b, h) + aoff + m * 2048 + k * 1024); } while (0)
; #define PG8_LDB(dst, b, h) do { _Pragma("unroll") for (int n = 0; n < 2; ++n) _Pragma("unroll") for (int k = 0; k < 2; ++k) dst[n][k] = *(const LAS bf16x8*)(lds + PG8_SB(b, h) + boff + n * 2048 + k * 1024); } while (0)
; #define PG8_MMA(ai, bj, At, Bt) do { __builtin_amdgcn_s_setprio(1); _Pragma("unroll") for (int m = 0; m < 4; ++m) _Pragma("unroll") for (int n = 0; n < 2; ++n) _Pragma("unroll") for (int k = 0; k < 2; ++k) \
;         acc[ai][bj][m][n] = __builtin_amdgcn_mfma_f32_16x16x32_bf16(Bt[n][k], At[m][k], acc[ai][bj][m][n], 0, 0, 0); __builtin_amdgcn_s_setprio(0); } while (0)
; #define PG8_WAIT_V(n) asm volatile("s_waitcnt vmcnt(" #n ")" ::: "memory")
; #define PG8_WAIT_L(n) asm volatile("s_waitcnt lgkmcnt(" #n ")" ::: "memory")
; #define PG8_BAR __builtin_amdgcn_s_barrier()
; #define PG8_SCHED __builtin_amdgcn_sched_barrier(0)
; template <class Epi, class Sched>
; DI void gemm_phase(LAS unsigned char* lds, const int K, const Sched& S, const Epi& E) {
;     ...
;             const bool last = (t == nt - 2);
;             const char* a1 = cA + (size_t)(t + 1) * kstep;
;             const char* a2 = last ? nA : cA + (size_t)(t + 2) * kstep; const char* b2 = last ? nB : cB + (size_t)(t + 2) * kstep;
;             const char* a3 = a2 + kstep; const char* b3 = b2 + kstep;
;             PG8_LDB(B0, 0, 0); PG8_LDB(B1, 0, 1); PG8_SCHED; PG8_LDA(At, 0, 0); PG8_STAGE(PG8_SA(1, 1), a1 + hstep, voffA);
;             PG8_WAIT_V(8); PG8_WAIT_L(0); PG8_BAR; PG8_MMA(0, 0, At, B0); PG8_MMA(0, 1, At, B1); PG8_BAR; PG8_SCHED;
;             PG8_LDA(At, 0, 1); PG8_STAGE(PG8_SB(0, 0), b2, voffB); PG8_STAGE(PG8_SB(0, 1), b2 + hstep, voffB); PG8_STAGE(PG8_SA(0, 0), a2, voffA);
;             PG8_WAIT_V(8); PG8_WAIT_L(0); PG8_BAR; PG8_MMA(1, 0, At, B0); PG8_MMA(1, 1, At, B1); PG8_BAR; PG8_SCHED;
.LBB0_338:
	s_add_u32 s58, s56, 0xfffc0080
	s_addc_u32 s59, s57, -1
	s_add_i32 s79, 0, 0x10000
	s_cmp_eq_u32 s78, 12
	s_cselect_b32 s61, s53, s59
	s_cselect_b32 s60, s52, s58
	v_add_u32_e32 v142, s79, v145
	s_cselect_b32 s59, s55, s51
	s_cselect_b32 s58, s54, s49
	s_add_i32 s82, 0, 0x14000
	ds_read_b128 v[148:151], v142
	ds_read_b128 v[152:155], v142 offset:1024
	ds_read_b128 v[156:159], v142 offset:2048
	ds_read_b128 v[160:163], v142 offset:3072
	v_add_u32_e32 v142, s82, v145
	ds_read_b128 v[164:167], v142
	ds_read_b128 v[168:171], v142 offset:1024
	ds_read_b128 v[172:175], v142 offset:2048
	ds_read_b128 v[182:185], v142 offset:3072
	s_nop 0
	s_add_i32 m0, s67, 0xc000
	ds_read_b128 v[190:193], v146
	ds_read_b128 v[194:197], v146 offset:1024
	ds_read_b128 v[198:201], v146 offset:2048
	ds_read_b128 v[202:205], v146 offset:3072
	ds_read_b128 v[212:215], v146 offset:4096
	ds_read_b128 v[216:219], v146 offset:5120
	ds_read_b128 v[220:223], v146 offset:6144
	ds_read_b128 v[224:227], v146 offset:7168
	global_load_lds_dwordx4 v140, s[56:57]
	s_nop 0
	s_add_i32 m0, s67, 0xe000
	s_nop 0
	global_load_lds_dwordx4 v138, s[56:57]
	s_waitcnt vmcnt(8)
	s_waitcnt lgkmcnt(0)
	s_barrier
	s_nop 0
	s_waitcnt lgkmcnt(0)
	v_mfma_f32_16x16x32_bf16 v[126:129], v[148:151], v[190:193], v[126:129]
	v_mfma_f32_16x16x32_bf16 v[122:125], v[156:159], v[190:193], v[122:125]
	v_mfma_f32_16x16x32_bf16 v[110:113], v[148:151], v[198:201], v[110:113]
	v_mfma_f32_16x16x32_bf16 v[106:109], v[156:159], v[198:201], v[106:109]
	v_mfma_f32_16x16x32_bf16 v[94:97], v[148:151], v[212:215], v[94:97]
	v_mfma_f32_16x16x32_bf16 v[90:93], v[156:159], v[212:215], v[90:93]
	v_mfma_f32_16x16x32_bf16 v[78:81], v[148:151], v[220:223], v[78:81]
	v_mfma_f32_16x16x32_bf16 v[74:77], v[156:159], v[220:223], v[74:77]
	v_mfma_f32_16x16x32_bf16 v[126:129], v[152:155], v[194:197], v[126:129]
	v_mfma_f32_16x16x32_bf16 v[122:125], v[160:163], v[194:197], v[122:125]
	v_mfma_f32_16x16x32_bf16 v[110:113], v[152:155], v[202:205], v[110:113]
	v_mfma_f32_16x16x32_bf16 v[106:109], v[160:163], v[202:205], v[106:109]
	v_mfma_f32_16x16x32_bf16 v[94:97], v[152:155], v[216:219], v[94:97]
	v_mfma_f32_16x16x32_bf16 v[90:93], v[160:163], v[216:219], v[90:93]
	v_mfma_f32_16x16x32_bf16 v[78:81], v[152:155], v[224:227], v[78:81]
	v_mfma_f32_16x16x32_bf16 v[74:77], v[160:163], v[224:227], v[74:77]
	s_nop 0
	s_nop 0
	v_mfma_f32_16x16x32_bf16 v[118:121], v[164:167], v[190:193], v[118:121]
	v_mfma_f32_16x16x32_bf16 v[114:117], v[172:175], v[190:193], v[114:117]
	v_mfma_f32_16x16x32_bf16 v[102:105], v[164:167], v[198:201], v[102:105]
	v_mfma_f32_16x16x32_bf16 v[98:101], v[172:175], v[198:201], v[98:101]
	v_mfma_f32_16x16x32_bf16 v[86:89], v[164:167], v[212:215], v[86:89]
	v_mfma_f32_16x16x32_bf16 v[82:85], v[172:175], v[212:215], v[82:85]
	v_mfma_f32_16x16x32_bf16 v[70:73], v[164:167], v[220:223], v[70:73]
	v_mfma_f32_16x16x32_bf16 v[66:69], v[172:175], v[220:223], v[66:69]
	v_mfma_f32_16x16x32_bf16 v[118:121], v[168:171], v[194:197], v[118:121]
	v_mfma_f32_16x16x32_bf16 v[114:117], v[182:185], v[194:197], v[114:117]
	v_mfma_f32_16x16x32_bf16 v[102:105], v[168:171], v[202:205], v[102:105]
	v_mfma_f32_16x16x32_bf16 v[98:101], v[182:185], v[202:205], v[98:101]
	v_mfma_f32_16x16x32_bf16 v[86:89], v[168:171], v[216:219], v[86:89]
	v_mfma_f32_16x16x32_bf16 v[82:85], v[182:185], v[216:219], v[82:85]
	v_mfma_f32_16x16x32_bf16 v[70:73], v[168:171], v[224:227], v[70:73]
	v_mfma_f32_16x16x32_bf16 v[66:69], v[182:185], v[224:227], v[66:69]
	s_nop 0
	s_barrier
	s_add_i32 s79, s79, s66
	s_nop 0
	s_mov_b32 m0, s79
	ds_read_b128 v[190:193], v146 offset:16384
	ds_read_b128 v[194:197], v146 offset:17408
	ds_read_b128 v[198:201], v146 offset:18432
	ds_read_b128 v[202:205], v146 offset:19456
	ds_read_b128 v[212:215], v146 offset:20480
	ds_read_b128 v[216:219], v146 offset:21504
	ds_read_b128 v[220:223], v146 offset:22528
	ds_read_b128 v[224:227], v146 offset:23552
	global_load_lds_dwordx4 v134, s[58:59]
	s_add_i32 m0, s79, 0x2000
	s_add_u32 s80, s58, 0x40000
	s_nop 0
	s_addc_u32 s81, s59, 0
	s_add_i32 s79, s82, s66
	global_load_lds_dwordx4 v130, s[58:59]
	s_nop 0
	s_mov_b32 m0, s79
	s_nop 0
	global_load_lds_dwordx4 v134, s[80:81]
	s_nop 0
	s_add_i32 m0, s79, 0x2000
	s_nop 0
	global_load_lds_dwordx4 v130, s[80:81]
	s_nop 0
	s_add_u32 s98, s60, s90
	s_addc_u32 s99, s61, s91
	s_waitcnt vmcnt(6)
	s_waitcnt lgkmcnt(0)
	s_barrier
	s_nop 0
	s_waitcnt lgkmcnt(0)
	v_mfma_f32_16x16x32_bf16 v[62:65], v[148:151], v[190:193], v[62:65]
	v_mfma_f32_16x16x32_bf16 v[58:61], v[156:159], v[190:193], v[58:61]
	v_mfma_f32_16x16x32_bf16 v[46:49], v[148:151], v[198:201], v[46:49]
	v_mfma_f32_16x16x32_bf16 v[42:45], v[156:159], v[198:201], v[42:45]
	v_mfma_f32_16x16x32_bf16 v[30:33], v[148:151], v[212:215], v[30:33]
	v_mfma_f32_16x16x32_bf16 v[26:29], v[156:159], v[212:215], v[26:29]
	v_mfma_f32_16x16x32_bf16 v[14:17], v[148:151], v[220:223], v[14:17]
	v_mfma_f32_16x16x32_bf16 v[10:13], v[156:159], v[220:223], v[10:13]
	v_mfma_f32_16x16x32_bf16 v[62:65], v[152:155], v[194:197], v[62:65]
	v_mfma_f32_16x16x32_bf16 v[58:61], v[160:163], v[194:197], v[58:61]
	v_mfma_f32_16x16x32_bf16 v[46:49], v[152:155], v[202:205], v[46:49]
	v_mfma_f32_16x16x32_bf16 v[42:45], v[160:163], v[202:205], v[42:45]
	v_mfma_f32_16x16x32_bf16 v[30:33], v[152:155], v[216:219], v[30:33]
	v_mfma_f32_16x16x32_bf16 v[26:29], v[160:163], v[216:219], v[26:29]
	v_mfma_f32_16x16x32_bf16 v[14:17], v[152:155], v[224:227], v[14:17]
	v_mfma_f32_16x16x32_bf16 v[10:13], v[160:163], v[224:227], v[10:13]
	s_nop 0
	s_nop 0
	v_mfma_f32_16x16x32_bf16 v[54:57], v[164:167], v[190:193], v[54:57]
	v_mfma_f32_16x16x32_bf16 v[50:53], v[172:175], v[190:193], v[50:53]
	v_mfma_f32_16x16x32_bf16 v[38:41], v[164:167], v[198:201], v[38:41]
	v_mfma_f32_16x16x32_bf16 v[34:37], v[172:175], v[198:201], v[34:37]
	v_mfma_f32_16x16x32_bf16 v[22:25], v[164:167], v[212:215], v[22:25]
	v_mfma_f32_16x16x32_bf16 v[18:21], v[172:175], v[212:215], v[18:21]
	v_mfma_f32_16x16x32_bf16 v[6:9], v[164:167], v[220:223], v[6:9]
	v_mfma_f32_16x16x32_bf16 v[2:5], v[172:175], v[220:223], v[2:5]
	v_mfma_f32_16x16x32_bf16 v[54:57], v[168:171], v[194:197], v[54:57]
	v_mfma_f32_16x16x32_bf16 v[50:53], v[182:185], v[194:197], v[50:53]
	v_mfma_f32_16x16x32_bf16 v[38:41], v[168:171], v[202:205], v[38:41]
	v_mfma_f32_16x16x32_bf16 v[34:37], v[182:185], v[202:205], v[34:37]
	v_mfma_f32_16x16x32_bf16 v[22:25], v[168:171], v[216:219], v[22:25]
	v_mfma_f32_16x16x32_bf16 v[18:21], v[182:185], v[216:219], v[18:21]
	v_mfma_f32_16x16x32_bf16 v[6:9], v[168:171], v[224:227], v[6:9]
	v_mfma_f32_16x16x32_bf16 v[2:5], v[182:185], v[224:227], v[2:5]
	s_nop 0
	s_barrier
; #define PG8_STAGE(bufoff, gbase, voff) do { _Pragma("unroll") for (int _i = 0; _i < 2; ++_i) \
;         __builtin_amdgcn_global_load_lds((const unsigned*)((const char*)(gbase) + (voff)[_i]), (LAS unsigned*)(lds + (bufoff) + ldsw + _i * 8192), 16, 0, 0); } while (0)
; #define PG8_LDA(dst, b, h) do { _Pragma("unroll") for (int m = 0; m < 4; ++m) _Pragma("unroll") for (int k = 0; k < 2; ++k) dst[m][k] = *(const LAS bf16x8*)(lds + PG8_SA(b, h) + aoff + m * 2048 + k * 1024); } while (0)
; #define PG8_LDB(dst, b, h) do { _Pragma("unroll") for (int n = 0; n < 2; ++n) _Pragma("unroll") for (int k = 0; k < 2; ++k) dst[n][k] = *(const LAS bf16x8*)(lds + PG8_SB(b, h) + boff + n * 2048 + k * 1024); } while (0)
; #define PG8_MMA(ai, bj, At, Bt) do { __builtin_amdgcn_s_setprio(1); _Pragma("unroll") for (int m = 0; m < 4; ++m) _Pragma("unroll") for (int n = 0; n < 2; ++n) _Pragma("unroll") for (int k = 0; k < 2; ++k) \
;         acc[ai][bj][m][n] = __builtin_amdgcn_mfma_f32_16x16x32_bf16(Bt[n][k], At[m][k], acc[ai][bj][m][n], 0, 0, 0); __builtin_amdgcn_s_setprio(0); } while (0)
; #define PG8_WAIT_V(n) asm volatile("s_waitcnt vmcnt(" #n ")" ::: "memory")
; #define PG8_WAIT_L(n) asm volatile("s_waitcnt lgkmcnt(" #n ")" ::: "memory")
; #define PG8_BAR __builtin_amdgcn_s_barrier()
; #define PG8_SCHED __builtin_amdgcn_sched_barrier(0)
; template <class Epi, class Sched>
; DI void gemm_phase(LAS unsigned char* lds, const int K, const Sched& S, const Epi& E) {
;     ...
;             PG8_LDB(B0, 1, 0); PG8_LDB(B1, 1, 1); PG8_SCHED; PG8_LDA(At, 1, 0); PG8_STAGE(PG8_SA(0, 1), a2 + hstep, voffA);
;             PG8_WAIT_V(8); PG8_WAIT_L(0); PG8_BAR; PG8_MMA(0, 0, At, B0); PG8_MMA(0, 1, At, B1); PG8_BAR; PG8_SCHED;
;             PG8_LDA(At, 1, 1); PG8_STAGE(PG8_SB(1, 0), b3, voffB); PG8_STAGE(PG8_SB(1, 1), b3 + hstep, voffB); PG8_STAGE(PG8_SA(1, 0), a3, voffA);
;             PG8_WAIT_V(8); PG8_WAIT_L(0); PG8_BAR; PG8_MMA(1, 0, At, B0); PG8_MMA(1, 1, At, B1); PG8_BAR; PG8_SCHED;
;         }
;         if (wr == 0) PG8_BAR;
	s_add_i32 s79, 0, 0x18000
	v_add_u32_e32 v147, s79, v145
	s_add_i32 s80, 0, 0x1c000
	ds_read_b128 v[148:151], v147
	ds_read_b128 v[152:155], v147 offset:1024
	ds_read_b128 v[156:159], v147 offset:2048
	ds_read_b128 v[160:163], v147 offset:3072
	v_add_u32_e32 v147, s80, v145
	ds_read_b128 v[164:167], v147
	ds_read_b128 v[168:171], v147 offset:1024
	ds_read_b128 v[172:175], v147 offset:2048
	ds_read_b128 v[182:185], v147 offset:3072
	s_mov_b32 m0, s67
	s_nop 0
	ds_read_b128 v[190:193], v146 offset:32768
	ds_read_b128 v[194:197], v146 offset:33792
	ds_read_b128 v[198:201], v146 offset:34816
	ds_read_b128 v[202:205], v146 offset:35840
	ds_read_b128 v[212:215], v146 offset:36864
	ds_read_b128 v[216:219], v146 offset:37888
	ds_read_b128 v[220:223], v146 offset:38912
	ds_read_b128 v[224:227], v146 offset:39936
	global_load_lds_dwordx4 v136, s[60:61]
	s_mov_b32 m0, s68
	s_nop 0
	global_load_lds_dwordx4 v132, s[60:61]
	s_add_u32 s60, s60, 0x40000
	s_addc_u32 s61, s61, 0
	s_mov_b32 m0, s69
	s_nop 0
	global_load_lds_dwordx4 v136, s[60:61]
	s_nop 0
	s_mov_b32 m0, s70
	s_nop 0
	global_load_lds_dwordx4 v132, s[60:61]
	s_waitcnt vmcnt(8)
	s_waitcnt lgkmcnt(0)
	s_barrier
	s_nop 0
	s_waitcnt lgkmcnt(0)
	v_mfma_f32_16x16x32_bf16 v[126:129], v[148:151], v[190:193], v[126:129]
	v_mfma_f32_16x16x32_bf16 v[122:125], v[156:159], v[190:193], v[122:125]
	v_mfma_f32_16x16x32_bf16 v[110:113], v[148:151], v[198:201], v[110:113]
	v_mfma_f32_16x16x32_bf16 v[106:109], v[156:159], v[198:201], v[106:109]
	v_mfma_f32_16x16x32_bf16 v[94:97], v[148:151], v[212:215], v[94:97]
	v_mfma_f32_16x16x32_bf16 v[90:93], v[156:159], v[212:215], v[90:93]
	v_mfma_f32_16x16x32_bf16 v[78:81], v[148:151], v[220:223], v[78:81]
	v_mfma_f32_16x16x32_bf16 v[74:77], v[156:159], v[220:223], v[74:77]
	v_mfma_f32_16x16x32_bf16 v[126:129], v[152:155], v[194:197], v[126:129]
	v_mfma_f32_16x16x32_bf16 v[122:125], v[160:163], v[194:197], v[122:125]
	v_mfma_f32_16x16x32_bf16 v[110:113], v[152:155], v[202:205], v[110:113]
	v_mfma_f32_16x16x32_bf16 v[106:109], v[160:163], v[202:205], v[106:109]
	v_mfma_f32_16x16x32_bf16 v[94:97], v[152:155], v[216:219], v[94:97]
	v_mfma_f32_16x16x32_bf16 v[90:93], v[160:163], v[216:219], v[90:93]
	v_mfma_f32_16x16x32_bf16 v[78:81], v[152:155], v[224:227], v[78:81]
	v_mfma_f32_16x16x32_bf16 v[74:77], v[160:163], v[224:227], v[74:77]
	s_nop 0
	s_nop 0
	v_mfma_f32_16x16x32_bf16 v[118:121], v[164:167], v[190:193], v[118:121]
	v_mfma_f32_16x16x32_bf16 v[114:117], v[172:175], v[190:193], v[114:117]
	v_mfma_f32_16x16x32_bf16 v[102:105], v[164:167], v[198:201], v[102:105]
	v_mfma_f32_16x16x32_bf16 v[98:101], v[172:175], v[198:201], v[98:101]
	v_mfma_f32_16x16x32_bf16 v[86:89], v[164:167], v[212:215], v[86:89]
	v_mfma_f32_16x16x32_bf16 v[82:85], v[172:175], v[212:215], v[82:85]
	v_mfma_f32_16x16x32_bf16 v[70:73], v[164:167], v[220:223], v[70:73]
	v_mfma_f32_16x16x32_bf16 v[66:69], v[172:175], v[220:223], v[66:69]
	v_mfma_f32_16x16x32_bf16 v[118:121], v[168:171], v[194:197], v[118:121]
	v_mfma_f32_16x16x32_bf16 v[114:117], v[182:185], v[194:197], v[114:117]
	v_mfma_f32_16x16x32_bf16 v[102:105], v[168:171], v[202:205], v[102:105]
	v_mfma_f32_16x16x32_bf16 v[98:101], v[182:185], v[202:205], v[98:101]
	v_mfma_f32_16x16x32_bf16 v[86:89], v[168:171], v[216:219], v[86:89]
	v_mfma_f32_16x16x32_bf16 v[82:85], v[182:185], v[216:219], v[82:85]
	v_mfma_f32_16x16x32_bf16 v[70:73], v[168:171], v[224:227], v[70:73]
	v_mfma_f32_16x16x32_bf16 v[66:69], v[182:185], v[224:227], v[66:69]
	s_nop 0
	s_barrier
	s_add_i32 s60, s79, s66
	s_add_u32 s58, s58, 0x80
	s_addc_u32 s59, s59, 0
	s_mov_b32 m0, s60
	ds_read_b128 v[190:193], v146 offset:49152
	ds_read_b128 v[194:197], v146 offset:50176
	ds_read_b128 v[198:201], v146 offset:51200
	ds_read_b128 v[202:205], v146 offset:52224
	ds_read_b128 v[212:215], v146 offset:53248
	ds_read_b128 v[216:219], v146 offset:54272
	ds_read_b128 v[220:223], v146 offset:55296
	ds_read_b128 v[224:227], v146 offset:56320
	global_load_lds_dwordx4 v134, s[58:59]
	s_add_i32 m0, s60, 0x2000
	s_nop 0
	s_nop 0
	s_nop 0
	s_add_i32 s60, s80, s66
	global_load_lds_dwordx4 v130, s[58:59]
	s_add_u32 s58, s58, 0x40000
	s_addc_u32 s59, s59, 0
	s_nop 0
	s_mov_b32 m0, s60
	s_nop 0
	global_load_lds_dwordx4 v134, s[58:59]
	s_nop 0
	s_add_i32 m0, s60, 0x2000
	s_nop 0
	global_load_lds_dwordx4 v130, s[58:59]
	s_nop 0
	s_mov_b32 m0, s73
	s_nop 0
	global_load_lds_dwordx4 v136, s[98:99]
	s_nop 0
	s_mov_b32 m0, s74
	s_nop 0
	global_load_lds_dwordx4 v132, s[98:99]
	s_waitcnt vmcnt(8)
	s_waitcnt lgkmcnt(0)
	s_barrier
	s_nop 0
	s_waitcnt lgkmcnt(0)
	v_mfma_f32_16x16x32_bf16 v[62:65], v[148:151], v[190:193], v[62:65]
	v_mfma_f32_16x16x32_bf16 v[58:61], v[156:159], v[190:193], v[58:61]
	v_mfma_f32_16x16x32_bf16 v[46:49], v[148:151], v[198:201], v[46:49]
	v_mfma_f32_16x16x32_bf16 v[42:45], v[156:159], v[198:201], v[42:45]
	v_mfma_f32_16x16x32_bf16 v[30:33], v[148:151], v[212:215], v[30:33]
	v_mfma_f32_16x16x32_bf16 v[26:29], v[156:159], v[212:215], v[26:29]
	v_mfma_f32_16x16x32_bf16 v[14:17], v[148:151], v[220:223], v[14:17]
	v_mfma_f32_16x16x32_bf16 v[10:13], v[156:159], v[220:223], v[10:13]
	v_mfma_f32_16x16x32_bf16 v[62:65], v[152:155], v[194:197], v[62:65]
	v_mfma_f32_16x16x32_bf16 v[58:61], v[160:163], v[194:197], v[58:61]
	v_mfma_f32_16x16x32_bf16 v[46:49], v[152:155], v[202:205], v[46:49]
	v_mfma_f32_16x16x32_bf16 v[42:45], v[160:163], v[202:205], v[42:45]
	v_mfma_f32_16x16x32_bf16 v[30:33], v[152:155], v[216:219], v[30:33]
	v_mfma_f32_16x16x32_bf16 v[26:29], v[160:163], v[216:219], v[26:29]
	v_mfma_f32_16x16x32_bf16 v[14:17], v[152:155], v[224:227], v[14:17]
	v_mfma_f32_16x16x32_bf16 v[10:13], v[160:163], v[224:227], v[10:13]
	s_nop 0
	s_nop 0
	v_mfma_f32_16x16x32_bf16 v[54:57], v[164:167], v[190:193], v[54:57]
	v_mfma_f32_16x16x32_bf16 v[50:53], v[172:175], v[190:193], v[50:53]
	v_mfma_f32_16x16x32_bf16 v[38:41], v[164:167], v[198:201], v[38:41]
	v_mfma_f32_16x16x32_bf16 v[34:37], v[172:175], v[198:201], v[34:37]
	v_mfma_f32_16x16x32_bf16 v[22:25], v[164:167], v[212:215], v[22:25]
	v_mfma_f32_16x16x32_bf16 v[18:21], v[172:175], v[212:215], v[18:21]
	v_mfma_f32_16x16x32_bf16 v[6:9], v[164:167], v[220:223], v[6:9]
	v_mfma_f32_16x16x32_bf16 v[2:5], v[172:175], v[220:223], v[2:5]
	v_mfma_f32_16x16x32_bf16 v[54:57], v[168:171], v[194:197], v[54:57]
	v_mfma_f32_16x16x32_bf16 v[50:53], v[182:185], v[194:197], v[50:53]
	v_mfma_f32_16x16x32_bf16 v[38:41], v[168:171], v[202:205], v[38:41]
	v_mfma_f32_16x16x32_bf16 v[34:37], v[182:185], v[202:205], v[34:37]
	v_mfma_f32_16x16x32_bf16 v[22:25], v[168:171], v[216:219], v[22:25]
	v_mfma_f32_16x16x32_bf16 v[18:21], v[182:185], v[216:219], v[18:21]
	v_mfma_f32_16x16x32_bf16 v[6:9], v[168:171], v[224:227], v[6:9]
	v_mfma_f32_16x16x32_bf16 v[2:5], v[182:185], v[224:227], v[2:5]
	s_nop 0
	s_barrier
	s_add_i32 s78, s78, 2
	s_add_u32 s49, s49, 0x100
	s_addc_u32 s51, s51, 0
	s_add_u32 s56, s56, 0x100
	s_addc_u32 s57, s57, 0
	s_cmp_gt_u32 s78, 13
	s_cbranch_scc0 .LBB0_338
	s_and_b64 vcc, exec, s[44:45]
	s_cbranch_vccz .LBB0_341
	s_barrier

; #define PG8_STAGE(bufoff, gbase, voff) do { _Pragma("unroll") for (int _i = 0; _i < 2; ++_i) \
;         __builtin_amdgcn_global_load_lds((const unsigned*)((const char*)(gbase) + (voff)[_i]), (LAS unsigned*)(lds + (bufoff) + ldsw + _i * 8192), 16, 0, 0); } while (0)
; #define PG8_LDA(dst, b, h) do { _Pragma("unroll") for (int m = 0; m < 4; ++m) _Pragma("unroll") for (int k = 0; k < 2; ++k) dst[m][k] = *(const LAS bf16x8*)(lds + PG8_SA(b, h) + aoff + m * 2048 + k * 1024); } while (0)
; #define PG8_LDB(dst, b, h) do { _Pragma("unroll") for (int n = 0; n < 2; ++n) _Pragma("unroll") for (int k = 0; k < 2; ++k) dst[n][k] = *(const LAS bf16x8*)(lds + PG8_SB(b, h) + boff + n * 2048 + k * 1024); } while (0)
; #define PG8_MMA(ai, bj, At, Bt) do { __builtin_amdgcn_s_setprio(1); _Pragma("unroll") for (int m = 0; m < 4; ++m) _Pragma("unroll") for (int n = 0; n < 2; ++n) _Pragma("unroll") for (int k = 0; k < 2; ++k) \
;         acc[ai][bj][m][n] = __builtin_amdgcn_mfma_f32_16x16x32_bf16(Bt[n][k], At[m][k], acc[ai][bj][m][n], 0, 0, 0); __builtin_amdgcn_s_setprio(0); } while (0)
; #define PG8_WAIT_V(n) asm volatile("s_waitcnt vmcnt(" #n ")" ::: "memory")
; #define PG8_WAIT_L(n) asm volatile("s_waitcnt lgkmcnt(" #n ")" ::: "memory")
; #define PG8_BAR __builtin_amdgcn_s_barrier()
; #define PG8_SCHED __builtin_amdgcn_sched_barrier(0)
; template <class Epi, class Sched>
; DI void gemm_phase(LAS unsigned char* lds, const int K, const Sched& S, const Epi& E) {
;     ...
;             const char* a1 = cA + (size_t)(t + 1) * kstep;
;             const char* a2 = last ? nA : cA + (size_t)(t + 2) * kstep; const char* b2 = last ? nB : cB + (size_t)(t + 2) * kstep;
;             const char* a3 = a2 + kstep; const char* b3 = b2 + kstep;
;             PG8_LDB(B0, 0, 0); PG8_LDB(B1, 0, 1); PG8_SCHED; PG8_LDA(At, 0, 0); PG8_STAGE(PG8_SA(1, 1), a1 + hstep, voffA);
;             PG8_WAIT_V(8); PG8_WAIT_L(0); PG8_BAR; PG8_MMA(0, 0, At, B0); PG8_MMA(0, 1, At, B1); PG8_BAR; PG8_SCHED;
;             PG8_LDA(At, 0, 1); PG8_STAGE(PG8_SB(0, 0), b2, voffB); PG8_STAGE(PG8_SB(0, 1), b2 + hstep, voffB); PG8_STAGE(PG8_SA(0, 0), a2, voffA);
;             PG8_WAIT_V(8); PG8_WAIT_L(0); PG8_BAR; PG8_MMA(1, 0, At, B0); PG8_MMA(1, 1, At, B1); PG8_BAR; PG8_SCHED;
.LBB0_465:
	s_add_u32 s70, s68, 0xfffc0080
	s_addc_u32 s71, s69, -1
	s_add_i32 vcc_lo, 0, 0x10000
	s_cmp_eq_u32 s79, 12
	s_cselect_b32 s73, s65, s71
	s_cselect_b32 s72, s67, s70
	s_cselect_b32 s71, s74, s78
	s_cselect_b32 s70, s76, s77
	s_add_i32 s42, 0, 0x14000
	v_add_u32_e32 v142, vcc_lo, v203
	v_add_u32_e32 v158, s42, v203
	ds_read_b128 v[130:133], v142
	ds_read_b128 v[134:137], v142 offset:1024
	ds_read_b128 v[138:141], v142 offset:2048
	ds_read_b128 v[142:145], v142 offset:3072
	ds_read_b128 v[146:149], v158
	ds_read_b128 v[150:153], v158 offset:1024
	ds_read_b128 v[154:157], v158 offset:2048
	ds_read_b128 v[158:161], v158 offset:3072
	s_nop 0
	s_add_i32 m0, s86, 0xc000
	ds_read_b128 v[174:177], v204
	ds_read_b128 v[182:185], v204 offset:1024
	ds_read_b128 v[190:193], v204 offset:2048
	ds_read_b128 v[194:197], v204 offset:3072
	ds_read_b128 v[198:201], v204 offset:4096
	ds_read_b128 v[212:215], v204 offset:5120
	ds_read_b128 v[216:219], v204 offset:6144
	ds_read_b128 v[220:223], v204 offset:7168
	global_load_lds_dwordx4 v172, s[68:69]
	s_nop 0
	s_add_i32 m0, s86, 0xe000
	s_nop 0
	global_load_lds_dwordx4 v170, s[68:69]
	s_waitcnt vmcnt(8)
	s_waitcnt lgkmcnt(0)
	s_barrier
	s_nop 0
	s_waitcnt lgkmcnt(0)
	v_mfma_f32_16x16x32_bf16 v[126:129], v[130:133], v[174:177], v[126:129]
	v_mfma_f32_16x16x32_bf16 v[122:125], v[138:141], v[174:177], v[122:125]
	v_mfma_f32_16x16x32_bf16 v[110:113], v[130:133], v[190:193], v[110:113]
	v_mfma_f32_16x16x32_bf16 v[106:109], v[138:141], v[190:193], v[106:109]
	v_mfma_f32_16x16x32_bf16 v[94:97], v[130:133], v[198:201], v[94:97]
	v_mfma_f32_16x16x32_bf16 v[90:93], v[138:141], v[198:201], v[90:93]
	v_mfma_f32_16x16x32_bf16 v[78:81], v[130:133], v[216:219], v[78:81]
	v_mfma_f32_16x16x32_bf16 v[74:77], v[138:141], v[216:219], v[74:77]
	v_mfma_f32_16x16x32_bf16 v[126:129], v[134:137], v[182:185], v[126:129]
	v_mfma_f32_16x16x32_bf16 v[122:125], v[142:145], v[182:185], v[122:125]
	v_mfma_f32_16x16x32_bf16 v[110:113], v[134:137], v[194:197], v[110:113]
	v_mfma_f32_16x16x32_bf16 v[106:109], v[142:145], v[194:197], v[106:109]
	v_mfma_f32_16x16x32_bf16 v[94:97], v[134:137], v[212:215], v[94:97]
	v_mfma_f32_16x16x32_bf16 v[90:93], v[142:145], v[212:215], v[90:93]
	v_mfma_f32_16x16x32_bf16 v[78:81], v[134:137], v[220:223], v[78:81]
	v_mfma_f32_16x16x32_bf16 v[74:77], v[142:145], v[220:223], v[74:77]
	s_nop 0
	s_nop 0
	v_mfma_f32_16x16x32_bf16 v[118:121], v[146:149], v[174:177], v[118:121]
	v_mfma_f32_16x16x32_bf16 v[114:117], v[154:157], v[174:177], v[114:117]
	v_mfma_f32_16x16x32_bf16 v[102:105], v[146:149], v[190:193], v[102:105]
	v_mfma_f32_16x16x32_bf16 v[98:101], v[154:157], v[190:193], v[98:101]
	v_mfma_f32_16x16x32_bf16 v[86:89], v[146:149], v[198:201], v[86:89]
	v_mfma_f32_16x16x32_bf16 v[82:85], v[154:157], v[198:201], v[82:85]
	v_mfma_f32_16x16x32_bf16 v[70:73], v[146:149], v[216:219], v[70:73]
	v_mfma_f32_16x16x32_bf16 v[66:69], v[154:157], v[216:219], v[66:69]
	v_mfma_f32_16x16x32_bf16 v[118:121], v[150:153], v[182:185], v[118:121]
	v_mfma_f32_16x16x32_bf16 v[114:117], v[158:161], v[182:185], v[114:117]
	v_mfma_f32_16x16x32_bf16 v[102:105], v[150:153], v[194:197], v[102:105]
	v_mfma_f32_16x16x32_bf16 v[98:101], v[158:161], v[194:197], v[98:101]
	v_mfma_f32_16x16x32_bf16 v[86:89], v[150:153], v[212:215], v[86:89]
	v_mfma_f32_16x16x32_bf16 v[82:85], v[158:161], v[212:215], v[82:85]
	v_mfma_f32_16x16x32_bf16 v[70:73], v[150:153], v[220:223], v[70:73]
	v_mfma_f32_16x16x32_bf16 v[66:69], v[158:161], v[220:223], v[66:69]
	s_nop 0
	s_barrier
	s_add_i32 s43, vcc_lo, s85
	s_nop 0
	s_mov_b32 m0, s43
	ds_read_b128 v[174:177], v204 offset:16384
	ds_read_b128 v[182:185], v204 offset:17408
	ds_read_b128 v[190:193], v204 offset:18432
	ds_read_b128 v[194:197], v204 offset:19456
	ds_read_b128 v[198:201], v204 offset:20480
	ds_read_b128 v[212:215], v204 offset:21504
	ds_read_b128 v[216:219], v204 offset:22528
	ds_read_b128 v[220:223], v204 offset:23552
	global_load_lds_dwordx4 v164, s[70:71]
	s_add_i32 m0, s43, 0x2000
	s_add_u32 vcc_lo, s70, 0x40000
	s_nop 0
	s_addc_u32 vcc_hi, s71, 0
	s_add_i32 s42, s42, s85
	global_load_lds_dwordx4 v168, s[70:71]
	s_nop 0
	s_mov_b32 m0, s42
	s_nop 0
	global_load_lds_dwordx4 v164, vcc
	s_nop 0
	s_add_i32 m0, s42, 0x2000
	s_nop 0
	global_load_lds_dwordx4 v168, vcc
	s_nop 0
	s_add_u32 s98, s72, s90
	s_addc_u32 s99, s73, s91
	s_waitcnt vmcnt(6)
	s_waitcnt lgkmcnt(0)
	s_barrier
	s_nop 0
	s_waitcnt lgkmcnt(0)
	v_mfma_f32_16x16x32_bf16 v[62:65], v[130:133], v[174:177], v[62:65]
	v_mfma_f32_16x16x32_bf16 v[58:61], v[138:141], v[174:177], v[58:61]
	v_mfma_f32_16x16x32_bf16 v[46:49], v[130:133], v[190:193], v[46:49]
	v_mfma_f32_16x16x32_bf16 v[42:45], v[138:141], v[190:193], v[42:45]
	v_mfma_f32_16x16x32_bf16 v[30:33], v[130:133], v[198:201], v[30:33]
	v_mfma_f32_16x16x32_bf16 v[26:29], v[138:141], v[198:201], v[26:29]
	v_mfma_f32_16x16x32_bf16 v[14:17], v[130:133], v[216:219], v[14:17]
	v_mfma_f32_16x16x32_bf16 v[10:13], v[138:141], v[216:219], v[10:13]
	v_mfma_f32_16x16x32_bf16 v[62:65], v[134:137], v[182:185], v[62:65]
	v_mfma_f32_16x16x32_bf16 v[58:61], v[142:145], v[182:185], v[58:61]
	v_mfma_f32_16x16x32_bf16 v[46:49], v[134:137], v[194:197], v[46:49]
	v_mfma_f32_16x16x32_bf16 v[42:45], v[142:145], v[194:197], v[42:45]
	v_mfma_f32_16x16x32_bf16 v[30:33], v[134:137], v[212:215], v[30:33]
	v_mfma_f32_16x16x32_bf16 v[26:29], v[142:145], v[212:215], v[26:29]
	v_mfma_f32_16x16x32_bf16 v[14:17], v[134:137], v[220:223], v[14:17]
	v_mfma_f32_16x16x32_bf16 v[10:13], v[142:145], v[220:223], v[10:13]
	s_nop 0
	s_nop 0
	v_mfma_f32_16x16x32_bf16 v[54:57], v[146:149], v[174:177], v[54:57]
	v_mfma_f32_16x16x32_bf16 v[50:53], v[154:157], v[174:177], v[50:53]
	v_mfma_f32_16x16x32_bf16 v[38:41], v[146:149], v[190:193], v[38:41]
	v_mfma_f32_16x16x32_bf16 v[34:37], v[154:157], v[190:193], v[34:37]
	v_mfma_f32_16x16x32_bf16 v[22:25], v[146:149], v[198:201], v[22:25]
	v_mfma_f32_16x16x32_bf16 v[18:21], v[154:157], v[198:201], v[18:21]
	v_mfma_f32_16x16x32_bf16 v[6:9], v[146:149], v[216:219], v[6:9]
	v_mfma_f32_16x16x32_bf16 v[2:5], v[154:157], v[216:219], v[2:5]
	v_mfma_f32_16x16x32_bf16 v[54:57], v[150:153], v[182:185], v[54:57]
	v_mfma_f32_16x16x32_bf16 v[50:53], v[158:161], v[182:185], v[50:53]
	v_mfma_f32_16x16x32_bf16 v[38:41], v[150:153], v[194:197], v[38:41]
	v_mfma_f32_16x16x32_bf16 v[34:37], v[158:161], v[194:197], v[34:37]
	v_mfma_f32_16x16x32_bf16 v[22:25], v[150:153], v[212:215], v[22:25]
	v_mfma_f32_16x16x32_bf16 v[18:21], v[158:161], v[212:215], v[18:21]
	v_mfma_f32_16x16x32_bf16 v[6:9], v[150:153], v[220:223], v[6:9]
	v_mfma_f32_16x16x32_bf16 v[2:5], v[158:161], v[220:223], v[2:5]
	s_nop 0
	s_barrier
; #define PG8_STAGE(bufoff, gbase, voff) do { _Pragma("unroll") for (int _i = 0; _i < 2; ++_i) \
;         __builtin_amdgcn_global_load_lds((const unsigned*)((const char*)(gbase) + (voff)[_i]), (LAS unsigned*)(lds + (bufoff) + ldsw + _i * 8192), 16, 0, 0); } while (0)
; #define PG8_LDA(dst, b, h) do { _Pragma("unroll") for (int m = 0; m < 4; ++m) _Pragma("unroll") for (int k = 0; k < 2; ++k) dst[m][k] = *(const LAS bf16x8*)(lds + PG8_SA(b, h) + aoff + m * 2048 + k * 1024); } while (0)
; #define PG8_LDB(dst, b, h) do { _Pragma("unroll") for (int n = 0; n < 2; ++n) _Pragma("unroll") for (int k = 0; k < 2; ++k) dst[n][k] = *(const LAS bf16x8*)(lds + PG8_SB(b, h) + boff + n * 2048 + k * 1024); } while (0)
; #define PG8_MMA(ai, bj, At, Bt) do { __builtin_amdgcn_s_setprio(1); _Pragma("unroll") for (int m = 0; m < 4; ++m) _Pragma("unroll") for (int n = 0; n < 2; ++n) _Pragma("unroll") for (int k = 0; k < 2; ++k) \
;         acc[ai][bj][m][n] = __builtin_amdgcn_mfma_f32_16x16x32_bf16(Bt[n][k], At[m][k], acc[ai][bj][m][n], 0, 0, 0); __builtin_amdgcn_s_setprio(0); } while (0)
; #define PG8_WAIT_V(n) asm volatile("s_waitcnt vmcnt(" #n ")" ::: "memory")
; #define PG8_WAIT_L(n) asm volatile("s_waitcnt lgkmcnt(" #n ")" ::: "memory")
; #define PG8_BAR __builtin_amdgcn_s_barrier()
; #define PG8_SCHED __builtin_amdgcn_sched_barrier(0)
; template <class Epi, class Sched>
; DI void gemm_phase(LAS unsigned char* lds, const int K, const Sched& S, const Epi& E) {
;     ...
;             PG8_LDB(B0, 1, 0); PG8_LDB(B1, 1, 1); PG8_SCHED; PG8_LDA(At, 1, 0); PG8_STAGE(PG8_SA(0, 1), a2 + hstep, voffA);
;             PG8_WAIT_V(8); PG8_WAIT_L(0); PG8_BAR; PG8_MMA(0, 0, At, B0); PG8_MMA(0, 1, At, B1); PG8_BAR; PG8_SCHED;
;             PG8_LDA(At, 1, 1); PG8_STAGE(PG8_SB(1, 0), b3, voffB); PG8_STAGE(PG8_SB(1, 1), b3 + hstep, voffB); PG8_STAGE(PG8_SA(1, 0), a3, voffA);
;             PG8_WAIT_V(8); PG8_WAIT_L(0); PG8_BAR; PG8_MMA(1, 0, At, B0); PG8_MMA(1, 1, At, B1); PG8_BAR; PG8_SCHED;
;         }
;         if (wr == 0) PG8_BAR;
	s_add_i32 s42, 0, 0x18000
	s_add_i32 s43, 0, 0x1c000
	v_add_u32_e32 v142, s42, v203
	v_add_u32_e32 v158, s43, v203
	ds_read_b128 v[130:133], v142
	ds_read_b128 v[134:137], v142 offset:1024
	ds_read_b128 v[138:141], v142 offset:2048
	ds_read_b128 v[142:145], v142 offset:3072
	ds_read_b128 v[146:149], v158
	ds_read_b128 v[150:153], v158 offset:1024
	ds_read_b128 v[154:157], v158 offset:2048
	ds_read_b128 v[158:161], v158 offset:3072
	s_mov_b32 m0, s86
	s_nop 0
	ds_read_b128 v[174:177], v204 offset:32768
	ds_read_b128 v[182:185], v204 offset:33792
	ds_read_b128 v[190:193], v204 offset:34816
	ds_read_b128 v[194:197], v204 offset:35840
	ds_read_b128 v[198:201], v204 offset:36864
	ds_read_b128 v[212:215], v204 offset:37888
	ds_read_b128 v[216:219], v204 offset:38912
	ds_read_b128 v[220:223], v204 offset:39936
	global_load_lds_dwordx4 v162, s[72:73]
	s_mov_b32 m0, s87
	s_nop 0
	global_load_lds_dwordx4 v166, s[72:73]
	s_add_u32 s72, s72, 0x40000
	s_addc_u32 s73, s73, 0
	s_mov_b32 m0, s92
	s_nop 0
	global_load_lds_dwordx4 v162, s[72:73]
	s_nop 0
	s_mov_b32 m0, s94
	s_nop 0
	global_load_lds_dwordx4 v166, s[72:73]
	s_waitcnt vmcnt(8)
	s_waitcnt lgkmcnt(0)
	s_barrier
	s_nop 0
	s_waitcnt lgkmcnt(0)
	v_mfma_f32_16x16x32_bf16 v[126:129], v[130:133], v[174:177], v[126:129]
	v_mfma_f32_16x16x32_bf16 v[122:125], v[138:141], v[174:177], v[122:125]
	v_mfma_f32_16x16x32_bf16 v[110:113], v[130:133], v[190:193], v[110:113]
	v_mfma_f32_16x16x32_bf16 v[106:109], v[138:141], v[190:193], v[106:109]
	v_mfma_f32_16x16x32_bf16 v[94:97], v[130:133], v[198:201], v[94:97]
	v_mfma_f32_16x16x32_bf16 v[90:93], v[138:141], v[198:201], v[90:93]
	v_mfma_f32_16x16x32_bf16 v[78:81], v[130:133], v[216:219], v[78:81]
	v_mfma_f32_16x16x32_bf16 v[74:77], v[138:141], v[216:219], v[74:77]
	v_mfma_f32_16x16x32_bf16 v[126:129], v[134:137], v[182:185], v[126:129]
	v_mfma_f32_16x16x32_bf16 v[122:125], v[142:145], v[182:185], v[122:125]
	v_mfma_f32_16x16x32_bf16 v[110:113], v[134:137], v[194:197], v[110:113]
	v_mfma_f32_16x16x32_bf16 v[106:109], v[142:145], v[194:197], v[106:109]
	v_mfma_f32_16x16x32_bf16 v[94:97], v[134:137], v[212:215], v[94:97]
	v_mfma_f32_16x16x32_bf16 v[90:93], v[142:145], v[212:215], v[90:93]
	v_mfma_f32_16x16x32_bf16 v[78:81], v[134:137], v[220:223], v[78:81]
	v_mfma_f32_16x16x32_bf16 v[74:77], v[142:145], v[220:223], v[74:77]
	s_nop 0
	s_nop 0
	v_mfma_f32_16x16x32_bf16 v[118:121], v[146:149], v[174:177], v[118:121]
	v_mfma_f32_16x16x32_bf16 v[114:117], v[154:157], v[174:177], v[114:117]
	v_mfma_f32_16x16x32_bf16 v[102:105], v[146:149], v[190:193], v[102:105]
	v_mfma_f32_16x16x32_bf16 v[98:101], v[154:157], v[190:193], v[98:101]
	v_mfma_f32_16x16x32_bf16 v[86:89], v[146:149], v[198:201], v[86:89]
	v_mfma_f32_16x16x32_bf16 v[82:85], v[154:157], v[198:201], v[82:85]
	v_mfma_f32_16x16x32_bf16 v[70:73], v[146:149], v[216:219], v[70:73]
	v_mfma_f32_16x16x32_bf16 v[66:69], v[154:157], v[216:219], v[66:69]
	v_mfma_f32_16x16x32_bf16 v[118:121], v[150:153], v[182:185], v[118:121]
	v_mfma_f32_16x16x32_bf16 v[114:117], v[158:161], v[182:185], v[114:117]
	v_mfma_f32_16x16x32_bf16 v[102:105], v[150:153], v[194:197], v[102:105]
	v_mfma_f32_16x16x32_bf16 v[98:101], v[158:161], v[194:197], v[98:101]
	v_mfma_f32_16x16x32_bf16 v[86:89], v[150:153], v[212:215], v[86:89]
	v_mfma_f32_16x16x32_bf16 v[82:85], v[158:161], v[212:215], v[82:85]
	v_mfma_f32_16x16x32_bf16 v[70:73], v[150:153], v[220:223], v[70:73]
	v_mfma_f32_16x16x32_bf16 v[66:69], v[158:161], v[220:223], v[66:69]
	s_nop 0
	s_barrier
	s_add_i32 s42, s42, s85
	s_add_u32 s70, s70, 0x80
	s_addc_u32 s71, s71, 0
	s_mov_b32 m0, s42
	ds_read_b128 v[174:177], v204 offset:49152
	ds_read_b128 v[182:185], v204 offset:50176
	ds_read_b128 v[190:193], v204 offset:51200
	ds_read_b128 v[194:197], v204 offset:52224
	ds_read_b128 v[198:201], v204 offset:53248
	ds_read_b128 v[212:215], v204 offset:54272
	ds_read_b128 v[216:219], v204 offset:55296
	ds_read_b128 v[220:223], v204 offset:56320
	global_load_lds_dwordx4 v164, s[70:71]
	s_add_i32 m0, s42, 0x2000
	s_nop 0
	s_nop 0
	s_nop 0
	s_add_i32 s42, s43, s85
	global_load_lds_dwordx4 v168, s[70:71]
	s_add_u32 s70, s70, 0x40000
	s_addc_u32 s71, s71, 0
	s_nop 0
	s_mov_b32 m0, s42
	s_nop 0
	global_load_lds_dwordx4 v164, s[70:71]
	s_nop 0
	s_add_i32 m0, s42, 0x2000
	s_nop 0
	global_load_lds_dwordx4 v168, s[70:71]
	s_nop 0
	s_mov_b32 m0, s45
	s_nop 0
	global_load_lds_dwordx4 v162, s[98:99]
	s_nop 0
	s_mov_b32 m0, s50
	s_nop 0
	global_load_lds_dwordx4 v166, s[98:99]
	s_waitcnt vmcnt(8)
	s_waitcnt lgkmcnt(0)
	s_barrier
	s_nop 0
	s_waitcnt lgkmcnt(0)
	v_mfma_f32_16x16x32_bf16 v[62:65], v[130:133], v[174:177], v[62:65]
	v_mfma_f32_16x16x32_bf16 v[58:61], v[138:141], v[174:177], v[58:61]
	v_mfma_f32_16x16x32_bf16 v[46:49], v[130:133], v[190:193], v[46:49]
	v_mfma_f32_16x16x32_bf16 v[42:45], v[138:141], v[190:193], v[42:45]
	v_mfma_f32_16x16x32_bf16 v[30:33], v[130:133], v[198:201], v[30:33]
	v_mfma_f32_16x16x32_bf16 v[26:29], v[138:141], v[198:201], v[26:29]
	v_mfma_f32_16x16x32_bf16 v[14:17], v[130:133], v[216:219], v[14:17]
	v_mfma_f32_16x16x32_bf16 v[10:13], v[138:141], v[216:219], v[10:13]
	v_mfma_f32_16x16x32_bf16 v[62:65], v[134:137], v[182:185], v[62:65]
	v_mfma_f32_16x16x32_bf16 v[58:61], v[142:145], v[182:185], v[58:61]
	v_mfma_f32_16x16x32_bf16 v[46:49], v[134:137], v[194:197], v[46:49]
	v_mfma_f32_16x16x32_bf16 v[42:45], v[142:145], v[194:197], v[42:45]
	v_mfma_f32_16x16x32_bf16 v[30:33], v[134:137], v[212:215], v[30:33]
	v_mfma_f32_16x16x32_bf16 v[26:29], v[142:145], v[212:215], v[26:29]
	v_mfma_f32_16x16x32_bf16 v[14:17], v[134:137], v[220:223], v[14:17]
	v_mfma_f32_16x16x32_bf16 v[10:13], v[142:145], v[220:223], v[10:13]
	s_nop 0
	s_nop 0
	v_mfma_f32_16x16x32_bf16 v[54:57], v[146:149], v[174:177], v[54:57]
	v_mfma_f32_16x16x32_bf16 v[50:53], v[154:157], v[174:177], v[50:53]
	v_mfma_f32_16x16x32_bf16 v[38:41], v[146:149], v[190:193], v[38:41]
	v_mfma_f32_16x16x32_bf16 v[34:37], v[154:157], v[190:193], v[34:37]
	v_mfma_f32_16x16x32_bf16 v[22:25], v[146:149], v[198:201], v[22:25]
	v_mfma_f32_16x16x32_bf16 v[18:21], v[154:157], v[198:201], v[18:21]
	v_mfma_f32_16x16x32_bf16 v[6:9], v[146:149], v[216:219], v[6:9]
	v_mfma_f32_16x16x32_bf16 v[2:5], v[154:157], v[216:219], v[2:5]
	v_mfma_f32_16x16x32_bf16 v[54:57], v[150:153], v[182:185], v[54:57]
	v_mfma_f32_16x16x32_bf16 v[50:53], v[158:161], v[182:185], v[50:53]
	v_mfma_f32_16x16x32_bf16 v[38:41], v[150:153], v[194:197], v[38:41]
	v_mfma_f32_16x16x32_bf16 v[34:37], v[158:161], v[194:197], v[34:37]
	v_mfma_f32_16x16x32_bf16 v[22:25], v[150:153], v[212:215], v[22:25]
	v_mfma_f32_16x16x32_bf16 v[18:21], v[158:161], v[212:215], v[18:21]
	v_mfma_f32_16x16x32_bf16 v[6:9], v[150:153], v[220:223], v[6:9]
	v_mfma_f32_16x16x32_bf16 v[2:5], v[158:161], v[220:223], v[2:5]
	s_nop 0
	s_barrier
	s_add_i32 s79, s79, 2
	s_add_u32 s77, s77, 0x100
	s_addc_u32 s78, s78, 0
	s_add_u32 s68, s68, 0x100
	s_addc_u32 s69, s69, 0
	s_cmp_gt_u32 s79, 13
	s_cbranch_scc0 .LBB0_465
	s_and_b64 vcc, exec, s[48:49]
	s_cbranch_vccz .LBB0_468
	s_barrier

; #define PG8_STAGE(bufoff, gbase, voff) do { _Pragma("unroll") for (int _i = 0; _i < 2; ++_i) \
;         __builtin_amdgcn_global_load_lds((const unsigned*)((const char*)(gbase) + (voff)[_i]), (LAS unsigned*)(lds + (bufoff) + ldsw + _i * 8192), 16, 0, 0); } while (0)
; #define PG8_LDA(dst, b, h) do { _Pragma("unroll") for (int m = 0; m < 4; ++m) _Pragma("unroll") for (int k = 0; k < 2; ++k) dst[m][k] = *(const LAS bf16x8*)(lds + PG8_SA(b, h) + aoff + m * 2048 + k * 1024); } while (0)
; #define PG8_LDB(dst, b, h) do { _Pragma("unroll") for (int n = 0; n < 2; ++n) _Pragma("unroll") for (int k = 0; k < 2; ++k) dst[n][k] = *(const LAS bf16x8*)(lds + PG8_SB(b, h) + boff + n * 2048 + k * 1024); } while (0)
; #define PG8_MMA(ai, bj, At, Bt) do { __builtin_amdgcn_s_setprio(1); _Pragma("unroll") for (int m = 0; m < 4; ++m) _Pragma("unroll") for (int n = 0; n < 2; ++n) _Pragma("unroll") for (int k = 0; k < 2; ++k) \
;         acc[ai][bj][m][n] = __builtin_amdgcn_mfma_f32_16x16x32_bf16(Bt[n][k], At[m][k], acc[ai][bj][m][n], 0, 0, 0); __builtin_amdgcn_s_setprio(0); } while (0)
; #define PG8_WAIT_V(n) asm volatile("s_waitcnt vmcnt(" #n ")" ::: "memory")
; #define PG8_WAIT_L(n) asm volatile("s_waitcnt lgkmcnt(" #n ")" ::: "memory")
; #define PG8_BAR __builtin_amdgcn_s_barrier()
; #define PG8_SCHED __builtin_amdgcn_sched_barrier(0)
; template <class Epi, class Sched>
; DI void gemm_phase(LAS unsigned char* lds, const int K, const Sched& S, const Epi& E) {
;     ...
;             const char* a1 = cA + (size_t)(t + 1) * kstep;
;             const char* a2 = last ? nA : cA + (size_t)(t + 2) * kstep; const char* b2 = last ? nB : cB + (size_t)(t + 2) * kstep;
;             const char* a3 = a2 + kstep; const char* b3 = b2 + kstep;
;             PG8_LDB(B0, 0, 0); PG8_LDB(B1, 0, 1); PG8_SCHED; PG8_LDA(At, 0, 0); PG8_STAGE(PG8_SA(1, 1), a1 + hstep, voffA);
;             PG8_WAIT_V(8); PG8_WAIT_L(0); PG8_BAR; PG8_MMA(0, 0, At, B0); PG8_MMA(0, 1, At, B1); PG8_BAR; PG8_SCHED;
;             PG8_LDA(At, 0, 1); PG8_STAGE(PG8_SB(0, 0), b2, voffB); PG8_STAGE(PG8_SB(0, 1), b2 + hstep, voffB); PG8_STAGE(PG8_SA(0, 0), a2, voffA);
;             PG8_WAIT_V(8); PG8_WAIT_L(0); PG8_BAR; PG8_MMA(1, 0, At, B0); PG8_MMA(1, 1, At, B1); PG8_BAR; PG8_SCHED;
.LBB0_648:
	s_add_u32 s66, s64, 0xfffc0080
	s_addc_u32 s67, s65, -1
	s_add_i32 s92, 0, 0x10000
	s_cmp_eq_u32 s63, 12
	s_cselect_b32 s69, s59, s67
	s_cselect_b32 s68, s58, s66
	v_add_u32_e32 v1, s92, v154
	s_cselect_b32 s67, s61, s57
	s_cselect_b32 s66, s60, s55
	s_add_i32 s95, 0, 0x14000
	ds_read_b128 v[142:145], v1
	s_waitcnt lgkmcnt(0)
	ds_read_b128 v[146:149], v1 offset:1024
	ds_read_b128 v[156:159], v1 offset:2048
	ds_read_b128 v[160:163], v1 offset:3072
	v_add_u32_e32 v1, s95, v154
	ds_read_b128 v[164:167], v1
	ds_read_b128 v[168:171], v1 offset:1024
	ds_read_b128 v[172:175], v1 offset:2048
	ds_read_b128 v[182:185], v1 offset:3072
	s_nop 0
	s_add_i32 m0, s76, 0xc000
	ds_read_b128 v[190:193], v155
	ds_read_b128 v[194:197], v155 offset:1024
	ds_read_b128 v[198:201], v155 offset:2048
	ds_read_b128 v[202:205], v155 offset:3072
	ds_read_b128 v[212:215], v155 offset:4096
	ds_read_b128 v[216:219], v155 offset:5120
	ds_read_b128 v[220:223], v155 offset:6144
	ds_read_b128 v[224:227], v155 offset:7168
	global_load_lds_dwordx4 v140, s[64:65]
	s_nop 0
	s_add_i32 m0, s76, 0xe000
	s_nop 0
	global_load_lds_dwordx4 v138, s[64:65]
	s_waitcnt vmcnt(8)
	s_waitcnt lgkmcnt(0)
	s_barrier
	s_nop 0
	s_waitcnt lgkmcnt(0)
	v_mfma_f32_16x16x32_bf16 v[126:129], v[142:145], v[190:193], v[126:129]
	v_mfma_f32_16x16x32_bf16 v[122:125], v[156:159], v[190:193], v[122:125]
	v_mfma_f32_16x16x32_bf16 v[110:113], v[142:145], v[198:201], v[110:113]
	v_mfma_f32_16x16x32_bf16 v[106:109], v[156:159], v[198:201], v[106:109]
	v_mfma_f32_16x16x32_bf16 v[94:97], v[142:145], v[212:215], v[94:97]
	v_mfma_f32_16x16x32_bf16 v[90:93], v[156:159], v[212:215], v[90:93]
	v_mfma_f32_16x16x32_bf16 v[78:81], v[142:145], v[220:223], v[78:81]
	v_mfma_f32_16x16x32_bf16 v[74:77], v[156:159], v[220:223], v[74:77]
	v_mfma_f32_16x16x32_bf16 v[126:129], v[146:149], v[194:197], v[126:129]
	v_mfma_f32_16x16x32_bf16 v[122:125], v[160:163], v[194:197], v[122:125]
	v_mfma_f32_16x16x32_bf16 v[110:113], v[146:149], v[202:205], v[110:113]
	v_mfma_f32_16x16x32_bf16 v[106:109], v[160:163], v[202:205], v[106:109]
	v_mfma_f32_16x16x32_bf16 v[94:97], v[146:149], v[216:219], v[94:97]
	v_mfma_f32_16x16x32_bf16 v[90:93], v[160:163], v[216:219], v[90:93]
	v_mfma_f32_16x16x32_bf16 v[78:81], v[146:149], v[224:227], v[78:81]
	v_mfma_f32_16x16x32_bf16 v[74:77], v[160:163], v[224:227], v[74:77]
	s_nop 0
	s_nop 0
	v_mfma_f32_16x16x32_bf16 v[118:121], v[164:167], v[190:193], v[118:121]
	v_mfma_f32_16x16x32_bf16 v[114:117], v[172:175], v[190:193], v[114:117]
	v_mfma_f32_16x16x32_bf16 v[102:105], v[164:167], v[198:201], v[102:105]
	v_mfma_f32_16x16x32_bf16 v[98:101], v[172:175], v[198:201], v[98:101]
	v_mfma_f32_16x16x32_bf16 v[86:89], v[164:167], v[212:215], v[86:89]
	v_mfma_f32_16x16x32_bf16 v[82:85], v[172:175], v[212:215], v[82:85]
	v_mfma_f32_16x16x32_bf16 v[70:73], v[164:167], v[220:223], v[70:73]
	v_mfma_f32_16x16x32_bf16 v[66:69], v[172:175], v[220:223], v[66:69]
	v_mfma_f32_16x16x32_bf16 v[118:121], v[168:171], v[194:197], v[118:121]
	v_mfma_f32_16x16x32_bf16 v[114:117], v[182:185], v[194:197], v[114:117]
	v_mfma_f32_16x16x32_bf16 v[102:105], v[168:171], v[202:205], v[102:105]
	v_mfma_f32_16x16x32_bf16 v[98:101], v[182:185], v[202:205], v[98:101]
	v_mfma_f32_16x16x32_bf16 v[86:89], v[168:171], v[216:219], v[86:89]
	v_mfma_f32_16x16x32_bf16 v[82:85], v[182:185], v[216:219], v[82:85]
	v_mfma_f32_16x16x32_bf16 v[70:73], v[168:171], v[224:227], v[70:73]
	v_mfma_f32_16x16x32_bf16 v[66:69], v[182:185], v[224:227], v[66:69]
	s_nop 0
	s_barrier
	s_add_i32 s92, s92, s75
	s_nop 0
	s_mov_b32 m0, s92
	ds_read_b128 v[190:193], v155 offset:16384
	ds_read_b128 v[194:197], v155 offset:17408
	ds_read_b128 v[198:201], v155 offset:18432
	ds_read_b128 v[202:205], v155 offset:19456
	ds_read_b128 v[212:215], v155 offset:20480
	ds_read_b128 v[216:219], v155 offset:21504
	ds_read_b128 v[220:223], v155 offset:22528
	ds_read_b128 v[224:227], v155 offset:23552
	global_load_lds_dwordx4 v132, s[66:67]
	s_add_i32 m0, s92, 0x2000
	s_add_u32 vcc_lo, s66, 0x40000
	s_nop 0
	s_addc_u32 vcc_hi, s67, 0
	s_add_i32 s92, s95, s75
	global_load_lds_dwordx4 v136, s[66:67]
	s_nop 0
	s_mov_b32 m0, s92
	s_nop 0
	global_load_lds_dwordx4 v132, vcc
	s_nop 0
	s_add_i32 m0, s92, 0x2000
	s_nop 0
	global_load_lds_dwordx4 v136, vcc
	s_nop 0
	s_add_u32 s98, s68, s90
	s_addc_u32 s99, s69, s91
	s_waitcnt vmcnt(6)
	s_waitcnt lgkmcnt(0)
	s_barrier
	s_nop 0
	s_waitcnt lgkmcnt(0)
	v_mfma_f32_16x16x32_bf16 v[62:65], v[142:145], v[190:193], v[62:65]
	v_mfma_f32_16x16x32_bf16 v[58:61], v[156:159], v[190:193], v[58:61]
	v_mfma_f32_16x16x32_bf16 v[46:49], v[142:145], v[198:201], v[46:49]
	v_mfma_f32_16x16x32_bf16 v[42:45], v[156:159], v[198:201], v[42:45]
	v_mfma_f32_16x16x32_bf16 v[30:33], v[142:145], v[212:215], v[30:33]
	v_mfma_f32_16x16x32_bf16 v[26:29], v[156:159], v[212:215], v[26:29]
	v_mfma_f32_16x16x32_bf16 v[14:17], v[142:145], v[220:223], v[14:17]
	v_mfma_f32_16x16x32_bf16 v[10:13], v[156:159], v[220:223], v[10:13]
	v_mfma_f32_16x16x32_bf16 v[62:65], v[146:149], v[194:197], v[62:65]
	v_mfma_f32_16x16x32_bf16 v[58:61], v[160:163], v[194:197], v[58:61]
	v_mfma_f32_16x16x32_bf16 v[46:49], v[146:149], v[202:205], v[46:49]
	v_mfma_f32_16x16x32_bf16 v[42:45], v[160:163], v[202:205], v[42:45]
	v_mfma_f32_16x16x32_bf16 v[30:33], v[146:149], v[216:219], v[30:33]
	v_mfma_f32_16x16x32_bf16 v[26:29], v[160:163], v[216:219], v[26:29]
	v_mfma_f32_16x16x32_bf16 v[14:17], v[146:149], v[224:227], v[14:17]
	v_mfma_f32_16x16x32_bf16 v[10:13], v[160:163], v[224:227], v[10:13]
	s_nop 0
	s_nop 0
	v_mfma_f32_16x16x32_bf16 v[54:57], v[164:167], v[190:193], v[54:57]
	v_mfma_f32_16x16x32_bf16 v[50:53], v[172:175], v[190:193], v[50:53]
	v_mfma_f32_16x16x32_bf16 v[38:41], v[164:167], v[198:201], v[38:41]
	v_mfma_f32_16x16x32_bf16 v[34:37], v[172:175], v[198:201], v[34:37]
	v_mfma_f32_16x16x32_bf16 v[22:25], v[164:167], v[212:215], v[22:25]
	v_mfma_f32_16x16x32_bf16 v[18:21], v[172:175], v[212:215], v[18:21]
	v_mfma_f32_16x16x32_bf16 v[6:9], v[164:167], v[220:223], v[6:9]
	v_mfma_f32_16x16x32_bf16 v[2:5], v[172:175], v[220:223], v[2:5]
	v_mfma_f32_16x16x32_bf16 v[54:57], v[168:171], v[194:197], v[54:57]
	v_mfma_f32_16x16x32_bf16 v[50:53], v[182:185], v[194:197], v[50:53]
	v_mfma_f32_16x16x32_bf16 v[38:41], v[168:171], v[202:205], v[38:41]
	v_mfma_f32_16x16x32_bf16 v[34:37], v[182:185], v[202:205], v[34:37]
	v_mfma_f32_16x16x32_bf16 v[22:25], v[168:171], v[216:219], v[22:25]
	v_mfma_f32_16x16x32_bf16 v[18:21], v[182:185], v[216:219], v[18:21]
	v_mfma_f32_16x16x32_bf16 v[6:9], v[168:171], v[224:227], v[6:9]
	v_mfma_f32_16x16x32_bf16 v[2:5], v[182:185], v[224:227], v[2:5]
	s_nop 0
	s_barrier
; #define PG8_STAGE(bufoff, gbase, voff) do { _Pragma("unroll") for (int _i = 0; _i < 2; ++_i) \
;         __builtin_amdgcn_global_load_lds((const unsigned*)((const char*)(gbase) + (voff)[_i]), (LAS unsigned*)(lds + (bufoff) + ldsw + _i * 8192), 16, 0, 0); } while (0)
; #define PG8_LDA(dst, b, h) do { _Pragma("unroll") for (int m = 0; m < 4; ++m) _Pragma("unroll") for (int k = 0; k < 2; ++k) dst[m][k] = *(const LAS bf16x8*)(lds + PG8_SA(b, h) + aoff + m * 2048 + k * 1024); } while (0)
; #define PG8_LDB(dst, b, h) do { _Pragma("unroll") for (int n = 0; n < 2; ++n) _Pragma("unroll") for (int k = 0; k < 2; ++k) dst[n][k] = *(const LAS bf16x8*)(lds + PG8_SB(b, h) + boff + n * 2048 + k * 1024); } while (0)
; #define PG8_MMA(ai, bj, At, Bt) do { __builtin_amdgcn_s_setprio(1); _Pragma("unroll") for (int m = 0; m < 4; ++m) _Pragma("unroll") for (int n = 0; n < 2; ++n) _Pragma("unroll") for (int k = 0; k < 2; ++k) \
;         acc[ai][bj][m][n] = __builtin_amdgcn_mfma_f32_16x16x32_bf16(Bt[n][k], At[m][k], acc[ai][bj][m][n], 0, 0, 0); __builtin_amdgcn_s_setprio(0); } while (0)
; #define PG8_WAIT_V(n) asm volatile("s_waitcnt vmcnt(" #n ")" ::: "memory")
; #define PG8_WAIT_L(n) asm volatile("s_waitcnt lgkmcnt(" #n ")" ::: "memory")
; #define PG8_BAR __builtin_amdgcn_s_barrier()
; #define PG8_SCHED __builtin_amdgcn_sched_barrier(0)
; template <class Epi, class Sched>
; DI void gemm_phase(LAS unsigned char* lds, const int K, const Sched& S, const Epi& E) {
;     ...
;             PG8_LDB(B0, 1, 0); PG8_LDB(B1, 1, 1); PG8_SCHED; PG8_LDA(At, 1, 0); PG8_STAGE(PG8_SA(0, 1), a2 + hstep, voffA);
;             PG8_WAIT_V(8); PG8_WAIT_L(0); PG8_BAR; PG8_MMA(0, 0, At, B0); PG8_MMA(0, 1, At, B1); PG8_BAR; PG8_SCHED;
;             PG8_LDA(At, 1, 1); PG8_STAGE(PG8_SB(1, 0), b3, voffB); PG8_STAGE(PG8_SB(1, 1), b3 + hstep, voffB); PG8_STAGE(PG8_SA(1, 0), a3, voffA);
;             PG8_WAIT_V(8); PG8_WAIT_L(0); PG8_BAR; PG8_MMA(1, 0, At, B0); PG8_MMA(1, 1, At, B1); PG8_BAR; PG8_SCHED;
;         }
;         if (wr == 0) PG8_BAR;
	s_add_i32 s92, 0, 0x18000
	v_add_u32_e32 v1, s92, v154
	s_add_i32 s95, 0, 0x1c000
	ds_read_b128 v[142:145], v1
	ds_read_b128 v[146:149], v1 offset:1024
	ds_read_b128 v[156:159], v1 offset:2048
	ds_read_b128 v[160:163], v1 offset:3072
	v_add_u32_e32 v1, s95, v154
	ds_read_b128 v[164:167], v1
	ds_read_b128 v[168:171], v1 offset:1024
	ds_read_b128 v[172:175], v1 offset:2048
	ds_read_b128 v[182:185], v1 offset:3072
	s_mov_b32 m0, s76
	s_nop 0
	ds_read_b128 v[190:193], v155 offset:32768
	ds_read_b128 v[194:197], v155 offset:33792
	ds_read_b128 v[198:201], v155 offset:34816
	ds_read_b128 v[202:205], v155 offset:35840
	ds_read_b128 v[212:215], v155 offset:36864
	ds_read_b128 v[216:219], v155 offset:37888
	ds_read_b128 v[220:223], v155 offset:38912
	ds_read_b128 v[224:227], v155 offset:39936
	global_load_lds_dwordx4 v130, s[68:69]
	s_mov_b32 m0, s77
	s_nop 0
	global_load_lds_dwordx4 v134, s[68:69]
	s_add_u32 s68, s68, 0x40000
	s_addc_u32 s69, s69, 0
	s_mov_b32 m0, s78
	s_nop 0
	global_load_lds_dwordx4 v130, s[68:69]
	s_nop 0
	s_mov_b32 m0, s79
	s_nop 0
	global_load_lds_dwordx4 v134, s[68:69]
	s_waitcnt vmcnt(8)
	s_waitcnt lgkmcnt(0)
	s_barrier
	s_nop 0
	s_waitcnt lgkmcnt(0)
	v_mfma_f32_16x16x32_bf16 v[126:129], v[142:145], v[190:193], v[126:129]
	v_mfma_f32_16x16x32_bf16 v[122:125], v[156:159], v[190:193], v[122:125]
	v_mfma_f32_16x16x32_bf16 v[110:113], v[142:145], v[198:201], v[110:113]
	v_mfma_f32_16x16x32_bf16 v[106:109], v[156:159], v[198:201], v[106:109]
	v_mfma_f32_16x16x32_bf16 v[94:97], v[142:145], v[212:215], v[94:97]
	v_mfma_f32_16x16x32_bf16 v[90:93], v[156:159], v[212:215], v[90:93]
	v_mfma_f32_16x16x32_bf16 v[78:81], v[142:145], v[220:223], v[78:81]
	v_mfma_f32_16x16x32_bf16 v[74:77], v[156:159], v[220:223], v[74:77]
	v_mfma_f32_16x16x32_bf16 v[126:129], v[146:149], v[194:197], v[126:129]
	v_mfma_f32_16x16x32_bf16 v[122:125], v[160:163], v[194:197], v[122:125]
	v_mfma_f32_16x16x32_bf16 v[110:113], v[146:149], v[202:205], v[110:113]
	v_mfma_f32_16x16x32_bf16 v[106:109], v[160:163], v[202:205], v[106:109]
	v_mfma_f32_16x16x32_bf16 v[94:97], v[146:149], v[216:219], v[94:97]
	v_mfma_f32_16x16x32_bf16 v[90:93], v[160:163], v[216:219], v[90:93]
	v_mfma_f32_16x16x32_bf16 v[78:81], v[146:149], v[224:227], v[78:81]
	v_mfma_f32_16x16x32_bf16 v[74:77], v[160:163], v[224:227], v[74:77]
	s_nop 0
	s_nop 0
	v_mfma_f32_16x16x32_bf16 v[118:121], v[164:167], v[190:193], v[118:121]
	v_mfma_f32_16x16x32_bf16 v[114:117], v[172:175], v[190:193], v[114:117]
	v_mfma_f32_16x16x32_bf16 v[102:105], v[164:167], v[198:201], v[102:105]
	v_mfma_f32_16x16x32_bf16 v[98:101], v[172:175], v[198:201], v[98:101]
	v_mfma_f32_16x16x32_bf16 v[86:89], v[164:167], v[212:215], v[86:89]
	v_mfma_f32_16x16x32_bf16 v[82:85], v[172:175], v[212:215], v[82:85]
	v_mfma_f32_16x16x32_bf16 v[70:73], v[164:167], v[220:223], v[70:73]
	v_mfma_f32_16x16x32_bf16 v[66:69], v[172:175], v[220:223], v[66:69]
	v_mfma_f32_16x16x32_bf16 v[118:121], v[168:171], v[194:197], v[118:121]
	v_mfma_f32_16x16x32_bf16 v[114:117], v[182:185], v[194:197], v[114:117]
	v_mfma_f32_16x16x32_bf16 v[102:105], v[168:171], v[202:205], v[102:105]
	v_mfma_f32_16x16x32_bf16 v[98:101], v[182:185], v[202:205], v[98:101]
	v_mfma_f32_16x16x32_bf16 v[86:89], v[168:171], v[216:219], v[86:89]
	v_mfma_f32_16x16x32_bf16 v[82:85], v[182:185], v[216:219], v[82:85]
	v_mfma_f32_16x16x32_bf16 v[70:73], v[168:171], v[224:227], v[70:73]
	v_mfma_f32_16x16x32_bf16 v[66:69], v[182:185], v[224:227], v[66:69]
	s_nop 0
	s_barrier
	s_add_i32 s68, s92, s75
	s_add_u32 s66, s66, 0x80
	s_addc_u32 s67, s67, 0
	s_mov_b32 m0, s68
	ds_read_b128 v[190:193], v155 offset:49152
	ds_read_b128 v[194:197], v155 offset:50176
	ds_read_b128 v[198:201], v155 offset:51200
	ds_read_b128 v[202:205], v155 offset:52224
	ds_read_b128 v[212:215], v155 offset:53248
	ds_read_b128 v[216:219], v155 offset:54272
	ds_read_b128 v[220:223], v155 offset:55296
	ds_read_b128 v[224:227], v155 offset:56320
	global_load_lds_dwordx4 v132, s[66:67]
	s_add_i32 m0, s68, 0x2000
	s_nop 0
	s_nop 0
	s_nop 0
	s_add_i32 s68, s95, s75
	global_load_lds_dwordx4 v136, s[66:67]
	s_add_u32 s66, s66, 0x40000
	s_addc_u32 s67, s67, 0
	s_nop 0
	s_mov_b32 m0, s68
	s_nop 0
	global_load_lds_dwordx4 v132, s[66:67]
	s_nop 0
	s_add_i32 m0, s68, 0x2000
	s_nop 0
	global_load_lds_dwordx4 v136, s[66:67]
	s_nop 0
	s_mov_b32 m0, s83
	s_nop 0
	global_load_lds_dwordx4 v130, s[98:99]
	s_nop 0
	s_mov_b32 m0, s84
	s_nop 0
	global_load_lds_dwordx4 v134, s[98:99]
	s_waitcnt vmcnt(8)
	s_waitcnt lgkmcnt(0)
	s_barrier
	s_nop 0
	s_waitcnt lgkmcnt(0)
	v_mfma_f32_16x16x32_bf16 v[62:65], v[142:145], v[190:193], v[62:65]
	v_mfma_f32_16x16x32_bf16 v[58:61], v[156:159], v[190:193], v[58:61]
	v_mfma_f32_16x16x32_bf16 v[46:49], v[142:145], v[198:201], v[46:49]
	v_mfma_f32_16x16x32_bf16 v[42:45], v[156:159], v[198:201], v[42:45]
	v_mfma_f32_16x16x32_bf16 v[30:33], v[142:145], v[212:215], v[30:33]
	v_mfma_f32_16x16x32_bf16 v[26:29], v[156:159], v[212:215], v[26:29]
	v_mfma_f32_16x16x32_bf16 v[14:17], v[142:145], v[220:223], v[14:17]
	v_mfma_f32_16x16x32_bf16 v[10:13], v[156:159], v[220:223], v[10:13]
	v_mfma_f32_16x16x32_bf16 v[62:65], v[146:149], v[194:197], v[62:65]
	v_mfma_f32_16x16x32_bf16 v[58:61], v[160:163], v[194:197], v[58:61]
	v_mfma_f32_16x16x32_bf16 v[46:49], v[146:149], v[202:205], v[46:49]
	v_mfma_f32_16x16x32_bf16 v[42:45], v[160:163], v[202:205], v[42:45]
	v_mfma_f32_16x16x32_bf16 v[30:33], v[146:149], v[216:219], v[30:33]
	v_mfma_f32_16x16x32_bf16 v[26:29], v[160:163], v[216:219], v[26:29]
	v_mfma_f32_16x16x32_bf16 v[14:17], v[146:149], v[224:227], v[14:17]
	v_mfma_f32_16x16x32_bf16 v[10:13], v[160:163], v[224:227], v[10:13]
	s_nop 0
	s_nop 0
	v_mfma_f32_16x16x32_bf16 v[54:57], v[164:167], v[190:193], v[54:57]
	v_mfma_f32_16x16x32_bf16 v[50:53], v[172:175], v[190:193], v[50:53]
	v_mfma_f32_16x16x32_bf16 v[38:41], v[164:167], v[198:201], v[38:41]
	v_mfma_f32_16x16x32_bf16 v[34:37], v[172:175], v[198:201], v[34:37]
	v_mfma_f32_16x16x32_bf16 v[22:25], v[164:167], v[212:215], v[22:25]
	v_mfma_f32_16x16x32_bf16 v[18:21], v[172:175], v[212:215], v[18:21]
	v_mfma_f32_16x16x32_bf16 v[6:9], v[164:167], v[220:223], v[6:9]
	v_mfma_f32_16x16x32_bf16 v[2:5], v[172:175], v[220:223], v[2:5]
	v_mfma_f32_16x16x32_bf16 v[54:57], v[168:171], v[194:197], v[54:57]
	v_mfma_f32_16x16x32_bf16 v[50:53], v[182:185], v[194:197], v[50:53]
	v_mfma_f32_16x16x32_bf16 v[38:41], v[168:171], v[202:205], v[38:41]
	v_mfma_f32_16x16x32_bf16 v[34:37], v[182:185], v[202:205], v[34:37]
	v_mfma_f32_16x16x32_bf16 v[22:25], v[168:171], v[216:219], v[22:25]
	v_mfma_f32_16x16x32_bf16 v[18:21], v[182:185], v[216:219], v[18:21]
	v_mfma_f32_16x16x32_bf16 v[6:9], v[168:171], v[224:227], v[6:9]
	v_mfma_f32_16x16x32_bf16 v[2:5], v[182:185], v[224:227], v[2:5]
	s_nop 0
	s_barrier
	s_add_i32 s63, s63, 2
	s_add_u32 s55, s55, 0x100
	s_addc_u32 s57, s57, 0
	s_add_u32 s64, s64, 0x100
	s_addc_u32 s65, s65, 0
	s_cmp_gt_u32 s63, 13
	s_cbranch_scc0 .LBB0_648
	s_and_b64 vcc, exec, s[46:47]
	s_cbranch_vccz .LBB0_651
	s_barrier

; #define PG8_STAGE(bufoff, gbase, voff) do { _Pragma("unroll") for (int _i = 0; _i < 2; ++_i) \
;         __builtin_amdgcn_global_load_lds((const unsigned*)((const char*)(gbase) + (voff)[_i]), (LAS unsigned*)(lds + (bufoff) + ldsw + _i * 8192), 16, 0, 0); } while (0)
; #define PG8_LDA(dst, b, h) do { _Pragma("unroll") for (int m = 0; m < 4; ++m) _Pragma("unroll") for (int k = 0; k < 2; ++k) dst[m][k] = *(const LAS bf16x8*)(lds + PG8_SA(b, h) + aoff + m * 2048 + k * 1024); } while (0)
; #define PG8_LDB(dst, b, h) do { _Pragma("unroll") for (int n = 0; n < 2; ++n) _Pragma("unroll") for (int k = 0; k < 2; ++k) dst[n][k] = *(const LAS bf16x8*)(lds + PG8_SB(b, h) + boff + n * 2048 + k * 1024); } while (0)
; #define PG8_MMA(ai, bj, At, Bt) do { __builtin_amdgcn_s_setprio(1); _Pragma("unroll") for (int m = 0; m < 4; ++m) _Pragma("unroll") for (int n = 0; n < 2; ++n) _Pragma("unroll") for (int k = 0; k < 2; ++k) \
;         acc[ai][bj][m][n] = __builtin_amdgcn_mfma_f32_16x16x32_bf16(Bt[n][k], At[m][k], acc[ai][bj][m][n], 0, 0, 0); __builtin_amdgcn_s_setprio(0); } while (0)
; #define PG8_WAIT_V(n) asm volatile("s_waitcnt vmcnt(" #n ")" ::: "memory")
; #define PG8_WAIT_L(n) asm volatile("s_waitcnt lgkmcnt(" #n ")" ::: "memory")
; #define PG8_BAR __builtin_amdgcn_s_barrier()
; #define PG8_SCHED __builtin_amdgcn_sched_barrier(0)
; template <class Epi, class Sched>
; DI void gemm_phase(LAS unsigned char* lds, const int K, const Sched& S, const Epi& E) {
;     ...
;             const char* a1 = cA + (size_t)(t + 1) * kstep;
;             const char* a2 = last ? nA : cA + (size_t)(t + 2) * kstep; const char* b2 = last ? nB : cB + (size_t)(t + 2) * kstep;
;             const char* a3 = a2 + kstep; const char* b3 = b2 + kstep;
;             PG8_LDB(B0, 0, 0); PG8_LDB(B1, 0, 1); PG8_SCHED; PG8_LDA(At, 0, 0); PG8_STAGE(PG8_SA(1, 1), a1 + hstep, voffA);
;             PG8_WAIT_V(8); PG8_WAIT_L(0); PG8_BAR; PG8_MMA(0, 0, At, B0); PG8_MMA(0, 1, At, B1); PG8_BAR; PG8_SCHED;
;             PG8_LDA(At, 0, 1); PG8_STAGE(PG8_SB(0, 0), b2, voffB); PG8_STAGE(PG8_SB(0, 1), b2 + hstep, voffB); PG8_STAGE(PG8_SA(0, 0), a2, voffA);
;             PG8_WAIT_V(8); PG8_WAIT_L(0); PG8_BAR; PG8_MMA(1, 0, At, B0); PG8_MMA(1, 1, At, B1); PG8_BAR; PG8_SCHED;
.LBB0_784:
	s_add_u32 s48, s44, 0xfffc0080
	s_addc_u32 s49, s45, -1
	s_add_i32 s77, 0, 0x10000
	s_cmp_eq_u32 s76, 12
	s_cselect_b32 s75, s69, s49
	s_cselect_b32 s74, s68, s48
	s_cselect_b32 s73, s71, s67
	s_cselect_b32 s72, s70, s65
	s_add_i32 s48, 0, 0x14000
	v_add_u32_e32 v142, s77, v199
	v_add_u32_e32 v158, s48, v199
	ds_read_b128 v[130:133], v142
	ds_read_b128 v[134:137], v142 offset:1024
	ds_read_b128 v[138:141], v142 offset:2048
	ds_read_b128 v[142:145], v142 offset:3072
	ds_read_b128 v[146:149], v158
	ds_read_b128 v[150:153], v158 offset:1024
	ds_read_b128 v[154:157], v158 offset:2048
	ds_read_b128 v[158:161], v158 offset:3072
	s_nop 0
	s_add_i32 m0, s80, 0xc000
	ds_read_b128 v[174:177], v200
	ds_read_b128 v[182:185], v200 offset:1024
	ds_read_b128 v[190:193], v200 offset:2048
	ds_read_b128 v[194:197], v200 offset:3072
	ds_read_b128 v[202:205], v200 offset:4096
	ds_read_b128 v[212:215], v200 offset:5120
	ds_read_b128 v[216:219], v200 offset:6144
	ds_read_b128 v[220:223], v200 offset:7168
	global_load_lds_dwordx4 v172, s[44:45]
	s_nop 0
	s_add_i32 m0, s80, 0xe000
	s_nop 0
	global_load_lds_dwordx4 v170, s[44:45]
	s_waitcnt vmcnt(8)
	s_waitcnt lgkmcnt(0)
	s_barrier
	s_nop 0
	s_waitcnt lgkmcnt(0)
	v_mfma_f32_16x16x32_bf16 v[126:129], v[130:133], v[174:177], v[126:129]
	v_mfma_f32_16x16x32_bf16 v[122:125], v[138:141], v[174:177], v[122:125]
	v_mfma_f32_16x16x32_bf16 v[118:121], v[130:133], v[190:193], v[118:121]
	v_mfma_f32_16x16x32_bf16 v[114:117], v[138:141], v[190:193], v[114:117]
	v_mfma_f32_16x16x32_bf16 v[110:113], v[130:133], v[202:205], v[110:113]
	v_mfma_f32_16x16x32_bf16 v[106:109], v[138:141], v[202:205], v[106:109]
	v_mfma_f32_16x16x32_bf16 v[102:105], v[130:133], v[216:219], v[102:105]
	v_mfma_f32_16x16x32_bf16 v[98:101], v[138:141], v[216:219], v[98:101]
	v_mfma_f32_16x16x32_bf16 v[126:129], v[134:137], v[182:185], v[126:129]
	v_mfma_f32_16x16x32_bf16 v[122:125], v[142:145], v[182:185], v[122:125]
	v_mfma_f32_16x16x32_bf16 v[118:121], v[134:137], v[194:197], v[118:121]
	v_mfma_f32_16x16x32_bf16 v[114:117], v[142:145], v[194:197], v[114:117]
	v_mfma_f32_16x16x32_bf16 v[110:113], v[134:137], v[212:215], v[110:113]
	v_mfma_f32_16x16x32_bf16 v[106:109], v[142:145], v[212:215], v[106:109]
	v_mfma_f32_16x16x32_bf16 v[102:105], v[134:137], v[220:223], v[102:105]
	v_mfma_f32_16x16x32_bf16 v[98:101], v[142:145], v[220:223], v[98:101]
	s_nop 0
	s_nop 0
	v_mfma_f32_16x16x32_bf16 v[94:97], v[146:149], v[174:177], v[94:97]
	v_mfma_f32_16x16x32_bf16 v[90:93], v[154:157], v[174:177], v[90:93]
	v_mfma_f32_16x16x32_bf16 v[86:89], v[146:149], v[190:193], v[86:89]
	v_mfma_f32_16x16x32_bf16 v[82:85], v[154:157], v[190:193], v[82:85]
	v_mfma_f32_16x16x32_bf16 v[78:81], v[146:149], v[202:205], v[78:81]
	v_mfma_f32_16x16x32_bf16 v[74:77], v[154:157], v[202:205], v[74:77]
	v_mfma_f32_16x16x32_bf16 v[70:73], v[146:149], v[216:219], v[70:73]
	v_mfma_f32_16x16x32_bf16 v[66:69], v[154:157], v[216:219], v[66:69]
	v_mfma_f32_16x16x32_bf16 v[94:97], v[150:153], v[182:185], v[94:97]
	v_mfma_f32_16x16x32_bf16 v[90:93], v[158:161], v[182:185], v[90:93]
	v_mfma_f32_16x16x32_bf16 v[86:89], v[150:153], v[194:197], v[86:89]
	v_mfma_f32_16x16x32_bf16 v[82:85], v[158:161], v[194:197], v[82:85]
	v_mfma_f32_16x16x32_bf16 v[78:81], v[150:153], v[212:215], v[78:81]
	v_mfma_f32_16x16x32_bf16 v[74:77], v[158:161], v[212:215], v[74:77]
	v_mfma_f32_16x16x32_bf16 v[70:73], v[150:153], v[220:223], v[70:73]
	v_mfma_f32_16x16x32_bf16 v[66:69], v[158:161], v[220:223], v[66:69]
	s_nop 0
	s_barrier
	s_add_i32 s49, s77, s79
	s_nop 0
	s_mov_b32 m0, s49
	ds_read_b128 v[174:177], v200 offset:16384
	ds_read_b128 v[182:185], v200 offset:17408
	ds_read_b128 v[190:193], v200 offset:18432
	ds_read_b128 v[194:197], v200 offset:19456
	ds_read_b128 v[202:205], v200 offset:20480
	ds_read_b128 v[212:215], v200 offset:21504
	ds_read_b128 v[216:219], v200 offset:22528
	ds_read_b128 v[220:223], v200 offset:23552
	global_load_lds_dwordx4 v164, s[72:73]
	s_add_i32 m0, s49, 0x2000
	s_add_u32 vcc_lo, s72, 0x40000
	s_nop 0
	s_addc_u32 vcc_hi, s73, 0
	s_add_i32 s48, s48, s79
	global_load_lds_dwordx4 v168, s[72:73]
	s_nop 0
	s_mov_b32 m0, s48
	s_nop 0
	global_load_lds_dwordx4 v164, vcc
	s_nop 0
	s_add_i32 m0, s48, 0x2000
	s_nop 0
	global_load_lds_dwordx4 v168, vcc
	s_nop 0
	s_add_u32 s98, s74, s90
	s_addc_u32 s99, s75, s91
	s_waitcnt vmcnt(6)
	s_waitcnt lgkmcnt(0)
	s_barrier
	s_nop 0
	s_waitcnt lgkmcnt(0)
	v_mfma_f32_16x16x32_bf16 v[62:65], v[130:133], v[174:177], v[62:65]
	v_mfma_f32_16x16x32_bf16 v[58:61], v[138:141], v[174:177], v[58:61]
	v_mfma_f32_16x16x32_bf16 v[54:57], v[130:133], v[190:193], v[54:57]
	v_mfma_f32_16x16x32_bf16 v[50:53], v[138:141], v[190:193], v[50:53]
	v_mfma_f32_16x16x32_bf16 v[46:49], v[130:133], v[202:205], v[46:49]
	v_mfma_f32_16x16x32_bf16 v[42:45], v[138:141], v[202:205], v[42:45]
	v_mfma_f32_16x16x32_bf16 v[38:41], v[130:133], v[216:219], v[38:41]
	v_mfma_f32_16x16x32_bf16 v[34:37], v[138:141], v[216:219], v[34:37]
	v_mfma_f32_16x16x32_bf16 v[62:65], v[134:137], v[182:185], v[62:65]
	v_mfma_f32_16x16x32_bf16 v[58:61], v[142:145], v[182:185], v[58:61]
	v_mfma_f32_16x16x32_bf16 v[54:57], v[134:137], v[194:197], v[54:57]
	v_mfma_f32_16x16x32_bf16 v[50:53], v[142:145], v[194:197], v[50:53]
	v_mfma_f32_16x16x32_bf16 v[46:49], v[134:137], v[212:215], v[46:49]
	v_mfma_f32_16x16x32_bf16 v[42:45], v[142:145], v[212:215], v[42:45]
	v_mfma_f32_16x16x32_bf16 v[38:41], v[134:137], v[220:223], v[38:41]
	v_mfma_f32_16x16x32_bf16 v[34:37], v[142:145], v[220:223], v[34:37]
	s_nop 0
	s_nop 0
	v_mfma_f32_16x16x32_bf16 v[30:33], v[146:149], v[174:177], v[30:33]
	v_mfma_f32_16x16x32_bf16 v[26:29], v[154:157], v[174:177], v[26:29]
	v_mfma_f32_16x16x32_bf16 v[22:25], v[146:149], v[190:193], v[22:25]
	v_mfma_f32_16x16x32_bf16 v[18:21], v[154:157], v[190:193], v[18:21]
	v_mfma_f32_16x16x32_bf16 v[14:17], v[146:149], v[202:205], v[14:17]
	v_mfma_f32_16x16x32_bf16 v[10:13], v[154:157], v[202:205], v[10:13]
	v_mfma_f32_16x16x32_bf16 v[6:9], v[146:149], v[216:219], v[6:9]
	v_mfma_f32_16x16x32_bf16 v[2:5], v[154:157], v[216:219], v[2:5]
	v_mfma_f32_16x16x32_bf16 v[30:33], v[150:153], v[182:185], v[30:33]
	v_mfma_f32_16x16x32_bf16 v[26:29], v[158:161], v[182:185], v[26:29]
	v_mfma_f32_16x16x32_bf16 v[22:25], v[150:153], v[194:197], v[22:25]
	v_mfma_f32_16x16x32_bf16 v[18:21], v[158:161], v[194:197], v[18:21]
	v_mfma_f32_16x16x32_bf16 v[14:17], v[150:153], v[212:215], v[14:17]
	v_mfma_f32_16x16x32_bf16 v[10:13], v[158:161], v[212:215], v[10:13]
	v_mfma_f32_16x16x32_bf16 v[6:9], v[150:153], v[220:223], v[6:9]
	v_mfma_f32_16x16x32_bf16 v[2:5], v[158:161], v[220:223], v[2:5]
	s_nop 0
	s_barrier
; #define PG8_STAGE(bufoff, gbase, voff) do { _Pragma("unroll") for (int _i = 0; _i < 2; ++_i) \
;         __builtin_amdgcn_global_load_lds((const unsigned*)((const char*)(gbase) + (voff)[_i]), (LAS unsigned*)(lds + (bufoff) + ldsw + _i * 8192), 16, 0, 0); } while (0)
; #define PG8_LDA(dst, b, h) do { _Pragma("unroll") for (int m = 0; m < 4; ++m) _Pragma("unroll") for (int k = 0; k < 2; ++k) dst[m][k] = *(const LAS bf16x8*)(lds + PG8_SA(b, h) + aoff + m * 2048 + k * 1024); } while (0)
; #define PG8_LDB(dst, b, h) do { _Pragma("unroll") for (int n = 0; n < 2; ++n) _Pragma("unroll") for (int k = 0; k < 2; ++k) dst[n][k] = *(const LAS bf16x8*)(lds + PG8_SB(b, h) + boff + n * 2048 + k * 1024); } while (0)
; #define PG8_MMA(ai, bj, At, Bt) do { __builtin_amdgcn_s_setprio(1); _Pragma("unroll") for (int m = 0; m < 4; ++m) _Pragma("unroll") for (int n = 0; n < 2; ++n) _Pragma("unroll") for (int k = 0; k < 2; ++k) \
;         acc[ai][bj][m][n] = __builtin_amdgcn_mfma_f32_16x16x32_bf16(Bt[n][k], At[m][k], acc[ai][bj][m][n], 0, 0, 0); __builtin_amdgcn_s_setprio(0); } while (0)
; #define PG8_WAIT_V(n) asm volatile("s_waitcnt vmcnt(" #n ")" ::: "memory")
; #define PG8_WAIT_L(n) asm volatile("s_waitcnt lgkmcnt(" #n ")" ::: "memory")
; #define PG8_BAR __builtin_amdgcn_s_barrier()
; #define PG8_SCHED __builtin_amdgcn_sched_barrier(0)
; template <class Epi, class Sched>
; DI void gemm_phase(LAS unsigned char* lds, const int K, const Sched& S, const Epi& E) {
;     ...
;             PG8_LDB(B0, 1, 0); PG8_LDB(B1, 1, 1); PG8_SCHED; PG8_LDA(At, 1, 0); PG8_STAGE(PG8_SA(0, 1), a2 + hstep, voffA);
;             PG8_WAIT_V(8); PG8_WAIT_L(0); PG8_BAR; PG8_MMA(0, 0, At, B0); PG8_MMA(0, 1, At, B1); PG8_BAR; PG8_SCHED;
;             PG8_LDA(At, 1, 1); PG8_STAGE(PG8_SB(1, 0), b3, voffB); PG8_STAGE(PG8_SB(1, 1), b3 + hstep, voffB); PG8_STAGE(PG8_SA(1, 0), a3, voffA);
;             PG8_WAIT_V(8); PG8_WAIT_L(0); PG8_BAR; PG8_MMA(1, 0, At, B0); PG8_MMA(1, 1, At, B1); PG8_BAR; PG8_SCHED;
;         }
;         if (wr == 0) PG8_BAR;
	s_add_i32 s48, 0, 0x18000
	s_add_i32 s49, 0, 0x1c000
	v_add_u32_e32 v142, s48, v199
	v_add_u32_e32 v158, s49, v199
	ds_read_b128 v[130:133], v142
	ds_read_b128 v[134:137], v142 offset:1024
	ds_read_b128 v[138:141], v142 offset:2048
	ds_read_b128 v[142:145], v142 offset:3072
	ds_read_b128 v[146:149], v158
	ds_read_b128 v[150:153], v158 offset:1024
	ds_read_b128 v[154:157], v158 offset:2048
	ds_read_b128 v[158:161], v158 offset:3072
	s_mov_b32 m0, s80
	s_nop 0
	ds_read_b128 v[174:177], v200 offset:32768
	ds_read_b128 v[182:185], v200 offset:33792
	ds_read_b128 v[190:193], v200 offset:34816
	ds_read_b128 v[194:197], v200 offset:35840
	ds_read_b128 v[202:205], v200 offset:36864
	ds_read_b128 v[212:215], v200 offset:37888
	ds_read_b128 v[216:219], v200 offset:38912
	ds_read_b128 v[220:223], v200 offset:39936
	global_load_lds_dwordx4 v162, s[74:75]
	s_mov_b32 m0, s81
	s_nop 0
	global_load_lds_dwordx4 v166, s[74:75]
	s_add_u32 s74, s74, 0x40000
	s_addc_u32 s75, s75, 0
	s_mov_b32 m0, s85
	s_nop 0
	global_load_lds_dwordx4 v162, s[74:75]
	s_nop 0
	s_mov_b32 m0, s86
	s_nop 0
	global_load_lds_dwordx4 v166, s[74:75]
	s_waitcnt vmcnt(8)
	s_waitcnt lgkmcnt(0)
	s_barrier
	s_nop 0
	s_waitcnt lgkmcnt(0)
	v_mfma_f32_16x16x32_bf16 v[126:129], v[130:133], v[174:177], v[126:129]
	v_mfma_f32_16x16x32_bf16 v[122:125], v[138:141], v[174:177], v[122:125]
	v_mfma_f32_16x16x32_bf16 v[118:121], v[130:133], v[190:193], v[118:121]
	v_mfma_f32_16x16x32_bf16 v[114:117], v[138:141], v[190:193], v[114:117]
	v_mfma_f32_16x16x32_bf16 v[110:113], v[130:133], v[202:205], v[110:113]
	v_mfma_f32_16x16x32_bf16 v[106:109], v[138:141], v[202:205], v[106:109]
	v_mfma_f32_16x16x32_bf16 v[102:105], v[130:133], v[216:219], v[102:105]
	v_mfma_f32_16x16x32_bf16 v[98:101], v[138:141], v[216:219], v[98:101]
	v_mfma_f32_16x16x32_bf16 v[126:129], v[134:137], v[182:185], v[126:129]
	v_mfma_f32_16x16x32_bf16 v[122:125], v[142:145], v[182:185], v[122:125]
	v_mfma_f32_16x16x32_bf16 v[118:121], v[134:137], v[194:197], v[118:121]
	v_mfma_f32_16x16x32_bf16 v[114:117], v[142:145], v[194:197], v[114:117]
	v_mfma_f32_16x16x32_bf16 v[110:113], v[134:137], v[212:215], v[110:113]
	v_mfma_f32_16x16x32_bf16 v[106:109], v[142:145], v[212:215], v[106:109]
	v_mfma_f32_16x16x32_bf16 v[102:105], v[134:137], v[220:223], v[102:105]
	v_mfma_f32_16x16x32_bf16 v[98:101], v[142:145], v[220:223], v[98:101]
	s_nop 0
	s_nop 0
	v_mfma_f32_16x16x32_bf16 v[94:97], v[146:149], v[174:177], v[94:97]
	v_mfma_f32_16x16x32_bf16 v[90:93], v[154:157], v[174:177], v[90:93]
	v_mfma_f32_16x16x32_bf16 v[86:89], v[146:149], v[190:193], v[86:89]
	v_mfma_f32_16x16x32_bf16 v[82:85], v[154:157], v[190:193], v[82:85]
	v_mfma_f32_16x16x32_bf16 v[78:81], v[146:149], v[202:205], v[78:81]
	v_mfma_f32_16x16x32_bf16 v[74:77], v[154:157], v[202:205], v[74:77]
	v_mfma_f32_16x16x32_bf16 v[70:73], v[146:149], v[216:219], v[70:73]
	v_mfma_f32_16x16x32_bf16 v[66:69], v[154:157], v[216:219], v[66:69]
	v_mfma_f32_16x16x32_bf16 v[94:97], v[150:153], v[182:185], v[94:97]
	v_mfma_f32_16x16x32_bf16 v[90:93], v[158:161], v[182:185], v[90:93]
	v_mfma_f32_16x16x32_bf16 v[86:89], v[150:153], v[194:197], v[86:89]
	v_mfma_f32_16x16x32_bf16 v[82:85], v[158:161], v[194:197], v[82:85]
	v_mfma_f32_16x16x32_bf16 v[78:81], v[150:153], v[212:215], v[78:81]
	v_mfma_f32_16x16x32_bf16 v[74:77], v[158:161], v[212:215], v[74:77]
	v_mfma_f32_16x16x32_bf16 v[70:73], v[150:153], v[220:223], v[70:73]
	v_mfma_f32_16x16x32_bf16 v[66:69], v[158:161], v[220:223], v[66:69]
	s_nop 0
	s_barrier
	s_add_i32 s48, s48, s79
	s_add_u32 s72, s72, 0x80
	s_addc_u32 s73, s73, 0
	s_mov_b32 m0, s48
	ds_read_b128 v[174:177], v200 offset:49152
	ds_read_b128 v[182:185], v200 offset:50176
	ds_read_b128 v[190:193], v200 offset:51200
	ds_read_b128 v[194:197], v200 offset:52224
	ds_read_b128 v[202:205], v200 offset:53248
	ds_read_b128 v[212:215], v200 offset:54272
	ds_read_b128 v[216:219], v200 offset:55296
	ds_read_b128 v[220:223], v200 offset:56320
	global_load_lds_dwordx4 v164, s[72:73]
	s_add_i32 m0, s48, 0x2000
	s_nop 0
	s_nop 0
	s_nop 0
	s_add_i32 s48, s49, s79
	global_load_lds_dwordx4 v168, s[72:73]
	s_add_u32 s72, s72, 0x40000
	s_addc_u32 s73, s73, 0
	s_nop 0
	s_mov_b32 m0, s48
	s_nop 0
	global_load_lds_dwordx4 v164, s[72:73]
	s_nop 0
	s_add_i32 m0, s48, 0x2000
	s_nop 0
	global_load_lds_dwordx4 v168, s[72:73]
	s_nop 0
	s_mov_b32 m0, s94
	s_nop 0
	global_load_lds_dwordx4 v162, s[98:99]
	s_nop 0
	s_mov_b32 m0, s95
	s_nop 0
	global_load_lds_dwordx4 v166, s[98:99]
	s_waitcnt vmcnt(8)
	s_waitcnt lgkmcnt(0)
	s_barrier
	s_nop 0
	s_waitcnt lgkmcnt(0)
	v_mfma_f32_16x16x32_bf16 v[62:65], v[130:133], v[174:177], v[62:65]
	v_mfma_f32_16x16x32_bf16 v[58:61], v[138:141], v[174:177], v[58:61]
	v_mfma_f32_16x16x32_bf16 v[54:57], v[130:133], v[190:193], v[54:57]
	v_mfma_f32_16x16x32_bf16 v[50:53], v[138:141], v[190:193], v[50:53]
	v_mfma_f32_16x16x32_bf16 v[46:49], v[130:133], v[202:205], v[46:49]
	v_mfma_f32_16x16x32_bf16 v[42:45], v[138:141], v[202:205], v[42:45]
	v_mfma_f32_16x16x32_bf16 v[38:41], v[130:133], v[216:219], v[38:41]
	v_mfma_f32_16x16x32_bf16 v[34:37], v[138:141], v[216:219], v[34:37]
	v_mfma_f32_16x16x32_bf16 v[62:65], v[134:137], v[182:185], v[62:65]
	v_mfma_f32_16x16x32_bf16 v[58:61], v[142:145], v[182:185], v[58:61]
	v_mfma_f32_16x16x32_bf16 v[54:57], v[134:137], v[194:197], v[54:57]
	v_mfma_f32_16x16x32_bf16 v[50:53], v[142:145], v[194:197], v[50:53]
	v_mfma_f32_16x16x32_bf16 v[46:49], v[134:137], v[212:215], v[46:49]
	v_mfma_f32_16x16x32_bf16 v[42:45], v[142:145], v[212:215], v[42:45]
	v_mfma_f32_16x16x32_bf16 v[38:41], v[134:137], v[220:223], v[38:41]
	v_mfma_f32_16x16x32_bf16 v[34:37], v[142:145], v[220:223], v[34:37]
	s_nop 0
	s_nop 0
	v_mfma_f32_16x16x32_bf16 v[30:33], v[146:149], v[174:177], v[30:33]
	v_mfma_f32_16x16x32_bf16 v[26:29], v[154:157], v[174:177], v[26:29]
	v_mfma_f32_16x16x32_bf16 v[22:25], v[146:149], v[190:193], v[22:25]
	v_mfma_f32_16x16x32_bf16 v[18:21], v[154:157], v[190:193], v[18:21]
	v_mfma_f32_16x16x32_bf16 v[14:17], v[146:149], v[202:205], v[14:17]
	v_mfma_f32_16x16x32_bf16 v[10:13], v[154:157], v[202:205], v[10:13]
	v_mfma_f32_16x16x32_bf16 v[6:9], v[146:149], v[216:219], v[6:9]
	v_mfma_f32_16x16x32_bf16 v[2:5], v[154:157], v[216:219], v[2:5]
	v_mfma_f32_16x16x32_bf16 v[30:33], v[150:153], v[182:185], v[30:33]
	v_mfma_f32_16x16x32_bf16 v[26:29], v[158:161], v[182:185], v[26:29]
	v_mfma_f32_16x16x32_bf16 v[22:25], v[150:153], v[194:197], v[22:25]
	v_mfma_f32_16x16x32_bf16 v[18:21], v[158:161], v[194:197], v[18:21]
	v_mfma_f32_16x16x32_bf16 v[14:17], v[150:153], v[212:215], v[14:17]
	v_mfma_f32_16x16x32_bf16 v[10:13], v[158:161], v[212:215], v[10:13]
	v_mfma_f32_16x16x32_bf16 v[6:9], v[150:153], v[220:223], v[6:9]
	v_mfma_f32_16x16x32_bf16 v[2:5], v[158:161], v[220:223], v[2:5]
	s_nop 0
	s_barrier
	s_add_i32 s76, s76, 2
	s_add_u32 s65, s65, 0x100
	s_addc_u32 s67, s67, 0
	s_add_u32 s44, s44, 0x100
	s_addc_u32 s45, s45, 0
	s_cmp_gt_u32 s76, 13
	s_cbranch_scc0 .LBB0_784
	s_and_b64 vcc, exec, s[58:59]
	s_cbranch_vccz .LBB0_787
	s_barrier

; #define PG8_STAGE(bufoff, gbase, voff) do { _Pragma("unroll") for (int _i = 0; _i < 2; ++_i) \
;         __builtin_amdgcn_global_load_lds((const unsigned*)((const char*)(gbase) + (voff)[_i]), (LAS unsigned*)(lds + (bufoff) + ldsw + _i * 8192), 16, 0, 0); } while (0)
; #define PG8_LDA(dst, b, h) do { _Pragma("unroll") for (int m = 0; m < 4; ++m) _Pragma("unroll") for (int k = 0; k < 2; ++k) dst[m][k] = *(const LAS bf16x8*)(lds + PG8_SA(b, h) + aoff + m * 2048 + k * 1024); } while (0)
; #define PG8_LDB(dst, b, h) do { _Pragma("unroll") for (int n = 0; n < 2; ++n) _Pragma("unroll") for (int k = 0; k < 2; ++k) dst[n][k] = *(const LAS bf16x8*)(lds + PG8_SB(b, h) + boff + n * 2048 + k * 1024); } while (0)
; #define PG8_MMA(ai, bj, At, Bt) do { __builtin_amdgcn_s_setprio(1); _Pragma("unroll") for (int m = 0; m < 4; ++m) _Pragma("unroll") for (int n = 0; n < 2; ++n) _Pragma("unroll") for (int k = 0; k < 2; ++k) \
;         acc[ai][bj][m][n] = __builtin_amdgcn_mfma_f32_16x16x32_bf16(Bt[n][k], At[m][k], acc[ai][bj][m][n], 0, 0, 0); __builtin_amdgcn_s_setprio(0); } while (0)
; #define PG8_WAIT_V(n) asm volatile("s_waitcnt vmcnt(" #n ")" ::: "memory")
; #define PG8_WAIT_L(n) asm volatile("s_waitcnt lgkmcnt(" #n ")" ::: "memory")
; #define PG8_BAR __builtin_amdgcn_s_barrier()
; #define PG8_SCHED __builtin_amdgcn_sched_barrier(0)
; template <class Epi, class Sched>
; DI void gemm_phase(LAS unsigned char* lds, const int K, const Sched& S, const Epi& E) {
;     ...
;             const char* a1 = cA + (size_t)(t + 1) * kstep;
;             const char* a2 = last ? nA : cA + (size_t)(t + 2) * kstep; const char* b2 = last ? nB : cB + (size_t)(t + 2) * kstep;
;             const char* a3 = a2 + kstep; const char* b3 = b2 + kstep;
;             PG8_LDB(B0, 0, 0); PG8_LDB(B1, 0, 1); PG8_SCHED; PG8_LDA(At, 0, 0); PG8_STAGE(PG8_SA(1, 1), a1 + hstep, voffA);
;             PG8_WAIT_V(8); PG8_WAIT_L(0); PG8_BAR; PG8_MMA(0, 0, At, B0); PG8_MMA(0, 1, At, B1); PG8_BAR; PG8_SCHED;
;             PG8_LDA(At, 0, 1); PG8_STAGE(PG8_SB(0, 0), b2, voffB); PG8_STAGE(PG8_SB(0, 1), b2 + hstep, voffB); PG8_STAGE(PG8_SA(0, 0), a2, voffA);
;             PG8_WAIT_V(8); PG8_WAIT_L(0); PG8_BAR; PG8_MMA(1, 0, At, B0); PG8_MMA(1, 1, At, B1); PG8_BAR; PG8_SCHED;
.LBB0_945:
	s_add_u32 s48, s62, 0xfffc0080
	s_addc_u32 s49, s63, -1
	s_add_i32 s84, 0, 0x10000
	s_cmp_eq_u32 s83, 12
	s_cselect_b32 s67, s59, s49
	s_cselect_b32 s66, s58, s48
	v_add_u32_e32 v145, s84, v143
	s_cselect_b32 s65, s61, s57
	s_cselect_b32 s64, s60, s55
	s_add_i32 s48, 0, 0x14000
	ds_read_b128 v[146:149], v145
	ds_read_b128 v[150:153], v145 offset:1024
	ds_read_b128 v[154:157], v145 offset:2048
	ds_read_b128 v[158:161], v145 offset:3072
	v_add_u32_e32 v145, s48, v143
	ds_read_b128 v[162:165], v145
	ds_read_b128 v[166:169], v145 offset:1024
	ds_read_b128 v[170:173], v145 offset:2048
	ds_read_b128 v[174:177], v145 offset:3072
	s_nop 0
	s_add_i32 m0, s53, 0xc000
	ds_read_b128 v[182:185], v144
	ds_read_b128 v[190:193], v144 offset:1024
	ds_read_b128 v[194:197], v144 offset:2048
	ds_read_b128 v[198:201], v144 offset:3072
	ds_read_b128 v[202:205], v144 offset:4096
	ds_read_b128 v[212:215], v144 offset:5120
	ds_read_b128 v[216:219], v144 offset:6144
	ds_read_b128 v[220:223], v144 offset:7168
	global_load_lds_dwordx4 v140, s[62:63]
	s_nop 0
	s_add_i32 m0, s53, 0xe000
	s_nop 0
	global_load_lds_dwordx4 v138, s[62:63]
	s_waitcnt vmcnt(8)
	s_waitcnt lgkmcnt(0)
	s_barrier
	s_nop 0
	s_waitcnt lgkmcnt(0)
	v_mfma_f32_16x16x32_bf16 v[126:129], v[146:149], v[182:185], v[126:129]
	v_mfma_f32_16x16x32_bf16 v[122:125], v[154:157], v[182:185], v[122:125]
	v_mfma_f32_16x16x32_bf16 v[118:121], v[146:149], v[194:197], v[118:121]
	v_mfma_f32_16x16x32_bf16 v[114:117], v[154:157], v[194:197], v[114:117]
	v_mfma_f32_16x16x32_bf16 v[102:105], v[146:149], v[202:205], v[102:105]
	v_mfma_f32_16x16x32_bf16 v[98:101], v[154:157], v[202:205], v[98:101]
	v_mfma_f32_16x16x32_bf16 v[86:89], v[146:149], v[216:219], v[86:89]
	v_mfma_f32_16x16x32_bf16 v[82:85], v[154:157], v[216:219], v[82:85]
	v_mfma_f32_16x16x32_bf16 v[126:129], v[150:153], v[190:193], v[126:129]
	v_mfma_f32_16x16x32_bf16 v[122:125], v[158:161], v[190:193], v[122:125]
	v_mfma_f32_16x16x32_bf16 v[118:121], v[150:153], v[198:201], v[118:121]
	v_mfma_f32_16x16x32_bf16 v[114:117], v[158:161], v[198:201], v[114:117]
	v_mfma_f32_16x16x32_bf16 v[102:105], v[150:153], v[212:215], v[102:105]
	v_mfma_f32_16x16x32_bf16 v[98:101], v[158:161], v[212:215], v[98:101]
	v_mfma_f32_16x16x32_bf16 v[86:89], v[150:153], v[220:223], v[86:89]
	v_mfma_f32_16x16x32_bf16 v[82:85], v[158:161], v[220:223], v[82:85]
	s_nop 0
	s_nop 0
	v_mfma_f32_16x16x32_bf16 v[110:113], v[162:165], v[182:185], v[110:113]
	v_mfma_f32_16x16x32_bf16 v[106:109], v[170:173], v[182:185], v[106:109]
	v_mfma_f32_16x16x32_bf16 v[94:97], v[162:165], v[194:197], v[94:97]
	v_mfma_f32_16x16x32_bf16 v[90:93], v[170:173], v[194:197], v[90:93]
	v_mfma_f32_16x16x32_bf16 v[78:81], v[162:165], v[202:205], v[78:81]
	v_mfma_f32_16x16x32_bf16 v[74:77], v[170:173], v[202:205], v[74:77]
	v_mfma_f32_16x16x32_bf16 v[70:73], v[162:165], v[216:219], v[70:73]
	v_mfma_f32_16x16x32_bf16 v[66:69], v[170:173], v[216:219], v[66:69]
	v_mfma_f32_16x16x32_bf16 v[110:113], v[166:169], v[190:193], v[110:113]
	v_mfma_f32_16x16x32_bf16 v[106:109], v[174:177], v[190:193], v[106:109]
	v_mfma_f32_16x16x32_bf16 v[94:97], v[166:169], v[198:201], v[94:97]
	v_mfma_f32_16x16x32_bf16 v[90:93], v[174:177], v[198:201], v[90:93]
	v_mfma_f32_16x16x32_bf16 v[78:81], v[166:169], v[212:215], v[78:81]
	v_mfma_f32_16x16x32_bf16 v[74:77], v[174:177], v[212:215], v[74:77]
	v_mfma_f32_16x16x32_bf16 v[70:73], v[166:169], v[220:223], v[70:73]
	v_mfma_f32_16x16x32_bf16 v[66:69], v[174:177], v[220:223], v[66:69]
	s_nop 0
	s_barrier
	s_add_i32 s49, s84, s71
	s_nop 0
	s_mov_b32 m0, s49
	ds_read_b128 v[182:185], v144 offset:16384
	ds_read_b128 v[190:193], v144 offset:17408
	ds_read_b128 v[194:197], v144 offset:18432
	ds_read_b128 v[198:201], v144 offset:19456
	ds_read_b128 v[202:205], v144 offset:20480
	ds_read_b128 v[212:215], v144 offset:21504
	ds_read_b128 v[216:219], v144 offset:22528
	ds_read_b128 v[220:223], v144 offset:23552
	global_load_lds_dwordx4 v134, s[64:65]
	s_add_i32 m0, s49, 0x2000
	s_add_u32 s84, s64, 0x40000
	s_nop 0
	s_addc_u32 s85, s65, 0
	s_add_i32 s48, s48, s71
	global_load_lds_dwordx4 v130, s[64:65]
	s_nop 0
	s_mov_b32 m0, s48
	s_nop 0
	global_load_lds_dwordx4 v134, s[84:85]
	s_nop 0
	s_add_i32 m0, s48, 0x2000
	s_nop 0
	global_load_lds_dwordx4 v130, s[84:85]
	s_nop 0
	s_add_u32 s98, s66, s90
	s_addc_u32 s99, s67, s91
	s_waitcnt vmcnt(6)
	s_waitcnt lgkmcnt(0)
	s_barrier
	s_nop 0
	s_waitcnt lgkmcnt(0)
	v_mfma_f32_16x16x32_bf16 v[62:65], v[146:149], v[182:185], v[62:65]
	v_mfma_f32_16x16x32_bf16 v[58:61], v[154:157], v[182:185], v[58:61]
	v_mfma_f32_16x16x32_bf16 v[54:57], v[146:149], v[194:197], v[54:57]
	v_mfma_f32_16x16x32_bf16 v[50:53], v[154:157], v[194:197], v[50:53]
	v_mfma_f32_16x16x32_bf16 v[38:41], v[146:149], v[202:205], v[38:41]
	v_mfma_f32_16x16x32_bf16 v[34:37], v[154:157], v[202:205], v[34:37]
	v_mfma_f32_16x16x32_bf16 v[22:25], v[146:149], v[216:219], v[22:25]
	v_mfma_f32_16x16x32_bf16 v[18:21], v[154:157], v[216:219], v[18:21]
	v_mfma_f32_16x16x32_bf16 v[62:65], v[150:153], v[190:193], v[62:65]
	v_mfma_f32_16x16x32_bf16 v[58:61], v[158:161], v[190:193], v[58:61]
	v_mfma_f32_16x16x32_bf16 v[54:57], v[150:153], v[198:201], v[54:57]
	v_mfma_f32_16x16x32_bf16 v[50:53], v[158:161], v[198:201], v[50:53]
	v_mfma_f32_16x16x32_bf16 v[38:41], v[150:153], v[212:215], v[38:41]
	v_mfma_f32_16x16x32_bf16 v[34:37], v[158:161], v[212:215], v[34:37]
	v_mfma_f32_16x16x32_bf16 v[22:25], v[150:153], v[220:223], v[22:25]
	v_mfma_f32_16x16x32_bf16 v[18:21], v[158:161], v[220:223], v[18:21]
	s_nop 0
	s_nop 0
	v_mfma_f32_16x16x32_bf16 v[46:49], v[162:165], v[182:185], v[46:49]
	v_mfma_f32_16x16x32_bf16 v[42:45], v[170:173], v[182:185], v[42:45]
	v_mfma_f32_16x16x32_bf16 v[30:33], v[162:165], v[194:197], v[30:33]
	v_mfma_f32_16x16x32_bf16 v[26:29], v[170:173], v[194:197], v[26:29]
	v_mfma_f32_16x16x32_bf16 v[14:17], v[162:165], v[202:205], v[14:17]
	v_mfma_f32_16x16x32_bf16 v[10:13], v[170:173], v[202:205], v[10:13]
	v_mfma_f32_16x16x32_bf16 v[6:9], v[162:165], v[216:219], v[6:9]
	v_mfma_f32_16x16x32_bf16 v[2:5], v[170:173], v[216:219], v[2:5]
	v_mfma_f32_16x16x32_bf16 v[46:49], v[166:169], v[190:193], v[46:49]
	v_mfma_f32_16x16x32_bf16 v[42:45], v[174:177], v[190:193], v[42:45]
	v_mfma_f32_16x16x32_bf16 v[30:33], v[166:169], v[198:201], v[30:33]
	v_mfma_f32_16x16x32_bf16 v[26:29], v[174:177], v[198:201], v[26:29]
	v_mfma_f32_16x16x32_bf16 v[14:17], v[166:169], v[212:215], v[14:17]
	v_mfma_f32_16x16x32_bf16 v[10:13], v[174:177], v[212:215], v[10:13]
	v_mfma_f32_16x16x32_bf16 v[6:9], v[166:169], v[220:223], v[6:9]
	v_mfma_f32_16x16x32_bf16 v[2:5], v[174:177], v[220:223], v[2:5]
	s_nop 0
	s_barrier
; #define PG8_STAGE(bufoff, gbase, voff) do { _Pragma("unroll") for (int _i = 0; _i < 2; ++_i) \
;         __builtin_amdgcn_global_load_lds((const unsigned*)((const char*)(gbase) + (voff)[_i]), (LAS unsigned*)(lds + (bufoff) + ldsw + _i * 8192), 16, 0, 0); } while (0)
; #define PG8_LDA(dst, b, h) do { _Pragma("unroll") for (int m = 0; m < 4; ++m) _Pragma("unroll") for (int k = 0; k < 2; ++k) dst[m][k] = *(const LAS bf16x8*)(lds + PG8_SA(b, h) + aoff + m * 2048 + k * 1024); } while (0)
; #define PG8_LDB(dst, b, h) do { _Pragma("unroll") for (int n = 0; n < 2; ++n) _Pragma("unroll") for (int k = 0; k < 2; ++k) dst[n][k] = *(const LAS bf16x8*)(lds + PG8_SB(b, h) + boff + n * 2048 + k * 1024); } while (0)
; #define PG8_MMA(ai, bj, At, Bt) do { __builtin_amdgcn_s_setprio(1); _Pragma("unroll") for (int m = 0; m < 4; ++m) _Pragma("unroll") for (int n = 0; n < 2; ++n) _Pragma("unroll") for (int k = 0; k < 2; ++k) \
;         acc[ai][bj][m][n] = __builtin_amdgcn_mfma_f32_16x16x32_bf16(Bt[n][k], At[m][k], acc[ai][bj][m][n], 0, 0, 0); __builtin_amdgcn_s_setprio(0); } while (0)
; #define PG8_WAIT_V(n) asm volatile("s_waitcnt vmcnt(" #n ")" ::: "memory")
; #define PG8_WAIT_L(n) asm volatile("s_waitcnt lgkmcnt(" #n ")" ::: "memory")
; #define PG8_BAR __builtin_amdgcn_s_barrier()
; #define PG8_SCHED __builtin_amdgcn_sched_barrier(0)
; template <class Epi, class Sched>
; DI void gemm_phase(LAS unsigned char* lds, const int K, const Sched& S, const Epi& E) {
;     ...
;             PG8_LDB(B0, 1, 0); PG8_LDB(B1, 1, 1); PG8_SCHED; PG8_LDA(At, 1, 0); PG8_STAGE(PG8_SA(0, 1), a2 + hstep, voffA);
;             PG8_WAIT_V(8); PG8_WAIT_L(0); PG8_BAR; PG8_MMA(0, 0, At, B0); PG8_MMA(0, 1, At, B1); PG8_BAR; PG8_SCHED;
;             PG8_LDA(At, 1, 1); PG8_STAGE(PG8_SB(1, 0), b3, voffB); PG8_STAGE(PG8_SB(1, 1), b3 + hstep, voffB); PG8_STAGE(PG8_SA(1, 0), a3, voffA);
;             PG8_WAIT_V(8); PG8_WAIT_L(0); PG8_BAR; PG8_MMA(1, 0, At, B0); PG8_MMA(1, 1, At, B1); PG8_BAR; PG8_SCHED;
;         }
;         if (wr == 0) PG8_BAR;
	s_add_i32 s48, 0, 0x18000
	v_add_u32_e32 v145, s48, v143
	s_add_i32 s49, 0, 0x1c000
	ds_read_b128 v[146:149], v145
	ds_read_b128 v[150:153], v145 offset:1024
	ds_read_b128 v[154:157], v145 offset:2048
	ds_read_b128 v[158:161], v145 offset:3072
	v_add_u32_e32 v145, s49, v143
	ds_read_b128 v[162:165], v145
	ds_read_b128 v[166:169], v145 offset:1024
	ds_read_b128 v[170:173], v145 offset:2048
	ds_read_b128 v[174:177], v145 offset:3072
	s_mov_b32 m0, s53
	s_nop 0
	ds_read_b128 v[182:185], v144 offset:32768
	ds_read_b128 v[190:193], v144 offset:33792
	ds_read_b128 v[194:197], v144 offset:34816
	ds_read_b128 v[198:201], v144 offset:35840
	ds_read_b128 v[202:205], v144 offset:36864
	ds_read_b128 v[212:215], v144 offset:37888
	ds_read_b128 v[216:219], v144 offset:38912
	ds_read_b128 v[220:223], v144 offset:39936
	global_load_lds_dwordx4 v136, s[66:67]
	s_mov_b32 m0, s73
	s_nop 0
	global_load_lds_dwordx4 v132, s[66:67]
	s_add_u32 s66, s66, 0x40000
	s_addc_u32 s67, s67, 0
	s_mov_b32 m0, s74
	s_nop 0
	global_load_lds_dwordx4 v136, s[66:67]
	s_nop 0
	s_mov_b32 m0, s75
	s_nop 0
	global_load_lds_dwordx4 v132, s[66:67]
	s_waitcnt vmcnt(8)
	s_waitcnt lgkmcnt(0)
	s_barrier
	s_nop 0
	s_waitcnt lgkmcnt(0)
	v_mfma_f32_16x16x32_bf16 v[126:129], v[146:149], v[182:185], v[126:129]
	v_mfma_f32_16x16x32_bf16 v[122:125], v[154:157], v[182:185], v[122:125]
	v_mfma_f32_16x16x32_bf16 v[118:121], v[146:149], v[194:197], v[118:121]
	v_mfma_f32_16x16x32_bf16 v[114:117], v[154:157], v[194:197], v[114:117]
	v_mfma_f32_16x16x32_bf16 v[102:105], v[146:149], v[202:205], v[102:105]
	v_mfma_f32_16x16x32_bf16 v[98:101], v[154:157], v[202:205], v[98:101]
	v_mfma_f32_16x16x32_bf16 v[86:89], v[146:149], v[216:219], v[86:89]
	v_mfma_f32_16x16x32_bf16 v[82:85], v[154:157], v[216:219], v[82:85]
	v_mfma_f32_16x16x32_bf16 v[126:129], v[150:153], v[190:193], v[126:129]
	v_mfma_f32_16x16x32_bf16 v[122:125], v[158:161], v[190:193], v[122:125]
	v_mfma_f32_16x16x32_bf16 v[118:121], v[150:153], v[198:201], v[118:121]
	v_mfma_f32_16x16x32_bf16 v[114:117], v[158:161], v[198:201], v[114:117]
	v_mfma_f32_16x16x32_bf16 v[102:105], v[150:153], v[212:215], v[102:105]
	v_mfma_f32_16x16x32_bf16 v[98:101], v[158:161], v[212:215], v[98:101]
	v_mfma_f32_16x16x32_bf16 v[86:89], v[150:153], v[220:223], v[86:89]
	v_mfma_f32_16x16x32_bf16 v[82:85], v[158:161], v[220:223], v[82:85]
	s_nop 0
	s_nop 0
	v_mfma_f32_16x16x32_bf16 v[110:113], v[162:165], v[182:185], v[110:113]
	v_mfma_f32_16x16x32_bf16 v[106:109], v[170:173], v[182:185], v[106:109]
	v_mfma_f32_16x16x32_bf16 v[94:97], v[162:165], v[194:197], v[94:97]
	v_mfma_f32_16x16x32_bf16 v[90:93], v[170:173], v[194:197], v[90:93]
	v_mfma_f32_16x16x32_bf16 v[78:81], v[162:165], v[202:205], v[78:81]
	v_mfma_f32_16x16x32_bf16 v[74:77], v[170:173], v[202:205], v[74:77]
	v_mfma_f32_16x16x32_bf16 v[70:73], v[162:165], v[216:219], v[70:73]
	v_mfma_f32_16x16x32_bf16 v[66:69], v[170:173], v[216:219], v[66:69]
	v_mfma_f32_16x16x32_bf16 v[110:113], v[166:169], v[190:193], v[110:113]
	v_mfma_f32_16x16x32_bf16 v[106:109], v[174:177], v[190:193], v[106:109]
	v_mfma_f32_16x16x32_bf16 v[94:97], v[166:169], v[198:201], v[94:97]
	v_mfma_f32_16x16x32_bf16 v[90:93], v[174:177], v[198:201], v[90:93]
	v_mfma_f32_16x16x32_bf16 v[78:81], v[166:169], v[212:215], v[78:81]
	v_mfma_f32_16x16x32_bf16 v[74:77], v[174:177], v[212:215], v[74:77]
	v_mfma_f32_16x16x32_bf16 v[70:73], v[166:169], v[220:223], v[70:73]
	v_mfma_f32_16x16x32_bf16 v[66:69], v[174:177], v[220:223], v[66:69]
	s_nop 0
	s_barrier
	s_add_i32 s48, s48, s71
	s_add_u32 s64, s64, 0x80
	s_addc_u32 s65, s65, 0
	s_mov_b32 m0, s48
	ds_read_b128 v[182:185], v144 offset:49152
	ds_read_b128 v[190:193], v144 offset:50176
	ds_read_b128 v[194:197], v144 offset:51200
	ds_read_b128 v[198:201], v144 offset:52224
	ds_read_b128 v[202:205], v144 offset:53248
	ds_read_b128 v[212:215], v144 offset:54272
	ds_read_b128 v[216:219], v144 offset:55296
	ds_read_b128 v[220:223], v144 offset:56320
	global_load_lds_dwordx4 v134, s[64:65]
	s_add_i32 m0, s48, 0x2000
	s_nop 0
	s_nop 0
	s_nop 0
	s_add_i32 s48, s49, s71
	global_load_lds_dwordx4 v130, s[64:65]
	s_add_u32 s64, s64, 0x40000
	s_addc_u32 s65, s65, 0
	s_nop 0
	s_mov_b32 m0, s48
	s_nop 0
	global_load_lds_dwordx4 v134, s[64:65]
	s_nop 0
	s_add_i32 m0, s48, 0x2000
	s_nop 0
	global_load_lds_dwordx4 v130, s[64:65]
	s_nop 0
	s_mov_b32 m0, s78
	s_nop 0
	global_load_lds_dwordx4 v136, s[98:99]
	s_nop 0
	s_mov_b32 m0, s79
	s_nop 0
	global_load_lds_dwordx4 v132, s[98:99]
	s_waitcnt vmcnt(8)
	s_waitcnt lgkmcnt(0)
	s_barrier
	s_nop 0
	s_waitcnt lgkmcnt(0)
	v_mfma_f32_16x16x32_bf16 v[62:65], v[146:149], v[182:185], v[62:65]
	v_mfma_f32_16x16x32_bf16 v[58:61], v[154:157], v[182:185], v[58:61]
	v_mfma_f32_16x16x32_bf16 v[54:57], v[146:149], v[194:197], v[54:57]
	v_mfma_f32_16x16x32_bf16 v[50:53], v[154:157], v[194:197], v[50:53]
	v_mfma_f32_16x16x32_bf16 v[38:41], v[146:149], v[202:205], v[38:41]
	v_mfma_f32_16x16x32_bf16 v[34:37], v[154:157], v[202:205], v[34:37]
	v_mfma_f32_16x16x32_bf16 v[22:25], v[146:149], v[216:219], v[22:25]
	v_mfma_f32_16x16x32_bf16 v[18:21], v[154:157], v[216:219], v[18:21]
	v_mfma_f32_16x16x32_bf16 v[62:65], v[150:153], v[190:193], v[62:65]
	v_mfma_f32_16x16x32_bf16 v[58:61], v[158:161], v[190:193], v[58:61]
	v_mfma_f32_16x16x32_bf16 v[54:57], v[150:153], v[198:201], v[54:57]
	v_mfma_f32_16x16x32_bf16 v[50:53], v[158:161], v[198:201], v[50:53]
	v_mfma_f32_16x16x32_bf16 v[38:41], v[150:153], v[212:215], v[38:41]
	v_mfma_f32_16x16x32_bf16 v[34:37], v[158:161], v[212:215], v[34:37]
	v_mfma_f32_16x16x32_bf16 v[22:25], v[150:153], v[220:223], v[22:25]
	v_mfma_f32_16x16x32_bf16 v[18:21], v[158:161], v[220:223], v[18:21]
	s_nop 0
	s_nop 0
	v_mfma_f32_16x16x32_bf16 v[46:49], v[162:165], v[182:185], v[46:49]
	v_mfma_f32_16x16x32_bf16 v[42:45], v[170:173], v[182:185], v[42:45]
	v_mfma_f32_16x16x32_bf16 v[30:33], v[162:165], v[194:197], v[30:33]
	v_mfma_f32_16x16x32_bf16 v[26:29], v[170:173], v[194:197], v[26:29]
	v_mfma_f32_16x16x32_bf16 v[14:17], v[162:165], v[202:205], v[14:17]
	v_mfma_f32_16x16x32_bf16 v[10:13], v[170:173], v[202:205], v[10:13]
	v_mfma_f32_16x16x32_bf16 v[6:9], v[162:165], v[216:219], v[6:9]
	v_mfma_f32_16x16x32_bf16 v[2:5], v[170:173], v[216:219], v[2:5]
	v_mfma_f32_16x16x32_bf16 v[46:49], v[166:169], v[190:193], v[46:49]
	v_mfma_f32_16x16x32_bf16 v[42:45], v[174:177], v[190:193], v[42:45]
	v_mfma_f32_16x16x32_bf16 v[30:33], v[166:169], v[198:201], v[30:33]
	v_mfma_f32_16x16x32_bf16 v[26:29], v[174:177], v[198:201], v[26:29]
	v_mfma_f32_16x16x32_bf16 v[14:17], v[166:169], v[212:215], v[14:17]
	v_mfma_f32_16x16x32_bf16 v[10:13], v[174:177], v[212:215], v[10:13]
	v_mfma_f32_16x16x32_bf16 v[6:9], v[166:169], v[220:223], v[6:9]
	v_mfma_f32_16x16x32_bf16 v[2:5], v[174:177], v[220:223], v[2:5]
	s_nop 0
	s_barrier
	s_add_i32 s83, s83, 2
	s_add_u32 s55, s55, 0x100
	s_addc_u32 s57, s57, 0
	s_add_u32 s62, s62, 0x100
	s_addc_u32 s63, s63, 0
	s_cmp_gt_u32 s83, 13
	s_cbranch_scc0 .LBB0_945
	s_and_b64 vcc, exec, s[50:51]
	s_cbranch_vccz .LBB0_948
	s_barrier

; #define PG8_STAGE(bufoff, gbase, voff) do { _Pragma("unroll") for (int _i = 0; _i < 2; ++_i) \
;         __builtin_amdgcn_global_load_lds((const unsigned*)((const char*)(gbase) + (voff)[_i]), (LAS unsigned*)(lds + (bufoff) + ldsw + _i * 8192), 16, 0, 0); } while (0)
; #define PG8_LDA(dst, b, h) do { _Pragma("unroll") for (int m = 0; m < 4; ++m) _Pragma("unroll") for (int k = 0; k < 2; ++k) dst[m][k] = *(const LAS bf16x8*)(lds + PG8_SA(b, h) + aoff + m * 2048 + k * 1024); } while (0)
; #define PG8_LDB(dst, b, h) do { _Pragma("unroll") for (int n = 0; n < 2; ++n) _Pragma("unroll") for (int k = 0; k < 2; ++k) dst[n][k] = *(const LAS bf16x8*)(lds + PG8_SB(b, h) + boff + n * 2048 + k * 1024); } while (0)
; #define PG8_MMA(ai, bj, At, Bt) do { __builtin_amdgcn_s_setprio(1); _Pragma("unroll") for (int m = 0; m < 4; ++m) _Pragma("unroll") for (int n = 0; n < 2; ++n) _Pragma("unroll") for (int k = 0; k < 2; ++k) \
;         acc[ai][bj][m][n] = __builtin_amdgcn_mfma_f32_16x16x32_bf16(Bt[n][k], At[m][k], acc[ai][bj][m][n], 0, 0, 0); __builtin_amdgcn_s_setprio(0); } while (0)
; #define PG8_WAIT_V(n) asm volatile("s_waitcnt vmcnt(" #n ")" ::: "memory")
; #define PG8_WAIT_L(n) asm volatile("s_waitcnt lgkmcnt(" #n ")" ::: "memory")
; #define PG8_BAR __builtin_amdgcn_s_barrier()
; #define PG8_SCHED __builtin_amdgcn_sched_barrier(0)
; template <class Epi, class Sched>
; DI void gemm_phase(LAS unsigned char* lds, const int K, const Sched& S, const Epi& E) {
;     ...
;             const char* a1 = cA + (size_t)(t + 1) * kstep;
;             const char* a2 = last ? nA : cA + (size_t)(t + 2) * kstep; const char* b2 = last ? nB : cB + (size_t)(t + 2) * kstep;
;             const char* a3 = a2 + kstep; const char* b3 = b2 + kstep;
;             PG8_LDB(B0, 0, 0); PG8_LDB(B1, 0, 1); PG8_SCHED; PG8_LDA(At, 0, 0); PG8_STAGE(PG8_SA(1, 1), a1 + hstep, voffA);
;             PG8_WAIT_V(8); PG8_WAIT_L(0); PG8_BAR; PG8_MMA(0, 0, At, B0); PG8_MMA(0, 1, At, B1); PG8_BAR; PG8_SCHED;
;             PG8_LDA(At, 0, 1); PG8_STAGE(PG8_SB(0, 0), b2, voffB); PG8_STAGE(PG8_SB(0, 1), b2 + hstep, voffB); PG8_STAGE(PG8_SA(0, 0), a2, voffA);
;             PG8_WAIT_V(8); PG8_WAIT_L(0); PG8_BAR; PG8_MMA(1, 0, At, B0); PG8_MMA(1, 1, At, B1); PG8_BAR; PG8_SCHED;
.LBB0_1086:
	s_add_u32 s48, s68, 0xfffc0080
	s_addc_u32 s49, s69, -1
	s_add_i32 vcc_hi, 0, 0x10000
	s_cmp_eq_u32 vcc_lo, 12
	s_cselect_b32 s73, s65, s49
	s_cselect_b32 s72, s64, s48
	v_add_u32_e32 v145, vcc_hi, v143
	s_cselect_b32 s71, s67, s63
	s_cselect_b32 s70, s66, s61
	s_add_i32 s94, 0, 0x14000
	ds_read_b128 v[146:149], v145
	ds_read_b128 v[150:153], v145 offset:1024
	ds_read_b128 v[154:157], v145 offset:2048
	ds_read_b128 v[158:161], v145 offset:3072
	v_add_u32_e32 v145, s94, v143
	ds_read_b128 v[162:165], v145
	ds_read_b128 v[166:169], v145 offset:1024
	ds_read_b128 v[170:173], v145 offset:2048
	ds_read_b128 v[174:177], v145 offset:3072
	s_nop 0
	s_add_i32 m0, s59, 0xc000
	ds_read_b128 v[182:185], v144
	ds_read_b128 v[190:193], v144 offset:1024
	ds_read_b128 v[194:197], v144 offset:2048
	ds_read_b128 v[198:201], v144 offset:3072
	ds_read_b128 v[202:205], v144 offset:4096
	ds_read_b128 v[212:215], v144 offset:5120
	ds_read_b128 v[216:219], v144 offset:6144
	ds_read_b128 v[220:223], v144 offset:7168
	global_load_lds_dwordx4 v140, s[68:69]
	s_nop 0
	s_add_i32 m0, s59, 0xe000
	s_nop 0
	global_load_lds_dwordx4 v138, s[68:69]
	s_waitcnt vmcnt(8)
	s_waitcnt lgkmcnt(0)
	s_barrier
	s_nop 0
	s_waitcnt lgkmcnt(0)
	v_mfma_f32_16x16x32_bf16 v[126:129], v[146:149], v[182:185], v[126:129]
	v_mfma_f32_16x16x32_bf16 v[122:125], v[154:157], v[182:185], v[122:125]
	v_mfma_f32_16x16x32_bf16 v[118:121], v[146:149], v[194:197], v[118:121]
	v_mfma_f32_16x16x32_bf16 v[114:117], v[154:157], v[194:197], v[114:117]
	v_mfma_f32_16x16x32_bf16 v[102:105], v[146:149], v[202:205], v[102:105]
	v_mfma_f32_16x16x32_bf16 v[98:101], v[154:157], v[202:205], v[98:101]
	v_mfma_f32_16x16x32_bf16 v[86:89], v[146:149], v[216:219], v[86:89]
	v_mfma_f32_16x16x32_bf16 v[82:85], v[154:157], v[216:219], v[82:85]
	v_mfma_f32_16x16x32_bf16 v[126:129], v[150:153], v[190:193], v[126:129]
	v_mfma_f32_16x16x32_bf16 v[122:125], v[158:161], v[190:193], v[122:125]
	v_mfma_f32_16x16x32_bf16 v[118:121], v[150:153], v[198:201], v[118:121]
	v_mfma_f32_16x16x32_bf16 v[114:117], v[158:161], v[198:201], v[114:117]
	v_mfma_f32_16x16x32_bf16 v[102:105], v[150:153], v[212:215], v[102:105]
	v_mfma_f32_16x16x32_bf16 v[98:101], v[158:161], v[212:215], v[98:101]
	v_mfma_f32_16x16x32_bf16 v[86:89], v[150:153], v[220:223], v[86:89]
	v_mfma_f32_16x16x32_bf16 v[82:85], v[158:161], v[220:223], v[82:85]
	s_nop 0
	s_nop 0
	v_mfma_f32_16x16x32_bf16 v[110:113], v[162:165], v[182:185], v[110:113]
	v_mfma_f32_16x16x32_bf16 v[106:109], v[170:173], v[182:185], v[106:109]
	v_mfma_f32_16x16x32_bf16 v[94:97], v[162:165], v[194:197], v[94:97]
	v_mfma_f32_16x16x32_bf16 v[90:93], v[170:173], v[194:197], v[90:93]
	v_mfma_f32_16x16x32_bf16 v[78:81], v[162:165], v[202:205], v[78:81]
	v_mfma_f32_16x16x32_bf16 v[74:77], v[170:173], v[202:205], v[74:77]
	v_mfma_f32_16x16x32_bf16 v[70:73], v[162:165], v[216:219], v[70:73]
	v_mfma_f32_16x16x32_bf16 v[66:69], v[170:173], v[216:219], v[66:69]
	v_mfma_f32_16x16x32_bf16 v[110:113], v[166:169], v[190:193], v[110:113]
	v_mfma_f32_16x16x32_bf16 v[106:109], v[174:177], v[190:193], v[106:109]
	v_mfma_f32_16x16x32_bf16 v[94:97], v[166:169], v[198:201], v[94:97]
	v_mfma_f32_16x16x32_bf16 v[90:93], v[174:177], v[198:201], v[90:93]
	v_mfma_f32_16x16x32_bf16 v[78:81], v[166:169], v[212:215], v[78:81]
	v_mfma_f32_16x16x32_bf16 v[74:77], v[174:177], v[212:215], v[74:77]
	v_mfma_f32_16x16x32_bf16 v[70:73], v[166:169], v[220:223], v[70:73]
	v_mfma_f32_16x16x32_bf16 v[66:69], v[174:177], v[220:223], v[66:69]
	s_nop 0
	s_barrier
	s_add_i32 s48, vcc_hi, s78
	s_nop 0
	s_mov_b32 m0, s48
	ds_read_b128 v[182:185], v144 offset:16384
	ds_read_b128 v[190:193], v144 offset:17408
	ds_read_b128 v[194:197], v144 offset:18432
	ds_read_b128 v[198:201], v144 offset:19456
	ds_read_b128 v[202:205], v144 offset:20480
	ds_read_b128 v[212:215], v144 offset:21504
	ds_read_b128 v[216:219], v144 offset:22528
	ds_read_b128 v[220:223], v144 offset:23552
	global_load_lds_dwordx4 v134, s[70:71]
	s_add_i32 m0, s48, 0x2000
	s_add_u32 s48, s70, 0x40000
	s_nop 0
	s_addc_u32 s49, s71, 0
	s_add_i32 s94, s94, s78
	global_load_lds_dwordx4 v130, s[70:71]
	s_nop 0
	s_mov_b32 m0, s94
	s_nop 0
	global_load_lds_dwordx4 v134, s[48:49]
	s_nop 0
	s_add_i32 m0, s94, 0x2000
	s_nop 0
	global_load_lds_dwordx4 v130, s[48:49]
	s_nop 0
	s_add_u32 s98, s72, s90
	s_addc_u32 s99, s73, s91
	s_waitcnt vmcnt(6)
	s_waitcnt lgkmcnt(0)
	s_barrier
	s_nop 0
	s_waitcnt lgkmcnt(0)
	v_mfma_f32_16x16x32_bf16 v[62:65], v[146:149], v[182:185], v[62:65]
	v_mfma_f32_16x16x32_bf16 v[58:61], v[154:157], v[182:185], v[58:61]
	v_mfma_f32_16x16x32_bf16 v[54:57], v[146:149], v[194:197], v[54:57]
	v_mfma_f32_16x16x32_bf16 v[50:53], v[154:157], v[194:197], v[50:53]
	v_mfma_f32_16x16x32_bf16 v[38:41], v[146:149], v[202:205], v[38:41]
	v_mfma_f32_16x16x32_bf16 v[34:37], v[154:157], v[202:205], v[34:37]
	v_mfma_f32_16x16x32_bf16 v[22:25], v[146:149], v[216:219], v[22:25]
	v_mfma_f32_16x16x32_bf16 v[18:21], v[154:157], v[216:219], v[18:21]
	v_mfma_f32_16x16x32_bf16 v[62:65], v[150:153], v[190:193], v[62:65]
	v_mfma_f32_16x16x32_bf16 v[58:61], v[158:161], v[190:193], v[58:61]
	v_mfma_f32_16x16x32_bf16 v[54:57], v[150:153], v[198:201], v[54:57]
	v_mfma_f32_16x16x32_bf16 v[50:53], v[158:161], v[198:201], v[50:53]
	v_mfma_f32_16x16x32_bf16 v[38:41], v[150:153], v[212:215], v[38:41]
	v_mfma_f32_16x16x32_bf16 v[34:37], v[158:161], v[212:215], v[34:37]
	v_mfma_f32_16x16x32_bf16 v[22:25], v[150:153], v[220:223], v[22:25]
	v_mfma_f32_16x16x32_bf16 v[18:21], v[158:161], v[220:223], v[18:21]
	s_nop 0
	s_nop 0
	v_mfma_f32_16x16x32_bf16 v[46:49], v[162:165], v[182:185], v[46:49]
	v_mfma_f32_16x16x32_bf16 v[42:45], v[170:173], v[182:185], v[42:45]
	v_mfma_f32_16x16x32_bf16 v[30:33], v[162:165], v[194:197], v[30:33]
	v_mfma_f32_16x16x32_bf16 v[26:29], v[170:173], v[194:197], v[26:29]
	v_mfma_f32_16x16x32_bf16 v[14:17], v[162:165], v[202:205], v[14:17]
	v_mfma_f32_16x16x32_bf16 v[10:13], v[170:173], v[202:205], v[10:13]
	v_mfma_f32_16x16x32_bf16 v[6:9], v[162:165], v[216:219], v[6:9]
	v_mfma_f32_16x16x32_bf16 v[2:5], v[170:173], v[216:219], v[2:5]
	v_mfma_f32_16x16x32_bf16 v[46:49], v[166:169], v[190:193], v[46:49]
	v_mfma_f32_16x16x32_bf16 v[42:45], v[174:177], v[190:193], v[42:45]
	v_mfma_f32_16x16x32_bf16 v[30:33], v[166:169], v[198:201], v[30:33]
	v_mfma_f32_16x16x32_bf16 v[26:29], v[174:177], v[198:201], v[26:29]
	v_mfma_f32_16x16x32_bf16 v[14:17], v[166:169], v[212:215], v[14:17]
	v_mfma_f32_16x16x32_bf16 v[10:13], v[174:177], v[212:215], v[10:13]
	v_mfma_f32_16x16x32_bf16 v[6:9], v[166:169], v[220:223], v[6:9]
	v_mfma_f32_16x16x32_bf16 v[2:5], v[174:177], v[220:223], v[2:5]
	s_nop 0
	s_barrier
; #define PG8_STAGE(bufoff, gbase, voff) do { _Pragma("unroll") for (int _i = 0; _i < 2; ++_i) \
;         __builtin_amdgcn_global_load_lds((const unsigned*)((const char*)(gbase) + (voff)[_i]), (LAS unsigned*)(lds + (bufoff) + ldsw + _i * 8192), 16, 0, 0); } while (0)
; #define PG8_LDA(dst, b, h) do { _Pragma("unroll") for (int m = 0; m < 4; ++m) _Pragma("unroll") for (int k = 0; k < 2; ++k) dst[m][k] = *(const LAS bf16x8*)(lds + PG8_SA(b, h) + aoff + m * 2048 + k * 1024); } while (0)
; #define PG8_LDB(dst, b, h) do { _Pragma("unroll") for (int n = 0; n < 2; ++n) _Pragma("unroll") for (int k = 0; k < 2; ++k) dst[n][k] = *(const LAS bf16x8*)(lds + PG8_SB(b, h) + boff + n * 2048 + k * 1024); } while (0)
; #define PG8_MMA(ai, bj, At, Bt) do { __builtin_amdgcn_s_setprio(1); _Pragma("unroll") for (int m = 0; m < 4; ++m) _Pragma("unroll") for (int n = 0; n < 2; ++n) _Pragma("unroll") for (int k = 0; k < 2; ++k) \
;         acc[ai][bj][m][n] = __builtin_amdgcn_mfma_f32_16x16x32_bf16(Bt[n][k], At[m][k], acc[ai][bj][m][n], 0, 0, 0); __builtin_amdgcn_s_setprio(0); } while (0)
; #define PG8_WAIT_V(n) asm volatile("s_waitcnt vmcnt(" #n ")" ::: "memory")
; #define PG8_WAIT_L(n) asm volatile("s_waitcnt lgkmcnt(" #n ")" ::: "memory")
; #define PG8_BAR __builtin_amdgcn_s_barrier()
; #define PG8_SCHED __builtin_amdgcn_sched_barrier(0)
; template <class Epi, class Sched>
; DI void gemm_phase(LAS unsigned char* lds, const int K, const Sched& S, const Epi& E) {
;     ...
;             PG8_LDB(B0, 1, 0); PG8_LDB(B1, 1, 1); PG8_SCHED; PG8_LDA(At, 1, 0); PG8_STAGE(PG8_SA(0, 1), a2 + hstep, voffA);
;             PG8_WAIT_V(8); PG8_WAIT_L(0); PG8_BAR; PG8_MMA(0, 0, At, B0); PG8_MMA(0, 1, At, B1); PG8_BAR; PG8_SCHED;
;             PG8_LDA(At, 1, 1); PG8_STAGE(PG8_SB(1, 0), b3, voffB); PG8_STAGE(PG8_SB(1, 1), b3 + hstep, voffB); PG8_STAGE(PG8_SA(1, 0), a3, voffA);
;             PG8_WAIT_V(8); PG8_WAIT_L(0); PG8_BAR; PG8_MMA(1, 0, At, B0); PG8_MMA(1, 1, At, B1); PG8_BAR; PG8_SCHED;
;         }
;         if (wr == 0) PG8_BAR;
	s_add_i32 s94, 0, 0x18000
	v_add_u32_e32 v145, s94, v143
	s_add_i32 vcc_hi, 0, 0x1c000
	ds_read_b128 v[146:149], v145
	ds_read_b128 v[150:153], v145 offset:1024
	ds_read_b128 v[154:157], v145 offset:2048
	ds_read_b128 v[158:161], v145 offset:3072
	v_add_u32_e32 v145, vcc_hi, v143
	ds_read_b128 v[162:165], v145
	ds_read_b128 v[166:169], v145 offset:1024
	ds_read_b128 v[170:173], v145 offset:2048
	ds_read_b128 v[174:177], v145 offset:3072
	s_mov_b32 m0, s59
	s_nop 0
	ds_read_b128 v[182:185], v144 offset:32768
	ds_read_b128 v[190:193], v144 offset:33792
	ds_read_b128 v[194:197], v144 offset:34816
	ds_read_b128 v[198:201], v144 offset:35840
	ds_read_b128 v[202:205], v144 offset:36864
	ds_read_b128 v[212:215], v144 offset:37888
	ds_read_b128 v[216:219], v144 offset:38912
	ds_read_b128 v[220:223], v144 offset:39936
	global_load_lds_dwordx4 v136, s[72:73]
	s_mov_b32 m0, s80
	s_nop 0
	global_load_lds_dwordx4 v132, s[72:73]
	s_add_u32 s48, s72, 0x40000
	s_addc_u32 s49, s73, 0
	s_mov_b32 m0, s81
	s_nop 0
	global_load_lds_dwordx4 v136, s[48:49]
	s_nop 0
	s_mov_b32 m0, s83
	s_nop 0
	global_load_lds_dwordx4 v132, s[48:49]
	s_waitcnt vmcnt(8)
	s_waitcnt lgkmcnt(0)
	s_barrier
	s_nop 0
	s_waitcnt lgkmcnt(0)
	v_mfma_f32_16x16x32_bf16 v[126:129], v[146:149], v[182:185], v[126:129]
	v_mfma_f32_16x16x32_bf16 v[122:125], v[154:157], v[182:185], v[122:125]
	v_mfma_f32_16x16x32_bf16 v[118:121], v[146:149], v[194:197], v[118:121]
	v_mfma_f32_16x16x32_bf16 v[114:117], v[154:157], v[194:197], v[114:117]
	v_mfma_f32_16x16x32_bf16 v[102:105], v[146:149], v[202:205], v[102:105]
	v_mfma_f32_16x16x32_bf16 v[98:101], v[154:157], v[202:205], v[98:101]
	v_mfma_f32_16x16x32_bf16 v[86:89], v[146:149], v[216:219], v[86:89]
	v_mfma_f32_16x16x32_bf16 v[82:85], v[154:157], v[216:219], v[82:85]
	v_mfma_f32_16x16x32_bf16 v[126:129], v[150:153], v[190:193], v[126:129]
	v_mfma_f32_16x16x32_bf16 v[122:125], v[158:161], v[190:193], v[122:125]
	v_mfma_f32_16x16x32_bf16 v[118:121], v[150:153], v[198:201], v[118:121]
	v_mfma_f32_16x16x32_bf16 v[114:117], v[158:161], v[198:201], v[114:117]
	v_mfma_f32_16x16x32_bf16 v[102:105], v[150:153], v[212:215], v[102:105]
	v_mfma_f32_16x16x32_bf16 v[98:101], v[158:161], v[212:215], v[98:101]
	v_mfma_f32_16x16x32_bf16 v[86:89], v[150:153], v[220:223], v[86:89]
	v_mfma_f32_16x16x32_bf16 v[82:85], v[158:161], v[220:223], v[82:85]
	s_nop 0
	s_nop 0
	v_mfma_f32_16x16x32_bf16 v[110:113], v[162:165], v[182:185], v[110:113]
	v_mfma_f32_16x16x32_bf16 v[106:109], v[170:173], v[182:185], v[106:109]
	v_mfma_f32_16x16x32_bf16 v[94:97], v[162:165], v[194:197], v[94:97]
	v_mfma_f32_16x16x32_bf16 v[90:93], v[170:173], v[194:197], v[90:93]
	v_mfma_f32_16x16x32_bf16 v[78:81], v[162:165], v[202:205], v[78:81]
	v_mfma_f32_16x16x32_bf16 v[74:77], v[170:173], v[202:205], v[74:77]
	v_mfma_f32_16x16x32_bf16 v[70:73], v[162:165], v[216:219], v[70:73]
	v_mfma_f32_16x16x32_bf16 v[66:69], v[170:173], v[216:219], v[66:69]
	v_mfma_f32_16x16x32_bf16 v[110:113], v[166:169], v[190:193], v[110:113]
	v_mfma_f32_16x16x32_bf16 v[106:109], v[174:177], v[190:193], v[106:109]
	v_mfma_f32_16x16x32_bf16 v[94:97], v[166:169], v[198:201], v[94:97]
	v_mfma_f32_16x16x32_bf16 v[90:93], v[174:177], v[198:201], v[90:93]
	v_mfma_f32_16x16x32_bf16 v[78:81], v[166:169], v[212:215], v[78:81]
	v_mfma_f32_16x16x32_bf16 v[74:77], v[174:177], v[212:215], v[74:77]
	v_mfma_f32_16x16x32_bf16 v[70:73], v[166:169], v[220:223], v[70:73]
	v_mfma_f32_16x16x32_bf16 v[66:69], v[174:177], v[220:223], v[66:69]
	s_nop 0
	s_barrier
	s_add_i32 s48, s94, s78
	s_add_u32 s70, s70, 0x80
	s_addc_u32 s71, s71, 0
	s_mov_b32 m0, s48
	ds_read_b128 v[182:185], v144 offset:49152
	ds_read_b128 v[190:193], v144 offset:50176
	ds_read_b128 v[194:197], v144 offset:51200
	ds_read_b128 v[198:201], v144 offset:52224
	ds_read_b128 v[202:205], v144 offset:53248
	ds_read_b128 v[212:215], v144 offset:54272
	ds_read_b128 v[216:219], v144 offset:55296
	ds_read_b128 v[220:223], v144 offset:56320
	global_load_lds_dwordx4 v134, s[70:71]
	s_add_i32 m0, s48, 0x2000
	s_add_u32 s48, s70, 0x40000
	s_nop 0
	s_addc_u32 s49, s71, 0
	global_load_lds_dwordx4 v130, s[70:71]
	s_add_i32 s70, vcc_hi, s78
	s_nop 0
	s_mov_b32 m0, s70
	s_nop 0
	global_load_lds_dwordx4 v134, s[48:49]
	s_nop 0
	s_add_i32 m0, s70, 0x2000
	s_nop 0
	global_load_lds_dwordx4 v130, s[48:49]
	s_nop 0
	s_mov_b32 m0, s95
	s_nop 0
	global_load_lds_dwordx4 v136, s[98:99]
	s_nop 0
	s_mov_b32 m0, s42
	s_nop 0
	global_load_lds_dwordx4 v132, s[98:99]
	s_waitcnt vmcnt(8)
	s_waitcnt lgkmcnt(0)
	s_barrier
	s_nop 0
	s_waitcnt lgkmcnt(0)
	v_mfma_f32_16x16x32_bf16 v[62:65], v[146:149], v[182:185], v[62:65]
	v_mfma_f32_16x16x32_bf16 v[58:61], v[154:157], v[182:185], v[58:61]
	v_mfma_f32_16x16x32_bf16 v[54:57], v[146:149], v[194:197], v[54:57]
	v_mfma_f32_16x16x32_bf16 v[50:53], v[154:157], v[194:197], v[50:53]
	v_mfma_f32_16x16x32_bf16 v[38:41], v[146:149], v[202:205], v[38:41]
	v_mfma_f32_16x16x32_bf16 v[34:37], v[154:157], v[202:205], v[34:37]
	v_mfma_f32_16x16x32_bf16 v[22:25], v[146:149], v[216:219], v[22:25]
	v_mfma_f32_16x16x32_bf16 v[18:21], v[154:157], v[216:219], v[18:21]
	v_mfma_f32_16x16x32_bf16 v[62:65], v[150:153], v[190:193], v[62:65]
	v_mfma_f32_16x16x32_bf16 v[58:61], v[158:161], v[190:193], v[58:61]
	v_mfma_f32_16x16x32_bf16 v[54:57], v[150:153], v[198:201], v[54:57]
	v_mfma_f32_16x16x32_bf16 v[50:53], v[158:161], v[198:201], v[50:53]
	v_mfma_f32_16x16x32_bf16 v[38:41], v[150:153], v[212:215], v[38:41]
	v_mfma_f32_16x16x32_bf16 v[34:37], v[158:161], v[212:215], v[34:37]
	v_mfma_f32_16x16x32_bf16 v[22:25], v[150:153], v[220:223], v[22:25]
	v_mfma_f32_16x16x32_bf16 v[18:21], v[158:161], v[220:223], v[18:21]
	s_nop 0
	s_nop 0
	v_mfma_f32_16x16x32_bf16 v[46:49], v[162:165], v[182:185], v[46:49]
	v_mfma_f32_16x16x32_bf16 v[42:45], v[170:173], v[182:185], v[42:45]
	v_mfma_f32_16x16x32_bf16 v[30:33], v[162:165], v[194:197], v[30:33]
	v_mfma_f32_16x16x32_bf16 v[26:29], v[170:173], v[194:197], v[26:29]
	v_mfma_f32_16x16x32_bf16 v[14:17], v[162:165], v[202:205], v[14:17]
	v_mfma_f32_16x16x32_bf16 v[10:13], v[170:173], v[202:205], v[10:13]
	v_mfma_f32_16x16x32_bf16 v[6:9], v[162:165], v[216:219], v[6:9]
	v_mfma_f32_16x16x32_bf16 v[2:5], v[170:173], v[216:219], v[2:5]
	v_mfma_f32_16x16x32_bf16 v[46:49], v[166:169], v[190:193], v[46:49]
	v_mfma_f32_16x16x32_bf16 v[42:45], v[174:177], v[190:193], v[42:45]
	v_mfma_f32_16x16x32_bf16 v[30:33], v[166:169], v[198:201], v[30:33]
	v_mfma_f32_16x16x32_bf16 v[26:29], v[174:177], v[198:201], v[26:29]
	v_mfma_f32_16x16x32_bf16 v[14:17], v[166:169], v[212:215], v[14:17]
	v_mfma_f32_16x16x32_bf16 v[10:13], v[174:177], v[212:215], v[10:13]
	v_mfma_f32_16x16x32_bf16 v[6:9], v[166:169], v[220:223], v[6:9]
	v_mfma_f32_16x16x32_bf16 v[2:5], v[174:177], v[220:223], v[2:5]
	s_nop 0
	s_barrier
	s_add_i32 vcc_lo, vcc_lo, 2
	s_add_u32 s61, s61, 0x100
	s_addc_u32 s63, s63, 0
	s_add_u32 s68, s68, 0x100
	s_addc_u32 s69, s69, 0
	s_cmp_gt_u32 vcc_lo, 13
	s_cbranch_scc0 .LBB0_1086
	s_and_b64 vcc, exec, s[56:57]
	s_cbranch_vccz .LBB0_1089
	s_barrier

; #define PG8_STAGE(bufoff, gbase, voff) do { _Pragma("unroll") for (int _i = 0; _i < 2; ++_i) \
;         __builtin_amdgcn_global_load_lds((const unsigned*)((const char*)(gbase) + (voff)[_i]), (LAS unsigned*)(lds + (bufoff) + ldsw + _i * 8192), 16, 0, 0); } while (0)
; #define PG8_LDA(dst, b, h) do { _Pragma("unroll") for (int m = 0; m < 4; ++m) _Pragma("unroll") for (int k = 0; k < 2; ++k) dst[m][k] = *(const LAS bf16x8*)(lds + PG8_SA(b, h) + aoff + m * 2048 + k * 1024); } while (0)
; #define PG8_LDB(dst, b, h) do { _Pragma("unroll") for (int n = 0; n < 2; ++n) _Pragma("unroll") for (int k = 0; k < 2; ++k) dst[n][k] = *(const LAS bf16x8*)(lds + PG8_SB(b, h) + boff + n * 2048 + k * 1024); } while (0)
; #define PG8_MMA(ai, bj, At, Bt) do { __builtin_amdgcn_s_setprio(1); _Pragma("unroll") for (int m = 0; m < 4; ++m) _Pragma("unroll") for (int n = 0; n < 2; ++n) _Pragma("unroll") for (int k = 0; k < 2; ++k) \
;         acc[ai][bj][m][n] = __builtin_amdgcn_mfma_f32_16x16x32_bf16(Bt[n][k], At[m][k], acc[ai][bj][m][n], 0, 0, 0); __builtin_amdgcn_s_setprio(0); } while (0)
; #define PG8_WAIT_V(n) asm volatile("s_waitcnt vmcnt(" #n ")" ::: "memory")
; #define PG8_WAIT_L(n) asm volatile("s_waitcnt lgkmcnt(" #n ")" ::: "memory")
; #define PG8_BAR __builtin_amdgcn_s_barrier()
; #define PG8_SCHED __builtin_amdgcn_sched_barrier(0)
; template <class Epi, class Sched>
; DI void gemm_phase(LAS unsigned char* lds, const int K, const Sched& S, const Epi& E) {
;     ...
;             const char* a1 = cA + (size_t)(t + 1) * kstep;
;             const char* a2 = last ? nA : cA + (size_t)(t + 2) * kstep; const char* b2 = last ? nB : cB + (size_t)(t + 2) * kstep;
;             const char* a3 = a2 + kstep; const char* b3 = b2 + kstep;
;             PG8_LDB(B0, 0, 0); PG8_LDB(B1, 0, 1); PG8_SCHED; PG8_LDA(At, 0, 0); PG8_STAGE(PG8_SA(1, 1), a1 + hstep, voffA);
;             PG8_WAIT_V(8); PG8_WAIT_L(0); PG8_BAR; PG8_MMA(0, 0, At, B0); PG8_MMA(0, 1, At, B1); PG8_BAR; PG8_SCHED;
;             PG8_LDA(At, 0, 1); PG8_STAGE(PG8_SB(0, 0), b2, voffB); PG8_STAGE(PG8_SB(0, 1), b2 + hstep, voffB); PG8_STAGE(PG8_SA(0, 0), a2, voffA);
;             PG8_WAIT_V(8); PG8_WAIT_L(0); PG8_BAR; PG8_MMA(1, 0, At, B0); PG8_MMA(1, 1, At, B1); PG8_BAR; PG8_SCHED;
.LBB0_1204:
	s_add_u32 s60, s58, 0x100
	s_addc_u32 s61, s59, 0
	s_add_i32 s48, 0, 0x10000
	s_cmp_eq_u32 s85, 40
	s_cselect_b32 s65, s55, s61
	s_cselect_b32 s64, s54, s60
	v_add_u32_e32 v145, s48, v143
	s_cselect_b32 s63, s57, s84
	s_cselect_b32 s62, s56, s83
	s_add_i32 s86, 0, 0x14000
	ds_read_b128 v[146:149], v145
	ds_read_b128 v[150:153], v145 offset:1024
	ds_read_b128 v[154:157], v145 offset:2048
	ds_read_b128 v[158:161], v145 offset:3072
	v_add_u32_e32 v145, s86, v143
	ds_read_b128 v[162:165], v145
	ds_read_b128 v[166:169], v145 offset:1024
	ds_read_b128 v[170:173], v145 offset:2048
	ds_read_b128 v[174:177], v145 offset:3072
	s_nop 0
	s_add_i32 m0, s71, 0xc000
	ds_read_b128 v[182:185], v144
	ds_read_b128 v[190:193], v144 offset:1024
	ds_read_b128 v[194:197], v144 offset:2048
	ds_read_b128 v[198:201], v144 offset:3072
	ds_read_b128 v[202:205], v144 offset:4096
	ds_read_b128 v[212:215], v144 offset:5120
	ds_read_b128 v[216:219], v144 offset:6144
	ds_read_b128 v[220:223], v144 offset:7168
	global_load_lds_dwordx4 v140, s[58:59]
	s_nop 0
	s_add_i32 m0, s71, 0xe000
	s_nop 0
	global_load_lds_dwordx4 v138, s[58:59]
	s_waitcnt vmcnt(8)
	s_waitcnt lgkmcnt(0)
	s_barrier
	s_nop 0
	s_waitcnt lgkmcnt(0)
	v_mfma_f32_16x16x32_bf16 v[126:129], v[146:149], v[182:185], v[126:129]
	v_mfma_f32_16x16x32_bf16 v[122:125], v[154:157], v[182:185], v[122:125]
	v_mfma_f32_16x16x32_bf16 v[118:121], v[146:149], v[194:197], v[118:121]
	v_mfma_f32_16x16x32_bf16 v[114:117], v[154:157], v[194:197], v[114:117]
	v_mfma_f32_16x16x32_bf16 v[102:105], v[146:149], v[202:205], v[102:105]
	v_mfma_f32_16x16x32_bf16 v[98:101], v[154:157], v[202:205], v[98:101]
	v_mfma_f32_16x16x32_bf16 v[86:89], v[146:149], v[216:219], v[86:89]
	v_mfma_f32_16x16x32_bf16 v[82:85], v[154:157], v[216:219], v[82:85]
	v_mfma_f32_16x16x32_bf16 v[126:129], v[150:153], v[190:193], v[126:129]
	v_mfma_f32_16x16x32_bf16 v[122:125], v[158:161], v[190:193], v[122:125]
	v_mfma_f32_16x16x32_bf16 v[118:121], v[150:153], v[198:201], v[118:121]
	v_mfma_f32_16x16x32_bf16 v[114:117], v[158:161], v[198:201], v[114:117]
	v_mfma_f32_16x16x32_bf16 v[102:105], v[150:153], v[212:215], v[102:105]
	v_mfma_f32_16x16x32_bf16 v[98:101], v[158:161], v[212:215], v[98:101]
	v_mfma_f32_16x16x32_bf16 v[86:89], v[150:153], v[220:223], v[86:89]
	v_mfma_f32_16x16x32_bf16 v[82:85], v[158:161], v[220:223], v[82:85]
	s_nop 0
	s_nop 0
	v_mfma_f32_16x16x32_bf16 v[110:113], v[162:165], v[182:185], v[110:113]
	v_mfma_f32_16x16x32_bf16 v[106:109], v[170:173], v[182:185], v[106:109]
	v_mfma_f32_16x16x32_bf16 v[94:97], v[162:165], v[194:197], v[94:97]
	v_mfma_f32_16x16x32_bf16 v[90:93], v[170:173], v[194:197], v[90:93]
	v_mfma_f32_16x16x32_bf16 v[78:81], v[162:165], v[202:205], v[78:81]
	v_mfma_f32_16x16x32_bf16 v[74:77], v[170:173], v[202:205], v[74:77]
	v_mfma_f32_16x16x32_bf16 v[70:73], v[162:165], v[216:219], v[70:73]
	v_mfma_f32_16x16x32_bf16 v[66:69], v[170:173], v[216:219], v[66:69]
	v_mfma_f32_16x16x32_bf16 v[110:113], v[166:169], v[190:193], v[110:113]
	v_mfma_f32_16x16x32_bf16 v[106:109], v[174:177], v[190:193], v[106:109]
	v_mfma_f32_16x16x32_bf16 v[94:97], v[166:169], v[198:201], v[94:97]
	v_mfma_f32_16x16x32_bf16 v[90:93], v[174:177], v[198:201], v[90:93]
	v_mfma_f32_16x16x32_bf16 v[78:81], v[166:169], v[212:215], v[78:81]
	v_mfma_f32_16x16x32_bf16 v[74:77], v[174:177], v[212:215], v[74:77]
	v_mfma_f32_16x16x32_bf16 v[70:73], v[166:169], v[220:223], v[70:73]
	v_mfma_f32_16x16x32_bf16 v[66:69], v[174:177], v[220:223], v[66:69]
	s_nop 0
	s_barrier
	s_add_i32 s48, s48, s69
	s_nop 0
	s_mov_b32 m0, s48
	ds_read_b128 v[182:185], v144 offset:16384
	ds_read_b128 v[190:193], v144 offset:17408
	ds_read_b128 v[194:197], v144 offset:18432
	ds_read_b128 v[198:201], v144 offset:19456
	ds_read_b128 v[202:205], v144 offset:20480
	ds_read_b128 v[212:215], v144 offset:21504
	ds_read_b128 v[216:219], v144 offset:22528
	ds_read_b128 v[220:223], v144 offset:23552
	global_load_lds_dwordx4 v134, s[62:63]
	s_add_i32 m0, s48, 0x2000
	s_add_u32 s48, s62, 0xb0000
	s_nop 0
	s_addc_u32 s49, s63, 0
	s_add_i32 s58, s86, s69
	global_load_lds_dwordx4 v130, s[62:63]
	s_nop 0
	s_mov_b32 m0, s58
	s_nop 0
	global_load_lds_dwordx4 v134, s[48:49]
	s_nop 0
	s_add_i32 m0, s58, 0x2000
	s_nop 0
	global_load_lds_dwordx4 v130, s[48:49]
	s_nop 0
	s_add_u32 s98, s64, s90
	s_addc_u32 s99, s65, s91
	s_waitcnt vmcnt(6)
	s_waitcnt lgkmcnt(0)
	s_barrier
	s_nop 0
	s_waitcnt lgkmcnt(0)
	v_mfma_f32_16x16x32_bf16 v[62:65], v[146:149], v[182:185], v[62:65]
	v_mfma_f32_16x16x32_bf16 v[58:61], v[154:157], v[182:185], v[58:61]
	v_mfma_f32_16x16x32_bf16 v[54:57], v[146:149], v[194:197], v[54:57]
	v_mfma_f32_16x16x32_bf16 v[50:53], v[154:157], v[194:197], v[50:53]
	v_mfma_f32_16x16x32_bf16 v[38:41], v[146:149], v[202:205], v[38:41]
	v_mfma_f32_16x16x32_bf16 v[34:37], v[154:157], v[202:205], v[34:37]
	v_mfma_f32_16x16x32_bf16 v[22:25], v[146:149], v[216:219], v[22:25]
	v_mfma_f32_16x16x32_bf16 v[18:21], v[154:157], v[216:219], v[18:21]
	v_mfma_f32_16x16x32_bf16 v[62:65], v[150:153], v[190:193], v[62:65]
	v_mfma_f32_16x16x32_bf16 v[58:61], v[158:161], v[190:193], v[58:61]
	v_mfma_f32_16x16x32_bf16 v[54:57], v[150:153], v[198:201], v[54:57]
	v_mfma_f32_16x16x32_bf16 v[50:53], v[158:161], v[198:201], v[50:53]
	v_mfma_f32_16x16x32_bf16 v[38:41], v[150:153], v[212:215], v[38:41]
	v_mfma_f32_16x16x32_bf16 v[34:37], v[158:161], v[212:215], v[34:37]
	v_mfma_f32_16x16x32_bf16 v[22:25], v[150:153], v[220:223], v[22:25]
	v_mfma_f32_16x16x32_bf16 v[18:21], v[158:161], v[220:223], v[18:21]
	s_nop 0
	s_nop 0
	v_mfma_f32_16x16x32_bf16 v[46:49], v[162:165], v[182:185], v[46:49]
	v_mfma_f32_16x16x32_bf16 v[42:45], v[170:173], v[182:185], v[42:45]
	v_mfma_f32_16x16x32_bf16 v[30:33], v[162:165], v[194:197], v[30:33]
	v_mfma_f32_16x16x32_bf16 v[26:29], v[170:173], v[194:197], v[26:29]
	v_mfma_f32_16x16x32_bf16 v[14:17], v[162:165], v[202:205], v[14:17]
	v_mfma_f32_16x16x32_bf16 v[10:13], v[170:173], v[202:205], v[10:13]
	v_mfma_f32_16x16x32_bf16 v[6:9], v[162:165], v[216:219], v[6:9]
	v_mfma_f32_16x16x32_bf16 v[2:5], v[170:173], v[216:219], v[2:5]
	v_mfma_f32_16x16x32_bf16 v[46:49], v[166:169], v[190:193], v[46:49]
	v_mfma_f32_16x16x32_bf16 v[42:45], v[174:177], v[190:193], v[42:45]
	v_mfma_f32_16x16x32_bf16 v[30:33], v[166:169], v[198:201], v[30:33]
	v_mfma_f32_16x16x32_bf16 v[26:29], v[174:177], v[198:201], v[26:29]
	v_mfma_f32_16x16x32_bf16 v[14:17], v[166:169], v[212:215], v[14:17]
	v_mfma_f32_16x16x32_bf16 v[10:13], v[174:177], v[212:215], v[10:13]
	v_mfma_f32_16x16x32_bf16 v[6:9], v[166:169], v[220:223], v[6:9]
	v_mfma_f32_16x16x32_bf16 v[2:5], v[174:177], v[220:223], v[2:5]
	s_nop 0
	s_barrier
; #define PG8_STAGE(bufoff, gbase, voff) do { _Pragma("unroll") for (int _i = 0; _i < 2; ++_i) \
;         __builtin_amdgcn_global_load_lds((const unsigned*)((const char*)(gbase) + (voff)[_i]), (LAS unsigned*)(lds + (bufoff) + ldsw + _i * 8192), 16, 0, 0); } while (0)
; #define PG8_LDA(dst, b, h) do { _Pragma("unroll") for (int m = 0; m < 4; ++m) _Pragma("unroll") for (int k = 0; k < 2; ++k) dst[m][k] = *(const LAS bf16x8*)(lds + PG8_SA(b, h) + aoff + m * 2048 + k * 1024); } while (0)
; #define PG8_LDB(dst, b, h) do { _Pragma("unroll") for (int n = 0; n < 2; ++n) _Pragma("unroll") for (int k = 0; k < 2; ++k) dst[n][k] = *(const LAS bf16x8*)(lds + PG8_SB(b, h) + boff + n * 2048 + k * 1024); } while (0)
; #define PG8_MMA(ai, bj, At, Bt) do { __builtin_amdgcn_s_setprio(1); _Pragma("unroll") for (int m = 0; m < 4; ++m) _Pragma("unroll") for (int n = 0; n < 2; ++n) _Pragma("unroll") for (int k = 0; k < 2; ++k) \
;         acc[ai][bj][m][n] = __builtin_amdgcn_mfma_f32_16x16x32_bf16(Bt[n][k], At[m][k], acc[ai][bj][m][n], 0, 0, 0); __builtin_amdgcn_s_setprio(0); } while (0)
; #define PG8_WAIT_V(n) asm volatile("s_waitcnt vmcnt(" #n ")" ::: "memory")
; #define PG8_WAIT_L(n) asm volatile("s_waitcnt lgkmcnt(" #n ")" ::: "memory")
; #define PG8_BAR __builtin_amdgcn_s_barrier()
; #define PG8_SCHED __builtin_amdgcn_sched_barrier(0)
; template <class Epi, class Sched>
; DI void gemm_phase(LAS unsigned char* lds, const int K, const Sched& S, const Epi& E) {
;     ...
;             PG8_LDB(B0, 1, 0); PG8_LDB(B1, 1, 1); PG8_SCHED; PG8_LDA(At, 1, 0); PG8_STAGE(PG8_SA(0, 1), a2 + hstep, voffA);
;             PG8_WAIT_V(8); PG8_WAIT_L(0); PG8_BAR; PG8_MMA(0, 0, At, B0); PG8_MMA(0, 1, At, B1); PG8_BAR; PG8_SCHED;
;             PG8_LDA(At, 1, 1); PG8_STAGE(PG8_SB(1, 0), b3, voffB); PG8_STAGE(PG8_SB(1, 1), b3 + hstep, voffB); PG8_STAGE(PG8_SA(1, 0), a3, voffA);
;             PG8_WAIT_V(8); PG8_WAIT_L(0); PG8_BAR; PG8_MMA(1, 0, At, B0); PG8_MMA(1, 1, At, B1); PG8_BAR; PG8_SCHED;
;         }
;         if (wr == 0) PG8_BAR;
	s_add_i32 s58, 0, 0x18000
	v_add_u32_e32 v145, s58, v143
	s_add_i32 s59, 0, 0x1c000
	ds_read_b128 v[146:149], v145
	ds_read_b128 v[150:153], v145 offset:1024
	ds_read_b128 v[154:157], v145 offset:2048
	ds_read_b128 v[158:161], v145 offset:3072
	v_add_u32_e32 v145, s59, v143
	ds_read_b128 v[162:165], v145
	ds_read_b128 v[166:169], v145 offset:1024
	ds_read_b128 v[170:173], v145 offset:2048
	ds_read_b128 v[174:177], v145 offset:3072
	s_mov_b32 m0, s71
	s_nop 0
	ds_read_b128 v[182:185], v144 offset:32768
	ds_read_b128 v[190:193], v144 offset:33792
	ds_read_b128 v[194:197], v144 offset:34816
	ds_read_b128 v[198:201], v144 offset:35840
	ds_read_b128 v[202:205], v144 offset:36864
	ds_read_b128 v[212:215], v144 offset:37888
	ds_read_b128 v[216:219], v144 offset:38912
	ds_read_b128 v[220:223], v144 offset:39936
	global_load_lds_dwordx4 v136, s[64:65]
	s_mov_b32 m0, s72
	s_nop 0
	global_load_lds_dwordx4 v132, s[64:65]
	s_add_u32 s48, s64, 0xb0000
	s_addc_u32 s49, s65, 0
	s_mov_b32 m0, s73
	s_nop 0
	global_load_lds_dwordx4 v136, s[48:49]
	s_nop 0
	s_mov_b32 m0, s74
	s_nop 0
	global_load_lds_dwordx4 v132, s[48:49]
	s_waitcnt vmcnt(8)
	s_waitcnt lgkmcnt(0)
	s_barrier
	s_nop 0
	s_waitcnt lgkmcnt(0)
	v_mfma_f32_16x16x32_bf16 v[126:129], v[146:149], v[182:185], v[126:129]
	v_mfma_f32_16x16x32_bf16 v[122:125], v[154:157], v[182:185], v[122:125]
	v_mfma_f32_16x16x32_bf16 v[118:121], v[146:149], v[194:197], v[118:121]
	v_mfma_f32_16x16x32_bf16 v[114:117], v[154:157], v[194:197], v[114:117]
	v_mfma_f32_16x16x32_bf16 v[102:105], v[146:149], v[202:205], v[102:105]
	v_mfma_f32_16x16x32_bf16 v[98:101], v[154:157], v[202:205], v[98:101]
	v_mfma_f32_16x16x32_bf16 v[86:89], v[146:149], v[216:219], v[86:89]
	v_mfma_f32_16x16x32_bf16 v[82:85], v[154:157], v[216:219], v[82:85]
	v_mfma_f32_16x16x32_bf16 v[126:129], v[150:153], v[190:193], v[126:129]
	v_mfma_f32_16x16x32_bf16 v[122:125], v[158:161], v[190:193], v[122:125]
	v_mfma_f32_16x16x32_bf16 v[118:121], v[150:153], v[198:201], v[118:121]
	v_mfma_f32_16x16x32_bf16 v[114:117], v[158:161], v[198:201], v[114:117]
	v_mfma_f32_16x16x32_bf16 v[102:105], v[150:153], v[212:215], v[102:105]
	v_mfma_f32_16x16x32_bf16 v[98:101], v[158:161], v[212:215], v[98:101]
	v_mfma_f32_16x16x32_bf16 v[86:89], v[150:153], v[220:223], v[86:89]
	v_mfma_f32_16x16x32_bf16 v[82:85], v[158:161], v[220:223], v[82:85]
	s_nop 0
	s_nop 0
	v_mfma_f32_16x16x32_bf16 v[110:113], v[162:165], v[182:185], v[110:113]
	v_mfma_f32_16x16x32_bf16 v[106:109], v[170:173], v[182:185], v[106:109]
	v_mfma_f32_16x16x32_bf16 v[94:97], v[162:165], v[194:197], v[94:97]
	v_mfma_f32_16x16x32_bf16 v[90:93], v[170:173], v[194:197], v[90:93]
	v_mfma_f32_16x16x32_bf16 v[78:81], v[162:165], v[202:205], v[78:81]
	v_mfma_f32_16x16x32_bf16 v[74:77], v[170:173], v[202:205], v[74:77]
	v_mfma_f32_16x16x32_bf16 v[70:73], v[162:165], v[216:219], v[70:73]
	v_mfma_f32_16x16x32_bf16 v[66:69], v[170:173], v[216:219], v[66:69]
	v_mfma_f32_16x16x32_bf16 v[110:113], v[166:169], v[190:193], v[110:113]
	v_mfma_f32_16x16x32_bf16 v[106:109], v[174:177], v[190:193], v[106:109]
	v_mfma_f32_16x16x32_bf16 v[94:97], v[166:169], v[198:201], v[94:97]
	v_mfma_f32_16x16x32_bf16 v[90:93], v[174:177], v[198:201], v[90:93]
	v_mfma_f32_16x16x32_bf16 v[78:81], v[166:169], v[212:215], v[78:81]
	v_mfma_f32_16x16x32_bf16 v[74:77], v[174:177], v[212:215], v[74:77]
	v_mfma_f32_16x16x32_bf16 v[70:73], v[166:169], v[220:223], v[70:73]
	v_mfma_f32_16x16x32_bf16 v[66:69], v[174:177], v[220:223], v[66:69]
	s_nop 0
	s_barrier
	s_add_i32 s48, s58, s69
	s_add_u32 s62, s62, 0x80
	s_addc_u32 s63, s63, 0
	s_mov_b32 m0, s48
	ds_read_b128 v[182:185], v144 offset:49152
	ds_read_b128 v[190:193], v144 offset:50176
	ds_read_b128 v[194:197], v144 offset:51200
	ds_read_b128 v[198:201], v144 offset:52224
	ds_read_b128 v[202:205], v144 offset:53248
	ds_read_b128 v[212:215], v144 offset:54272
	ds_read_b128 v[216:219], v144 offset:55296
	ds_read_b128 v[220:223], v144 offset:56320
	global_load_lds_dwordx4 v134, s[62:63]
	s_add_i32 m0, s48, 0x2000
	s_add_u32 s48, s62, 0xb0000
	s_nop 0
	s_addc_u32 s49, s63, 0
	s_add_i32 s58, s59, s69
	global_load_lds_dwordx4 v130, s[62:63]
	s_nop 0
	s_mov_b32 m0, s58
	s_nop 0
	global_load_lds_dwordx4 v134, s[48:49]
	s_nop 0
	s_add_i32 m0, s58, 0x2000
	s_nop 0
	global_load_lds_dwordx4 v130, s[48:49]
	s_nop 0
	s_mov_b32 m0, s77
	s_nop 0
	global_load_lds_dwordx4 v136, s[98:99]
	s_nop 0
	s_mov_b32 m0, s78
	s_nop 0
	global_load_lds_dwordx4 v132, s[98:99]
	s_waitcnt vmcnt(8)
	s_waitcnt lgkmcnt(0)
	s_barrier
	s_nop 0
	s_waitcnt lgkmcnt(0)
	v_mfma_f32_16x16x32_bf16 v[62:65], v[146:149], v[182:185], v[62:65]
	v_mfma_f32_16x16x32_bf16 v[58:61], v[154:157], v[182:185], v[58:61]
	v_mfma_f32_16x16x32_bf16 v[54:57], v[146:149], v[194:197], v[54:57]
	v_mfma_f32_16x16x32_bf16 v[50:53], v[154:157], v[194:197], v[50:53]
	v_mfma_f32_16x16x32_bf16 v[38:41], v[146:149], v[202:205], v[38:41]
	v_mfma_f32_16x16x32_bf16 v[34:37], v[154:157], v[202:205], v[34:37]
	v_mfma_f32_16x16x32_bf16 v[22:25], v[146:149], v[216:219], v[22:25]
	v_mfma_f32_16x16x32_bf16 v[18:21], v[154:157], v[216:219], v[18:21]
	v_mfma_f32_16x16x32_bf16 v[62:65], v[150:153], v[190:193], v[62:65]
	v_mfma_f32_16x16x32_bf16 v[58:61], v[158:161], v[190:193], v[58:61]
	v_mfma_f32_16x16x32_bf16 v[54:57], v[150:153], v[198:201], v[54:57]
	v_mfma_f32_16x16x32_bf16 v[50:53], v[158:161], v[198:201], v[50:53]
	v_mfma_f32_16x16x32_bf16 v[38:41], v[150:153], v[212:215], v[38:41]
	v_mfma_f32_16x16x32_bf16 v[34:37], v[158:161], v[212:215], v[34:37]
	v_mfma_f32_16x16x32_bf16 v[22:25], v[150:153], v[220:223], v[22:25]
	v_mfma_f32_16x16x32_bf16 v[18:21], v[158:161], v[220:223], v[18:21]
	s_nop 0
	s_nop 0
	v_mfma_f32_16x16x32_bf16 v[46:49], v[162:165], v[182:185], v[46:49]
	v_mfma_f32_16x16x32_bf16 v[42:45], v[170:173], v[182:185], v[42:45]
	v_mfma_f32_16x16x32_bf16 v[30:33], v[162:165], v[194:197], v[30:33]
	v_mfma_f32_16x16x32_bf16 v[26:29], v[170:173], v[194:197], v[26:29]
	v_mfma_f32_16x16x32_bf16 v[14:17], v[162:165], v[202:205], v[14:17]
	v_mfma_f32_16x16x32_bf16 v[10:13], v[170:173], v[202:205], v[10:13]
	v_mfma_f32_16x16x32_bf16 v[6:9], v[162:165], v[216:219], v[6:9]
	v_mfma_f32_16x16x32_bf16 v[2:5], v[170:173], v[216:219], v[2:5]
	v_mfma_f32_16x16x32_bf16 v[46:49], v[166:169], v[190:193], v[46:49]
	v_mfma_f32_16x16x32_bf16 v[42:45], v[174:177], v[190:193], v[42:45]
	v_mfma_f32_16x16x32_bf16 v[30:33], v[166:169], v[198:201], v[30:33]
	v_mfma_f32_16x16x32_bf16 v[26:29], v[174:177], v[198:201], v[26:29]
	v_mfma_f32_16x16x32_bf16 v[14:17], v[166:169], v[212:215], v[14:17]
	v_mfma_f32_16x16x32_bf16 v[10:13], v[174:177], v[212:215], v[10:13]
	v_mfma_f32_16x16x32_bf16 v[6:9], v[166:169], v[220:223], v[6:9]
	v_mfma_f32_16x16x32_bf16 v[2:5], v[174:177], v[220:223], v[2:5]
	s_nop 0
	s_barrier
	s_add_i32 s85, s85, 2
	s_add_u32 s83, s83, 0x100
	s_addc_u32 s84, s84, 0
	s_cmp_gt_u32 s85, 41
	s_mov_b64 s[58:59], s[60:61]
	s_cbranch_scc0 .LBB0_1204
	s_and_b64 vcc, exec, s[52:53]
	s_cbranch_vccz .LBB0_1207
	s_barrier
